# gather_u rewritten by hand: column sub-phases over a sliced fp6 U table (3 MB per slice, L2-resident), LDS partial sums, DPP lane reduction, 2-unit load pipeline
# speedup vs baseline: 1.0734x; 1.0398x over previous
.LBB0_35:
	s_or_b64 exec, exec, s[0:1]
	s_and_b32 s0, 0xffff, s20
	s_cmp_lg_u32 s0, 0
	s_cselect_b64 s[6:7], -1, 0
	s_cmp_lg_u64 s[6:7], 0
	s_addc_u32 s92, s96, 0
	s_lshr_b32 s3, s92, 1
	v_cvt_f32_u32_e32 v1, s3
	s_sub_i32 s0, 0, s3
	v_mov_b32_e32 v2, v205
	v_mov_b32_e32 v3, v205
	v_rcp_iflag_f32_e32 v1, v1
	v_mbcnt_lo_u32_b32 v207, -1, 0
	v_mul_f32_e32 v1, 0x4f7ffffe, v1
	v_cvt_u32_f32_e32 v1, v1
	v_ashrrev_i32_e32 v3, 6, v3
	v_readfirstlane_b32 s1, v1
	s_mul_i32 s0, s0, s1
	s_mul_hi_u32 s0, s1, s0
	s_add_i32 s1, s1, s0
	s_mul_hi_u32 s0, s2, s1
	s_mul_i32 s0, s0, s3
	s_sub_i32 s0, s2, s0
	s_sub_i32 s1, s0, s3
	s_cmp_ge_u32 s0, s3
	s_cselect_b32 s0, s1, s0
	s_sub_i32 s1, s0, s3
	s_cmp_ge_u32 s0, s3
	s_cselect_b32 s0, s1, s0
	s_add_u32 s52, s26, 0x1400000
	s_addc_u32 s53, s27, 0
	s_and_b32 s19, s92, -2
	s_lshl_b32 s0, s0, 3
	s_cmp_lt_u32 s2, s3
	s_cselect_b32 s1, 0, 4
	s_or_b32 s21, s0, s1
	v_add_u32_e32 v1, s21, v3
	s_movk_i32 s0, 0x2000
	v_cmp_gt_i32_e32 vcc, s0, v1
	s_and_saveexec_b64 s[14:15], vcc
	s_cbranch_execz .LBB0_40
	v_and_b32_e32 v5, 31, v2
	v_bfe_u32 v4, v2, 5, 1
	v_lshlrev_b32_e32 v2, 7, v5
	v_mov_b32_e32 v3, 0
	v_mbcnt_hi_u32_b32 v6, -1, v207
	v_lshl_add_u64 v[26:27], s[8:9], 0, v[2:3]
	v_and_b32_e32 v2, 64, v6
	v_add_u32_e32 v7, 64, v2
	v_and_b32_e32 v2, 7, v5
	v_mul_u32_u24_e32 v2, 24, v2
	v_lshrrev_b32_e32 v3, 3, v5
	v_mul_u32_u24_e32 v3, 0x300000, v3
	v_add_u32_e32 v2, v2, v3
	v_mov_b32_e32 v3, 0
	v_lshl_add_u64 v[2:3], s[26:27], 0, v[2:3]
	s_mov_b64 s[0:1], 0x1800000
	v_lshl_add_u64 v[28:29], v[2:3], 0, s[0:1]
	v_xor_b32_e32 v2, 16, v6
	v_cmp_lt_i32_e32 vcc, v2, v7
	v_cmp_eq_u32_e64 s[0:1], 0, v5
	s_lshl_b32 s28, s19, 2
	v_cndmask_b32_e32 v2, v6, v2, vcc
	v_lshlrev_b32_e32 v38, 2, v2
	v_xor_b32_e32 v2, 8, v6
	v_cmp_lt_i32_e32 vcc, v2, v7
	v_lshl_or_b32 v30, v1, 1, v4
	s_lshl_b32 s29, s3, 4
	v_cndmask_b32_e32 v2, v6, v2, vcc
	v_lshlrev_b32_e32 v39, 2, v2
	v_xor_b32_e32 v2, 4, v6
	v_cmp_lt_i32_e32 vcc, v2, v7
	s_mov_b64 s[16:17], 0
	s_movk_i32 s30, 0xc0
	v_cndmask_b32_e32 v2, v6, v2, vcc
	v_lshlrev_b32_e32 v40, 2, v2
	v_xor_b32_e32 v2, 2, v6
	v_cmp_lt_i32_e32 vcc, v2, v7
	s_mov_b32 s31, 0x40f00000
	s_mov_b32 s18, 0x41000000
	v_cndmask_b32_e32 v2, v6, v2, vcc
	v_lshlrev_b32_e32 v41, 2, v2
	v_xor_b32_e32 v2, 1, v6
	v_cmp_lt_i32_e32 vcc, v2, v7
	s_mov_b32 s20, 0x41800000
	s_movk_i32 s34, 0x1fff
	v_cndmask_b32_e32 v2, v6, v2, vcc
	v_lshlrev_b32_e32 v42, 2, v2
	s_branch .LBB0_38

.LBB0_45:
	s_or_b64 exec, exec, s[14:15]
	v_mov_b32_e32 v2, v205
	v_mov_b32_e32 v1, v205
	s_add_u32 s28, s26, 0x1420000
	v_ashrrev_i32_e32 v1, 6, v1
	v_add_u32_e32 v1, s21, v1
	s_movk_i32 s0, 0x2000
	s_addc_u32 s29, s27, 0
	v_cmp_gt_i32_e32 vcc, s0, v1
	s_and_saveexec_b64 s[14:15], vcc
	s_cbranch_execz .LBB0_50
	v_and_b32_e32 v7, 31, v2
	v_bfe_u32 v6, v2, 5, 1
	v_lshlrev_b32_e32 v2, 7, v7
	v_mov_b32_e32 v3, 0
	v_lshl_add_u64 v[4:5], s[8:9], 0, v[2:3]
	s_mov_b64 s[0:1], 0x4000000
	v_lshl_add_u64 v[26:27], v[4:5], 0, s[0:1]
	v_mbcnt_hi_u32_b32 v4, -1, v207
	v_and_b32_e32 v2, 64, v4
	v_add_u32_e32 v5, 64, v2
	v_and_b32_e32 v2, 7, v7
	v_mul_u32_u24_e32 v2, 24, v2
	v_lshrrev_b32_e32 v3, 3, v7
	v_mul_u32_u24_e32 v3, 0x300000, v3
	v_add_u32_e32 v2, v2, v3
	v_mov_b32_e32 v3, 0
	v_lshl_add_u64 v[2:3], s[26:27], 0, v[2:3]
	s_mov_b64 s[0:1], 0x2800000
	v_lshl_add_u64 v[28:29], v[2:3], 0, s[0:1]
	v_xor_b32_e32 v2, 16, v4
	v_cmp_lt_i32_e32 vcc, v2, v5
	v_cmp_eq_u32_e64 s[0:1], 0, v7
	s_lshl_b32 s17, s19, 2
	v_cndmask_b32_e32 v2, v4, v2, vcc
	v_lshlrev_b32_e32 v38, 2, v2
	v_xor_b32_e32 v2, 8, v4
	v_cmp_lt_i32_e32 vcc, v2, v5
	v_lshl_or_b32 v30, v1, 1, v6
	s_lshl_b32 s20, s3, 4
	v_cndmask_b32_e32 v2, v4, v2, vcc
	v_lshlrev_b32_e32 v39, 2, v2
	v_xor_b32_e32 v2, 4, v4
	v_cmp_lt_i32_e32 vcc, v2, v5
	s_mov_b64 s[8:9], 0
	s_movk_i32 s30, 0xc0
	v_cndmask_b32_e32 v2, v4, v2, vcc
	v_lshlrev_b32_e32 v40, 2, v2
	v_xor_b32_e32 v2, 2, v4
	v_cmp_lt_i32_e32 vcc, v2, v5
	s_mov_b32 s31, 0x40f00000
	s_mov_b32 s16, 0x41000000
	v_cndmask_b32_e32 v2, v4, v2, vcc
	v_lshlrev_b32_e32 v41, 2, v2
	v_xor_b32_e32 v2, 1, v4
	v_cmp_lt_i32_e32 vcc, v2, v5
	s_mov_b32 s18, 0x41800000
	s_movk_i32 s34, 0x1fff
	v_cndmask_b32_e32 v2, v4, v2, vcc
	v_lshlrev_b32_e32 v42, 2, v2
	s_branch .LBB0_48

.Lgu0_start:
	s_mov_b64 exec, -1
	v_and_b32_e32 v171, 63, v205
	v_lshrrev_b32_e32 v172, 6, v205
	v_lshlrev_b32_e32 v160, 2, v171
	v_readfirstlane_b32 s68, v172
	v_and_b32_e32 v172, 7, v171
	v_lshlrev_b32_e32 v163, 6, v172
	v_mul_u32_u24_e32 v164, 24, v172
	s_nop 3
	s_lshl_b32 s17, s68, 14
	s_add_i32 s69, s93, s68
	v_lshrrev_b32_e32 v172, 3, v171
	v_lshl_add_u32 v162, v172, 2, s17
	v_add_u32_e32 v161, 0x2000, v162
	v_lshl_add_u32 v173, v171, 4, s17
	v_add_u32_e32 v175, s17, v160
	v_add_u32_e32 v174, 0x2000, v175
.Lgu0_chunk:
	s_movk_i32 s64, 0xc0
	s_lshl_b32 s65, s92, 13
	s_mov_b32 s14, 0x01010101
	s_mov_b32 s15, 0x01010101
	s_add_u32 s10, s26, 0xd800000
	s_addc_u32 s11, s27, 0
	s_lshl_b32 s17, s69, 9
	s_add_u32 s10, s10, s17
	s_addc_u32 s11, s11, 0
	s_lshl_b32 s18, s92, 11
	global_load_dword v16, v160, s[10:11]
	global_load_dword v17, v160, s[10:11] offset:256
	s_add_u32 s10, s10, s18
	s_addc_u32 s11, s11, 0
	global_load_dword v18, v160, s[10:11]
	global_load_dword v19, v160, s[10:11] offset:256
	s_add_u32 s10, s10, s18
	s_addc_u32 s11, s11, 0
	global_load_dword v20, v160, s[10:11]
	global_load_dword v21, v160, s[10:11] offset:256
	s_add_u32 s10, s10, s18
	s_addc_u32 s11, s11, 0
	global_load_dword v22, v160, s[10:11]
	global_load_dword v23, v160, s[10:11] offset:256
	s_add_u32 s10, s10, s18
	s_addc_u32 s11, s11, 0
	global_load_dword v24, v160, s[10:11]
	global_load_dword v25, v160, s[10:11] offset:256
	s_add_u32 s10, s10, s18
	s_addc_u32 s11, s11, 0
	global_load_dword v26, v160, s[10:11]
	global_load_dword v27, v160, s[10:11] offset:256
	s_add_u32 s10, s10, s18
	s_addc_u32 s11, s11, 0
	global_load_dword v28, v160, s[10:11]
	global_load_dword v29, v160, s[10:11] offset:256
	s_add_u32 s10, s10, s18
	s_addc_u32 s11, s11, 0
	global_load_dword v30, v160, s[10:11]
	global_load_dword v31, v160, s[10:11] offset:256
	s_add_u32 s10, s10, s18
	s_addc_u32 s11, s11, 0
	global_load_dword v32, v160, s[10:11]
	global_load_dword v33, v160, s[10:11] offset:256
	s_add_u32 s10, s10, s18
	s_addc_u32 s11, s11, 0
	global_load_dword v34, v160, s[10:11]
	global_load_dword v35, v160, s[10:11] offset:256
	s_add_u32 s10, s10, s18
	s_addc_u32 s11, s11, 0
	global_load_dword v36, v160, s[10:11]
	global_load_dword v37, v160, s[10:11] offset:256
	s_add_u32 s10, s10, s18
	s_addc_u32 s11, s11, 0
	global_load_dword v38, v160, s[10:11]
	global_load_dword v39, v160, s[10:11] offset:256
	s_add_u32 s10, s10, s18
	s_addc_u32 s11, s11, 0
	global_load_dword v40, v160, s[10:11]
	global_load_dword v41, v160, s[10:11] offset:256
	s_add_u32 s10, s10, s18
	s_addc_u32 s11, s11, 0
	global_load_dword v42, v160, s[10:11]
	global_load_dword v43, v160, s[10:11] offset:256
	s_add_u32 s10, s10, s18
	s_addc_u32 s11, s11, 0
	global_load_dword v44, v160, s[10:11]
	global_load_dword v45, v160, s[10:11] offset:256
	s_add_u32 s10, s10, s18
	s_addc_u32 s11, s11, 0
	global_load_dword v46, v160, s[10:11]
	global_load_dword v47, v160, s[10:11] offset:256
	s_add_u32 s10, s10, s18
	s_addc_u32 s11, s11, 0
	v_mov_b32_e32 v0, 0
	v_mov_b32_e32 v1, 0
	v_mov_b32_e32 v2, 0
	v_mov_b32_e32 v3, 0
	ds_write_b128 v173, v[0:3] offset:0
	ds_write_b128 v173, v[0:3] offset:1024
	ds_write_b128 v173, v[0:3] offset:2048
	ds_write_b128 v173, v[0:3] offset:3072
	ds_write_b128 v173, v[0:3] offset:4096
	ds_write_b128 v173, v[0:3] offset:5120
	ds_write_b128 v173, v[0:3] offset:6144
	ds_write_b128 v173, v[0:3] offset:7168
	s_waitcnt vmcnt(0)
	ds_write2st64_b32 v174, v16, v17 offset0:0 offset1:1
	ds_write2st64_b32 v174, v18, v19 offset0:2 offset1:3
	ds_write2st64_b32 v174, v20, v21 offset0:4 offset1:5
	ds_write2st64_b32 v174, v22, v23 offset0:6 offset1:7
	ds_write2st64_b32 v174, v24, v25 offset0:8 offset1:9
	ds_write2st64_b32 v174, v26, v27 offset0:10 offset1:11
	ds_write2st64_b32 v174, v28, v29 offset0:12 offset1:13
	ds_write2st64_b32 v174, v30, v31 offset0:14 offset1:15
	ds_write2st64_b32 v174, v32, v33 offset0:16 offset1:17
	ds_write2st64_b32 v174, v34, v35 offset0:18 offset1:19
	ds_write2st64_b32 v174, v36, v37 offset0:20 offset1:21
	ds_write2st64_b32 v174, v38, v39 offset0:22 offset1:23
	ds_write2st64_b32 v174, v40, v41 offset0:24 offset1:25
	ds_write2st64_b32 v174, v42, v43 offset0:26 offset1:27
	ds_write2st64_b32 v174, v44, v45 offset0:28 offset1:29
	ds_write2st64_b32 v174, v46, v47 offset0:30 offset1:31
	s_waitcnt lgkmcnt(0)
	s_add_u32 s4, s26, 0x1800000
	s_addc_u32 s5, s27, 0
	s_add_u32 s8, s26, 0x5800000
	s_addc_u32 s9, s27, 0
	s_lshl_b32 s17, s69, 11
	s_add_u32 s8, s8, s17
	s_addc_u32 s9, s9, 0
	s_mov_b32 s16, 0
	s_and_b32 s19, s16, 15
	s_lshr_b32 s50, s16, 4
	s_lshl_b32 s51, s19, 9
	s_mul_i32 s17, s19, s65
	s_lshl_b32 s18, s50, 9
	s_add_u32 s17, s17, s18
	s_add_u32 s10, s8, s17
	s_addc_u32 s11, s9, 0
	s_mul_i32 s17, s50, 0x300000
	s_add_u32 s4, s26, 0x1800000
	s_addc_u32 s5, s27, 0
	s_add_u32 s4, s4, s17
	s_addc_u32 s5, s5, 0
	v_mov_b32_e32 v165, v164
	v_add_u32_e32 v167, s51, v161
	v_add_u32_e32 v169, s51, v162
	global_load_dwordx4 v[112:115], v163, s[10:11]
	global_load_dwordx4 v[116:119], v163, s[10:11] offset:16
	global_load_dwordx4 v[120:123], v163, s[10:11] offset:32
	global_load_dwordx4 v[124:127], v163, s[10:11] offset:48
	ds_read2_b32 v[144:145], v167 offset0:0 offset1:8
	ds_read2_b32 v[146:147], v167 offset0:16 offset1:24
	ds_read2_b32 v[148:149], v167 offset0:32 offset1:40
	ds_read2_b32 v[150:151], v167 offset0:48 offset1:56
	s_waitcnt lgkmcnt(0)
	v_mad_u32_u24 v144, v144, s64, v165
	v_mad_u32_u24 v145, v145, s64, v165
	v_mad_u32_u24 v146, v146, s64, v165
	v_mad_u32_u24 v147, v147, s64, v165
	v_mad_u32_u24 v148, v148, s64, v165
	v_mad_u32_u24 v149, v149, s64, v165
	v_mad_u32_u24 v150, v150, s64, v165
	v_mad_u32_u24 v151, v151, s64, v165
	global_load_dwordx4 v[16:19], v144, s[4:5]
	global_load_dwordx2 v[20:21], v144, s[4:5] offset:16
	global_load_dwordx4 v[22:25], v145, s[4:5]
	global_load_dwordx2 v[26:27], v145, s[4:5] offset:16
	global_load_dwordx4 v[28:31], v146, s[4:5]
	global_load_dwordx2 v[32:33], v146, s[4:5] offset:16
	global_load_dwordx4 v[34:37], v147, s[4:5]
	global_load_dwordx2 v[38:39], v147, s[4:5] offset:16
	global_load_dwordx4 v[40:43], v148, s[4:5]
	global_load_dwordx2 v[44:45], v148, s[4:5] offset:16
	global_load_dwordx4 v[46:49], v149, s[4:5]
	global_load_dwordx2 v[50:51], v149, s[4:5] offset:16
	global_load_dwordx4 v[52:55], v150, s[4:5]
	global_load_dwordx2 v[56:57], v150, s[4:5] offset:16
	global_load_dwordx4 v[58:61], v151, s[4:5]
	global_load_dwordx2 v[62:63], v151, s[4:5] offset:16
.Lgu0_loop:
	ds_read2_b32 v[144:145], v167 offset0:64 offset1:72
	ds_read2_b32 v[146:147], v167 offset0:80 offset1:88
	ds_read2_b32 v[148:149], v167 offset0:96 offset1:104
	ds_read2_b32 v[150:151], v167 offset0:112 offset1:120
	s_waitcnt lgkmcnt(0)
	v_mad_u32_u24 v144, v144, s64, v165
	v_mad_u32_u24 v145, v145, s64, v165
	v_mad_u32_u24 v146, v146, s64, v165
	v_mad_u32_u24 v147, v147, s64, v165
	v_mad_u32_u24 v148, v148, s64, v165
	v_mad_u32_u24 v149, v149, s64, v165
	v_mad_u32_u24 v150, v150, s64, v165
	v_mad_u32_u24 v151, v151, s64, v165
	global_load_dwordx4 v[64:67], v144, s[4:5]
	global_load_dwordx2 v[68:69], v144, s[4:5] offset:16
	global_load_dwordx4 v[70:73], v145, s[4:5]
	global_load_dwordx2 v[74:75], v145, s[4:5] offset:16
	global_load_dwordx4 v[76:79], v146, s[4:5]
	global_load_dwordx2 v[80:81], v146, s[4:5] offset:16
	global_load_dwordx4 v[82:85], v147, s[4:5]
	global_load_dwordx2 v[86:87], v147, s[4:5] offset:16
	global_load_dwordx4 v[88:91], v148, s[4:5]
	global_load_dwordx2 v[92:93], v148, s[4:5] offset:16
	global_load_dwordx4 v[94:97], v149, s[4:5]
	global_load_dwordx2 v[98:99], v149, s[4:5] offset:16
	global_load_dwordx4 v[100:103], v150, s[4:5]
	global_load_dwordx2 v[104:105], v150, s[4:5] offset:16
	global_load_dwordx4 v[106:109], v151, s[4:5]
	global_load_dwordx2 v[110:111], v151, s[4:5] offset:16
	v_mov_b32_e32 v152, 0
	v_mov_b32_e32 v153, 0
	v_mov_b32_e32 v154, 0
	v_mov_b32_e32 v155, 0
	s_waitcnt vmcnt(30)
	v_cvt_scalef32_pk32_bf16_fp6 v[0:15], v[16:21], 1.0
	v_dot2c_f32_bf16_e32 v152, v0, v112
	v_dot2c_f32_bf16_e32 v153, v1, v113
	v_dot2c_f32_bf16_e32 v154, v2, v114
	v_dot2c_f32_bf16_e32 v155, v3, v115
	v_dot2c_f32_bf16_e32 v152, v4, v116
	v_dot2c_f32_bf16_e32 v153, v5, v117
	v_dot2c_f32_bf16_e32 v154, v6, v118
	v_dot2c_f32_bf16_e32 v155, v7, v119
	v_dot2c_f32_bf16_e32 v152, v8, v120
	v_dot2c_f32_bf16_e32 v153, v9, v121
	v_dot2c_f32_bf16_e32 v154, v10, v122
	v_dot2c_f32_bf16_e32 v155, v11, v123
	v_dot2c_f32_bf16_e32 v152, v12, v124
	v_dot2c_f32_bf16_e32 v153, v13, v125
	v_dot2c_f32_bf16_e32 v154, v14, v126
	v_dot2c_f32_bf16_e32 v155, v15, v127
	s_nop 0
	v_add_f32_e32 v156, v152, v153
	s_nop 0
	v_add_f32_e32 v157, v154, v155
	v_add_f32_e32 v158, v156, v157
	s_nop 1
	v_add_f32_dpp v158, v158, v158 quad_perm:[1,0,3,2] row_mask:0xf bank_mask:0xf
	s_nop 1
	v_add_f32_dpp v158, v158, v158 quad_perm:[2,3,0,1] row_mask:0xf bank_mask:0xf
	s_nop 1
	v_add_f32_dpp v158, v158, v158 row_half_mirror row_mask:0xf bank_mask:0xf
	s_mov_b64 exec, s[14:15]
	ds_add_f32 v169, v158 offset:0
	s_mov_b64 exec, -1
	v_mov_b32_e32 v152, 0
	v_mov_b32_e32 v153, 0
	v_mov_b32_e32 v154, 0
	v_mov_b32_e32 v155, 0
	s_waitcnt vmcnt(28)
	v_cvt_scalef32_pk32_bf16_fp6 v[0:15], v[22:27], 1.0
	v_dot2c_f32_bf16_e32 v152, v0, v112
	v_dot2c_f32_bf16_e32 v153, v1, v113
	v_dot2c_f32_bf16_e32 v154, v2, v114
	v_dot2c_f32_bf16_e32 v155, v3, v115
	v_dot2c_f32_bf16_e32 v152, v4, v116
	v_dot2c_f32_bf16_e32 v153, v5, v117
	v_dot2c_f32_bf16_e32 v154, v6, v118
	v_dot2c_f32_bf16_e32 v155, v7, v119
	v_dot2c_f32_bf16_e32 v152, v8, v120
	v_dot2c_f32_bf16_e32 v153, v9, v121
	v_dot2c_f32_bf16_e32 v154, v10, v122
	v_dot2c_f32_bf16_e32 v155, v11, v123
	v_dot2c_f32_bf16_e32 v152, v12, v124
	v_dot2c_f32_bf16_e32 v153, v13, v125
	v_dot2c_f32_bf16_e32 v154, v14, v126
	v_dot2c_f32_bf16_e32 v155, v15, v127
	s_nop 0
	v_add_f32_e32 v156, v152, v153
	s_nop 0
	v_add_f32_e32 v157, v154, v155
	v_add_f32_e32 v158, v156, v157
	s_nop 1
	v_add_f32_dpp v158, v158, v158 quad_perm:[1,0,3,2] row_mask:0xf bank_mask:0xf
	s_nop 1
	v_add_f32_dpp v158, v158, v158 quad_perm:[2,3,0,1] row_mask:0xf bank_mask:0xf
	s_nop 1
	v_add_f32_dpp v158, v158, v158 row_half_mirror row_mask:0xf bank_mask:0xf
	s_mov_b64 exec, s[14:15]
	ds_add_f32 v169, v158 offset:32
	s_mov_b64 exec, -1
	v_mov_b32_e32 v152, 0
	v_mov_b32_e32 v153, 0
	v_mov_b32_e32 v154, 0
	v_mov_b32_e32 v155, 0
	s_waitcnt vmcnt(26)
	v_cvt_scalef32_pk32_bf16_fp6 v[0:15], v[28:33], 1.0
	v_dot2c_f32_bf16_e32 v152, v0, v112
	v_dot2c_f32_bf16_e32 v153, v1, v113
	v_dot2c_f32_bf16_e32 v154, v2, v114
	v_dot2c_f32_bf16_e32 v155, v3, v115
	v_dot2c_f32_bf16_e32 v152, v4, v116
	v_dot2c_f32_bf16_e32 v153, v5, v117
	v_dot2c_f32_bf16_e32 v154, v6, v118
	v_dot2c_f32_bf16_e32 v155, v7, v119
	v_dot2c_f32_bf16_e32 v152, v8, v120
	v_dot2c_f32_bf16_e32 v153, v9, v121
	v_dot2c_f32_bf16_e32 v154, v10, v122
	v_dot2c_f32_bf16_e32 v155, v11, v123
	v_dot2c_f32_bf16_e32 v152, v12, v124
	v_dot2c_f32_bf16_e32 v153, v13, v125
	v_dot2c_f32_bf16_e32 v154, v14, v126
	v_dot2c_f32_bf16_e32 v155, v15, v127
	s_nop 0
	v_add_f32_e32 v156, v152, v153
	s_nop 0
	v_add_f32_e32 v157, v154, v155
	v_add_f32_e32 v158, v156, v157
	s_nop 1
	v_add_f32_dpp v158, v158, v158 quad_perm:[1,0,3,2] row_mask:0xf bank_mask:0xf
	s_nop 1
	v_add_f32_dpp v158, v158, v158 quad_perm:[2,3,0,1] row_mask:0xf bank_mask:0xf
	s_nop 1
	v_add_f32_dpp v158, v158, v158 row_half_mirror row_mask:0xf bank_mask:0xf
	s_mov_b64 exec, s[14:15]
	ds_add_f32 v169, v158 offset:64
	s_mov_b64 exec, -1
	v_mov_b32_e32 v152, 0
	v_mov_b32_e32 v153, 0
	v_mov_b32_e32 v154, 0
	v_mov_b32_e32 v155, 0
	s_waitcnt vmcnt(24)
	v_cvt_scalef32_pk32_bf16_fp6 v[0:15], v[34:39], 1.0
	v_dot2c_f32_bf16_e32 v152, v0, v112
	v_dot2c_f32_bf16_e32 v153, v1, v113
	v_dot2c_f32_bf16_e32 v154, v2, v114
	v_dot2c_f32_bf16_e32 v155, v3, v115
	v_dot2c_f32_bf16_e32 v152, v4, v116
	v_dot2c_f32_bf16_e32 v153, v5, v117
	v_dot2c_f32_bf16_e32 v154, v6, v118
	v_dot2c_f32_bf16_e32 v155, v7, v119
	v_dot2c_f32_bf16_e32 v152, v8, v120
	v_dot2c_f32_bf16_e32 v153, v9, v121
	v_dot2c_f32_bf16_e32 v154, v10, v122
	v_dot2c_f32_bf16_e32 v155, v11, v123
	v_dot2c_f32_bf16_e32 v152, v12, v124
	v_dot2c_f32_bf16_e32 v153, v13, v125
	v_dot2c_f32_bf16_e32 v154, v14, v126
	v_dot2c_f32_bf16_e32 v155, v15, v127
	s_nop 0
	v_add_f32_e32 v156, v152, v153
	s_nop 0
	v_add_f32_e32 v157, v154, v155
	v_add_f32_e32 v158, v156, v157
	s_nop 1
	v_add_f32_dpp v158, v158, v158 quad_perm:[1,0,3,2] row_mask:0xf bank_mask:0xf
	s_nop 1
	v_add_f32_dpp v158, v158, v158 quad_perm:[2,3,0,1] row_mask:0xf bank_mask:0xf
	s_nop 1
	v_add_f32_dpp v158, v158, v158 row_half_mirror row_mask:0xf bank_mask:0xf
	s_mov_b64 exec, s[14:15]
	ds_add_f32 v169, v158 offset:96
	s_mov_b64 exec, -1
	v_mov_b32_e32 v152, 0
	v_mov_b32_e32 v153, 0
	v_mov_b32_e32 v154, 0
	v_mov_b32_e32 v155, 0
	s_waitcnt vmcnt(22)
	v_cvt_scalef32_pk32_bf16_fp6 v[0:15], v[40:45], 1.0
	v_dot2c_f32_bf16_e32 v152, v0, v112
	v_dot2c_f32_bf16_e32 v153, v1, v113
	v_dot2c_f32_bf16_e32 v154, v2, v114
	v_dot2c_f32_bf16_e32 v155, v3, v115
	v_dot2c_f32_bf16_e32 v152, v4, v116
	v_dot2c_f32_bf16_e32 v153, v5, v117
	v_dot2c_f32_bf16_e32 v154, v6, v118
	v_dot2c_f32_bf16_e32 v155, v7, v119
	v_dot2c_f32_bf16_e32 v152, v8, v120
	v_dot2c_f32_bf16_e32 v153, v9, v121
	v_dot2c_f32_bf16_e32 v154, v10, v122
	v_dot2c_f32_bf16_e32 v155, v11, v123
	v_dot2c_f32_bf16_e32 v152, v12, v124
	v_dot2c_f32_bf16_e32 v153, v13, v125
	v_dot2c_f32_bf16_e32 v154, v14, v126
	v_dot2c_f32_bf16_e32 v155, v15, v127
	s_nop 0
	v_add_f32_e32 v156, v152, v153
	s_nop 0
	v_add_f32_e32 v157, v154, v155
	v_add_f32_e32 v158, v156, v157
	s_nop 1
	v_add_f32_dpp v158, v158, v158 quad_perm:[1,0,3,2] row_mask:0xf bank_mask:0xf
	s_nop 1
	v_add_f32_dpp v158, v158, v158 quad_perm:[2,3,0,1] row_mask:0xf bank_mask:0xf
	s_nop 1
	v_add_f32_dpp v158, v158, v158 row_half_mirror row_mask:0xf bank_mask:0xf
	s_mov_b64 exec, s[14:15]
	ds_add_f32 v169, v158 offset:128
	s_mov_b64 exec, -1
	v_mov_b32_e32 v152, 0
	v_mov_b32_e32 v153, 0
	v_mov_b32_e32 v154, 0
	v_mov_b32_e32 v155, 0
	s_waitcnt vmcnt(20)
	v_cvt_scalef32_pk32_bf16_fp6 v[0:15], v[46:51], 1.0
	v_dot2c_f32_bf16_e32 v152, v0, v112
	v_dot2c_f32_bf16_e32 v153, v1, v113
	v_dot2c_f32_bf16_e32 v154, v2, v114
	v_dot2c_f32_bf16_e32 v155, v3, v115
	v_dot2c_f32_bf16_e32 v152, v4, v116
	v_dot2c_f32_bf16_e32 v153, v5, v117
	v_dot2c_f32_bf16_e32 v154, v6, v118
	v_dot2c_f32_bf16_e32 v155, v7, v119
	v_dot2c_f32_bf16_e32 v152, v8, v120
	v_dot2c_f32_bf16_e32 v153, v9, v121
	v_dot2c_f32_bf16_e32 v154, v10, v122
	v_dot2c_f32_bf16_e32 v155, v11, v123
	v_dot2c_f32_bf16_e32 v152, v12, v124
	v_dot2c_f32_bf16_e32 v153, v13, v125
	v_dot2c_f32_bf16_e32 v154, v14, v126
	v_dot2c_f32_bf16_e32 v155, v15, v127
	s_nop 0
	v_add_f32_e32 v156, v152, v153
	s_nop 0
	v_add_f32_e32 v157, v154, v155
	v_add_f32_e32 v158, v156, v157
	s_nop 1
	v_add_f32_dpp v158, v158, v158 quad_perm:[1,0,3,2] row_mask:0xf bank_mask:0xf
	s_nop 1
	v_add_f32_dpp v158, v158, v158 quad_perm:[2,3,0,1] row_mask:0xf bank_mask:0xf
	s_nop 1
	v_add_f32_dpp v158, v158, v158 row_half_mirror row_mask:0xf bank_mask:0xf
	s_mov_b64 exec, s[14:15]
	ds_add_f32 v169, v158 offset:160
	s_mov_b64 exec, -1
	v_mov_b32_e32 v152, 0
	v_mov_b32_e32 v153, 0
	v_mov_b32_e32 v154, 0
	v_mov_b32_e32 v155, 0
	s_waitcnt vmcnt(18)
	v_cvt_scalef32_pk32_bf16_fp6 v[0:15], v[52:57], 1.0
	v_dot2c_f32_bf16_e32 v152, v0, v112
	v_dot2c_f32_bf16_e32 v153, v1, v113
	v_dot2c_f32_bf16_e32 v154, v2, v114
	v_dot2c_f32_bf16_e32 v155, v3, v115
	v_dot2c_f32_bf16_e32 v152, v4, v116
	v_dot2c_f32_bf16_e32 v153, v5, v117
	v_dot2c_f32_bf16_e32 v154, v6, v118
	v_dot2c_f32_bf16_e32 v155, v7, v119
	v_dot2c_f32_bf16_e32 v152, v8, v120
	v_dot2c_f32_bf16_e32 v153, v9, v121
	v_dot2c_f32_bf16_e32 v154, v10, v122
	v_dot2c_f32_bf16_e32 v155, v11, v123
	v_dot2c_f32_bf16_e32 v152, v12, v124
	v_dot2c_f32_bf16_e32 v153, v13, v125
	v_dot2c_f32_bf16_e32 v154, v14, v126
	v_dot2c_f32_bf16_e32 v155, v15, v127
	s_nop 0
	v_add_f32_e32 v156, v152, v153
	s_nop 0
	v_add_f32_e32 v157, v154, v155
	v_add_f32_e32 v158, v156, v157
	s_nop 1
	v_add_f32_dpp v158, v158, v158 quad_perm:[1,0,3,2] row_mask:0xf bank_mask:0xf
	s_nop 1
	v_add_f32_dpp v158, v158, v158 quad_perm:[2,3,0,1] row_mask:0xf bank_mask:0xf
	s_nop 1
	v_add_f32_dpp v158, v158, v158 row_half_mirror row_mask:0xf bank_mask:0xf
	s_mov_b64 exec, s[14:15]
	ds_add_f32 v169, v158 offset:192
	s_mov_b64 exec, -1
	v_mov_b32_e32 v152, 0
	v_mov_b32_e32 v153, 0
	v_mov_b32_e32 v154, 0
	v_mov_b32_e32 v155, 0
	s_waitcnt vmcnt(16)
	v_cvt_scalef32_pk32_bf16_fp6 v[0:15], v[58:63], 1.0
	v_dot2c_f32_bf16_e32 v152, v0, v112
	v_dot2c_f32_bf16_e32 v153, v1, v113
	v_dot2c_f32_bf16_e32 v154, v2, v114
	v_dot2c_f32_bf16_e32 v155, v3, v115
	v_dot2c_f32_bf16_e32 v152, v4, v116
	v_dot2c_f32_bf16_e32 v153, v5, v117
	v_dot2c_f32_bf16_e32 v154, v6, v118
	v_dot2c_f32_bf16_e32 v155, v7, v119
	v_dot2c_f32_bf16_e32 v152, v8, v120
	v_dot2c_f32_bf16_e32 v153, v9, v121
	v_dot2c_f32_bf16_e32 v154, v10, v122
	v_dot2c_f32_bf16_e32 v155, v11, v123
	v_dot2c_f32_bf16_e32 v152, v12, v124
	v_dot2c_f32_bf16_e32 v153, v13, v125
	v_dot2c_f32_bf16_e32 v154, v14, v126
	v_dot2c_f32_bf16_e32 v155, v15, v127
	s_nop 0
	v_add_f32_e32 v156, v152, v153
	s_nop 0
	v_add_f32_e32 v157, v154, v155
	v_add_f32_e32 v158, v156, v157
	s_nop 1
	v_add_f32_dpp v158, v158, v158 quad_perm:[1,0,3,2] row_mask:0xf bank_mask:0xf
	s_nop 1
	v_add_f32_dpp v158, v158, v158 quad_perm:[2,3,0,1] row_mask:0xf bank_mask:0xf
	s_nop 1
	v_add_f32_dpp v158, v158, v158 row_half_mirror row_mask:0xf bank_mask:0xf
	s_mov_b64 exec, s[14:15]
	ds_add_f32 v169, v158 offset:224
	s_mov_b64 exec, -1
	s_add_u32 s16, s16, 1
	s_and_b32 s19, s16, 15
	s_lshr_b32 s50, s16, 4
	s_lshl_b32 s51, s19, 9
	s_mul_i32 s17, s19, s65
	s_lshl_b32 s18, s50, 9
	s_add_u32 s17, s17, s18
	s_add_u32 s12, s8, s17
	s_addc_u32 s13, s9, 0
	s_mul_i32 s17, s50, 0x300000
	s_add_u32 s4, s26, 0x1800000
	s_addc_u32 s5, s27, 0
	s_add_u32 s4, s4, s17
	s_addc_u32 s5, s5, 0
	v_mov_b32_e32 v166, v164
	v_add_u32_e32 v168, s51, v161
	v_add_u32_e32 v170, s51, v162
	global_load_dwordx4 v[128:131], v163, s[12:13]
	global_load_dwordx4 v[132:135], v163, s[12:13] offset:16
	global_load_dwordx4 v[136:139], v163, s[12:13] offset:32
	global_load_dwordx4 v[140:143], v163, s[12:13] offset:48
	ds_read2_b32 v[144:145], v168 offset0:0 offset1:8
	ds_read2_b32 v[146:147], v168 offset0:16 offset1:24
	ds_read2_b32 v[148:149], v168 offset0:32 offset1:40
	ds_read2_b32 v[150:151], v168 offset0:48 offset1:56
	s_waitcnt lgkmcnt(0)
	v_mad_u32_u24 v144, v144, s64, v166
	v_mad_u32_u24 v145, v145, s64, v166
	v_mad_u32_u24 v146, v146, s64, v166
	v_mad_u32_u24 v147, v147, s64, v166
	v_mad_u32_u24 v148, v148, s64, v166
	v_mad_u32_u24 v149, v149, s64, v166
	v_mad_u32_u24 v150, v150, s64, v166
	v_mad_u32_u24 v151, v151, s64, v166
	global_load_dwordx4 v[16:19], v144, s[4:5]
	global_load_dwordx2 v[20:21], v144, s[4:5] offset:16
	global_load_dwordx4 v[22:25], v145, s[4:5]
	global_load_dwordx2 v[26:27], v145, s[4:5] offset:16
	global_load_dwordx4 v[28:31], v146, s[4:5]
	global_load_dwordx2 v[32:33], v146, s[4:5] offset:16
	global_load_dwordx4 v[34:37], v147, s[4:5]
	global_load_dwordx2 v[38:39], v147, s[4:5] offset:16
	global_load_dwordx4 v[40:43], v148, s[4:5]
	global_load_dwordx2 v[44:45], v148, s[4:5] offset:16
	global_load_dwordx4 v[46:49], v149, s[4:5]
	global_load_dwordx2 v[50:51], v149, s[4:5] offset:16
	global_load_dwordx4 v[52:55], v150, s[4:5]
	global_load_dwordx2 v[56:57], v150, s[4:5] offset:16
	global_load_dwordx4 v[58:61], v151, s[4:5]
	global_load_dwordx2 v[62:63], v151, s[4:5] offset:16
	v_mov_b32_e32 v152, 0
	v_mov_b32_e32 v153, 0
	v_mov_b32_e32 v154, 0
	v_mov_b32_e32 v155, 0
	s_waitcnt vmcnt(34)
	v_cvt_scalef32_pk32_bf16_fp6 v[0:15], v[64:69], 1.0
	v_dot2c_f32_bf16_e32 v152, v0, v112
	v_dot2c_f32_bf16_e32 v153, v1, v113
	v_dot2c_f32_bf16_e32 v154, v2, v114
	v_dot2c_f32_bf16_e32 v155, v3, v115
	v_dot2c_f32_bf16_e32 v152, v4, v116
	v_dot2c_f32_bf16_e32 v153, v5, v117
	v_dot2c_f32_bf16_e32 v154, v6, v118
	v_dot2c_f32_bf16_e32 v155, v7, v119
	v_dot2c_f32_bf16_e32 v152, v8, v120
	v_dot2c_f32_bf16_e32 v153, v9, v121
	v_dot2c_f32_bf16_e32 v154, v10, v122
	v_dot2c_f32_bf16_e32 v155, v11, v123
	v_dot2c_f32_bf16_e32 v152, v12, v124
	v_dot2c_f32_bf16_e32 v153, v13, v125
	v_dot2c_f32_bf16_e32 v154, v14, v126
	v_dot2c_f32_bf16_e32 v155, v15, v127
	s_nop 0
	v_add_f32_e32 v156, v152, v153
	s_nop 0
	v_add_f32_e32 v157, v154, v155
	v_add_f32_e32 v158, v156, v157
	s_nop 1
	v_add_f32_dpp v158, v158, v158 quad_perm:[1,0,3,2] row_mask:0xf bank_mask:0xf
	s_nop 1
	v_add_f32_dpp v158, v158, v158 quad_perm:[2,3,0,1] row_mask:0xf bank_mask:0xf
	s_nop 1
	v_add_f32_dpp v158, v158, v158 row_half_mirror row_mask:0xf bank_mask:0xf
	s_mov_b64 exec, s[14:15]
	ds_add_f32 v169, v158 offset:256
	s_mov_b64 exec, -1
	v_mov_b32_e32 v152, 0
	v_mov_b32_e32 v153, 0
	v_mov_b32_e32 v154, 0
	v_mov_b32_e32 v155, 0
	s_waitcnt vmcnt(32)
	v_cvt_scalef32_pk32_bf16_fp6 v[0:15], v[70:75], 1.0
	v_dot2c_f32_bf16_e32 v152, v0, v112
	v_dot2c_f32_bf16_e32 v153, v1, v113
	v_dot2c_f32_bf16_e32 v154, v2, v114
	v_dot2c_f32_bf16_e32 v155, v3, v115
	v_dot2c_f32_bf16_e32 v152, v4, v116
	v_dot2c_f32_bf16_e32 v153, v5, v117
	v_dot2c_f32_bf16_e32 v154, v6, v118
	v_dot2c_f32_bf16_e32 v155, v7, v119
	v_dot2c_f32_bf16_e32 v152, v8, v120
	v_dot2c_f32_bf16_e32 v153, v9, v121
	v_dot2c_f32_bf16_e32 v154, v10, v122
	v_dot2c_f32_bf16_e32 v155, v11, v123
	v_dot2c_f32_bf16_e32 v152, v12, v124
	v_dot2c_f32_bf16_e32 v153, v13, v125
	v_dot2c_f32_bf16_e32 v154, v14, v126
	v_dot2c_f32_bf16_e32 v155, v15, v127
	s_nop 0
	v_add_f32_e32 v156, v152, v153
	s_nop 0
	v_add_f32_e32 v157, v154, v155
	v_add_f32_e32 v158, v156, v157
	s_nop 1
	v_add_f32_dpp v158, v158, v158 quad_perm:[1,0,3,2] row_mask:0xf bank_mask:0xf
	s_nop 1
	v_add_f32_dpp v158, v158, v158 quad_perm:[2,3,0,1] row_mask:0xf bank_mask:0xf
	s_nop 1
	v_add_f32_dpp v158, v158, v158 row_half_mirror row_mask:0xf bank_mask:0xf
	s_mov_b64 exec, s[14:15]
	ds_add_f32 v169, v158 offset:288
	s_mov_b64 exec, -1
	v_mov_b32_e32 v152, 0
	v_mov_b32_e32 v153, 0
	v_mov_b32_e32 v154, 0
	v_mov_b32_e32 v155, 0
	s_waitcnt vmcnt(30)
	v_cvt_scalef32_pk32_bf16_fp6 v[0:15], v[76:81], 1.0
	v_dot2c_f32_bf16_e32 v152, v0, v112
	v_dot2c_f32_bf16_e32 v153, v1, v113
	v_dot2c_f32_bf16_e32 v154, v2, v114
	v_dot2c_f32_bf16_e32 v155, v3, v115
	v_dot2c_f32_bf16_e32 v152, v4, v116
	v_dot2c_f32_bf16_e32 v153, v5, v117
	v_dot2c_f32_bf16_e32 v154, v6, v118
	v_dot2c_f32_bf16_e32 v155, v7, v119
	v_dot2c_f32_bf16_e32 v152, v8, v120
	v_dot2c_f32_bf16_e32 v153, v9, v121
	v_dot2c_f32_bf16_e32 v154, v10, v122
	v_dot2c_f32_bf16_e32 v155, v11, v123
	v_dot2c_f32_bf16_e32 v152, v12, v124
	v_dot2c_f32_bf16_e32 v153, v13, v125
	v_dot2c_f32_bf16_e32 v154, v14, v126
	v_dot2c_f32_bf16_e32 v155, v15, v127
	s_nop 0
	v_add_f32_e32 v156, v152, v153
	s_nop 0
	v_add_f32_e32 v157, v154, v155
	v_add_f32_e32 v158, v156, v157
	s_nop 1
	v_add_f32_dpp v158, v158, v158 quad_perm:[1,0,3,2] row_mask:0xf bank_mask:0xf
	s_nop 1
	v_add_f32_dpp v158, v158, v158 quad_perm:[2,3,0,1] row_mask:0xf bank_mask:0xf
	s_nop 1
	v_add_f32_dpp v158, v158, v158 row_half_mirror row_mask:0xf bank_mask:0xf
	s_mov_b64 exec, s[14:15]
	ds_add_f32 v169, v158 offset:320
	s_mov_b64 exec, -1
	v_mov_b32_e32 v152, 0
	v_mov_b32_e32 v153, 0
	v_mov_b32_e32 v154, 0
	v_mov_b32_e32 v155, 0
	s_waitcnt vmcnt(28)
	v_cvt_scalef32_pk32_bf16_fp6 v[0:15], v[82:87], 1.0
	v_dot2c_f32_bf16_e32 v152, v0, v112
	v_dot2c_f32_bf16_e32 v153, v1, v113
	v_dot2c_f32_bf16_e32 v154, v2, v114
	v_dot2c_f32_bf16_e32 v155, v3, v115
	v_dot2c_f32_bf16_e32 v152, v4, v116
	v_dot2c_f32_bf16_e32 v153, v5, v117
	v_dot2c_f32_bf16_e32 v154, v6, v118
	v_dot2c_f32_bf16_e32 v155, v7, v119
	v_dot2c_f32_bf16_e32 v152, v8, v120
	v_dot2c_f32_bf16_e32 v153, v9, v121
	v_dot2c_f32_bf16_e32 v154, v10, v122
	v_dot2c_f32_bf16_e32 v155, v11, v123
	v_dot2c_f32_bf16_e32 v152, v12, v124
	v_dot2c_f32_bf16_e32 v153, v13, v125
	v_dot2c_f32_bf16_e32 v154, v14, v126
	v_dot2c_f32_bf16_e32 v155, v15, v127
	s_nop 0
	v_add_f32_e32 v156, v152, v153
	s_nop 0
	v_add_f32_e32 v157, v154, v155
	v_add_f32_e32 v158, v156, v157
	s_nop 1
	v_add_f32_dpp v158, v158, v158 quad_perm:[1,0,3,2] row_mask:0xf bank_mask:0xf
	s_nop 1
	v_add_f32_dpp v158, v158, v158 quad_perm:[2,3,0,1] row_mask:0xf bank_mask:0xf
	s_nop 1
	v_add_f32_dpp v158, v158, v158 row_half_mirror row_mask:0xf bank_mask:0xf
	s_mov_b64 exec, s[14:15]
	ds_add_f32 v169, v158 offset:352
	s_mov_b64 exec, -1
	v_mov_b32_e32 v152, 0
	v_mov_b32_e32 v153, 0
	v_mov_b32_e32 v154, 0
	v_mov_b32_e32 v155, 0
	s_waitcnt vmcnt(26)
	v_cvt_scalef32_pk32_bf16_fp6 v[0:15], v[88:93], 1.0
	v_dot2c_f32_bf16_e32 v152, v0, v112
	v_dot2c_f32_bf16_e32 v153, v1, v113
	v_dot2c_f32_bf16_e32 v154, v2, v114
	v_dot2c_f32_bf16_e32 v155, v3, v115
	v_dot2c_f32_bf16_e32 v152, v4, v116
	v_dot2c_f32_bf16_e32 v153, v5, v117
	v_dot2c_f32_bf16_e32 v154, v6, v118
	v_dot2c_f32_bf16_e32 v155, v7, v119
	v_dot2c_f32_bf16_e32 v152, v8, v120
	v_dot2c_f32_bf16_e32 v153, v9, v121
	v_dot2c_f32_bf16_e32 v154, v10, v122
	v_dot2c_f32_bf16_e32 v155, v11, v123
	v_dot2c_f32_bf16_e32 v152, v12, v124
	v_dot2c_f32_bf16_e32 v153, v13, v125
	v_dot2c_f32_bf16_e32 v154, v14, v126
	v_dot2c_f32_bf16_e32 v155, v15, v127
	s_nop 0
	v_add_f32_e32 v156, v152, v153
	s_nop 0
	v_add_f32_e32 v157, v154, v155
	v_add_f32_e32 v158, v156, v157
	s_nop 1
	v_add_f32_dpp v158, v158, v158 quad_perm:[1,0,3,2] row_mask:0xf bank_mask:0xf
	s_nop 1
	v_add_f32_dpp v158, v158, v158 quad_perm:[2,3,0,1] row_mask:0xf bank_mask:0xf
	s_nop 1
	v_add_f32_dpp v158, v158, v158 row_half_mirror row_mask:0xf bank_mask:0xf
	s_mov_b64 exec, s[14:15]
	ds_add_f32 v169, v158 offset:384
	s_mov_b64 exec, -1
	v_mov_b32_e32 v152, 0
	v_mov_b32_e32 v153, 0
	v_mov_b32_e32 v154, 0
	v_mov_b32_e32 v155, 0
	s_waitcnt vmcnt(24)
	v_cvt_scalef32_pk32_bf16_fp6 v[0:15], v[94:99], 1.0
	v_dot2c_f32_bf16_e32 v152, v0, v112
	v_dot2c_f32_bf16_e32 v153, v1, v113
	v_dot2c_f32_bf16_e32 v154, v2, v114
	v_dot2c_f32_bf16_e32 v155, v3, v115
	v_dot2c_f32_bf16_e32 v152, v4, v116
	v_dot2c_f32_bf16_e32 v153, v5, v117
	v_dot2c_f32_bf16_e32 v154, v6, v118
	v_dot2c_f32_bf16_e32 v155, v7, v119
	v_dot2c_f32_bf16_e32 v152, v8, v120
	v_dot2c_f32_bf16_e32 v153, v9, v121
	v_dot2c_f32_bf16_e32 v154, v10, v122
	v_dot2c_f32_bf16_e32 v155, v11, v123
	v_dot2c_f32_bf16_e32 v152, v12, v124
	v_dot2c_f32_bf16_e32 v153, v13, v125
	v_dot2c_f32_bf16_e32 v154, v14, v126
	v_dot2c_f32_bf16_e32 v155, v15, v127
	s_nop 0
	v_add_f32_e32 v156, v152, v153
	s_nop 0
	v_add_f32_e32 v157, v154, v155
	v_add_f32_e32 v158, v156, v157
	s_nop 1
	v_add_f32_dpp v158, v158, v158 quad_perm:[1,0,3,2] row_mask:0xf bank_mask:0xf
	s_nop 1
	v_add_f32_dpp v158, v158, v158 quad_perm:[2,3,0,1] row_mask:0xf bank_mask:0xf
	s_nop 1
	v_add_f32_dpp v158, v158, v158 row_half_mirror row_mask:0xf bank_mask:0xf
	s_mov_b64 exec, s[14:15]
	ds_add_f32 v169, v158 offset:416
	s_mov_b64 exec, -1
	v_mov_b32_e32 v152, 0
	v_mov_b32_e32 v153, 0
	v_mov_b32_e32 v154, 0
	v_mov_b32_e32 v155, 0
	s_waitcnt vmcnt(22)
	v_cvt_scalef32_pk32_bf16_fp6 v[0:15], v[100:105], 1.0
	v_dot2c_f32_bf16_e32 v152, v0, v112
	v_dot2c_f32_bf16_e32 v153, v1, v113
	v_dot2c_f32_bf16_e32 v154, v2, v114
	v_dot2c_f32_bf16_e32 v155, v3, v115
	v_dot2c_f32_bf16_e32 v152, v4, v116
	v_dot2c_f32_bf16_e32 v153, v5, v117
	v_dot2c_f32_bf16_e32 v154, v6, v118
	v_dot2c_f32_bf16_e32 v155, v7, v119
	v_dot2c_f32_bf16_e32 v152, v8, v120
	v_dot2c_f32_bf16_e32 v153, v9, v121
	v_dot2c_f32_bf16_e32 v154, v10, v122
	v_dot2c_f32_bf16_e32 v155, v11, v123
	v_dot2c_f32_bf16_e32 v152, v12, v124
	v_dot2c_f32_bf16_e32 v153, v13, v125
	v_dot2c_f32_bf16_e32 v154, v14, v126
	v_dot2c_f32_bf16_e32 v155, v15, v127
	s_nop 0
	v_add_f32_e32 v156, v152, v153
	s_nop 0
	v_add_f32_e32 v157, v154, v155
	v_add_f32_e32 v158, v156, v157
	s_nop 1
	v_add_f32_dpp v158, v158, v158 quad_perm:[1,0,3,2] row_mask:0xf bank_mask:0xf
	s_nop 1
	v_add_f32_dpp v158, v158, v158 quad_perm:[2,3,0,1] row_mask:0xf bank_mask:0xf
	s_nop 1
	v_add_f32_dpp v158, v158, v158 row_half_mirror row_mask:0xf bank_mask:0xf
	s_mov_b64 exec, s[14:15]
	ds_add_f32 v169, v158 offset:448
	s_mov_b64 exec, -1
	v_mov_b32_e32 v152, 0
	v_mov_b32_e32 v153, 0
	v_mov_b32_e32 v154, 0
	v_mov_b32_e32 v155, 0
	s_waitcnt vmcnt(20)
	v_cvt_scalef32_pk32_bf16_fp6 v[0:15], v[106:111], 1.0
	v_dot2c_f32_bf16_e32 v152, v0, v112
	v_dot2c_f32_bf16_e32 v153, v1, v113
	v_dot2c_f32_bf16_e32 v154, v2, v114
	v_dot2c_f32_bf16_e32 v155, v3, v115
	v_dot2c_f32_bf16_e32 v152, v4, v116
	v_dot2c_f32_bf16_e32 v153, v5, v117
	v_dot2c_f32_bf16_e32 v154, v6, v118
	v_dot2c_f32_bf16_e32 v155, v7, v119
	v_dot2c_f32_bf16_e32 v152, v8, v120
	v_dot2c_f32_bf16_e32 v153, v9, v121
	v_dot2c_f32_bf16_e32 v154, v10, v122
	v_dot2c_f32_bf16_e32 v155, v11, v123
	v_dot2c_f32_bf16_e32 v152, v12, v124
	v_dot2c_f32_bf16_e32 v153, v13, v125
	v_dot2c_f32_bf16_e32 v154, v14, v126
	v_dot2c_f32_bf16_e32 v155, v15, v127
	s_nop 0
	v_add_f32_e32 v156, v152, v153
	s_nop 0
	v_add_f32_e32 v157, v154, v155
	v_add_f32_e32 v158, v156, v157
	s_nop 1
	v_add_f32_dpp v158, v158, v158 quad_perm:[1,0,3,2] row_mask:0xf bank_mask:0xf
	s_nop 1
	v_add_f32_dpp v158, v158, v158 quad_perm:[2,3,0,1] row_mask:0xf bank_mask:0xf
	s_nop 1
	v_add_f32_dpp v158, v158, v158 row_half_mirror row_mask:0xf bank_mask:0xf
	s_mov_b64 exec, s[14:15]
	ds_add_f32 v169, v158 offset:480
	s_mov_b64 exec, -1
	ds_read2_b32 v[144:145], v168 offset0:64 offset1:72
	ds_read2_b32 v[146:147], v168 offset0:80 offset1:88
	ds_read2_b32 v[148:149], v168 offset0:96 offset1:104
	ds_read2_b32 v[150:151], v168 offset0:112 offset1:120
	s_waitcnt lgkmcnt(0)
	v_mad_u32_u24 v144, v144, s64, v166
	v_mad_u32_u24 v145, v145, s64, v166
	v_mad_u32_u24 v146, v146, s64, v166
	v_mad_u32_u24 v147, v147, s64, v166
	v_mad_u32_u24 v148, v148, s64, v166
	v_mad_u32_u24 v149, v149, s64, v166
	v_mad_u32_u24 v150, v150, s64, v166
	v_mad_u32_u24 v151, v151, s64, v166
	global_load_dwordx4 v[64:67], v144, s[4:5]
	global_load_dwordx2 v[68:69], v144, s[4:5] offset:16
	global_load_dwordx4 v[70:73], v145, s[4:5]
	global_load_dwordx2 v[74:75], v145, s[4:5] offset:16
	global_load_dwordx4 v[76:79], v146, s[4:5]
	global_load_dwordx2 v[80:81], v146, s[4:5] offset:16
	global_load_dwordx4 v[82:85], v147, s[4:5]
	global_load_dwordx2 v[86:87], v147, s[4:5] offset:16
	global_load_dwordx4 v[88:91], v148, s[4:5]
	global_load_dwordx2 v[92:93], v148, s[4:5] offset:16
	global_load_dwordx4 v[94:97], v149, s[4:5]
	global_load_dwordx2 v[98:99], v149, s[4:5] offset:16
	global_load_dwordx4 v[100:103], v150, s[4:5]
	global_load_dwordx2 v[104:105], v150, s[4:5] offset:16
	global_load_dwordx4 v[106:109], v151, s[4:5]
	global_load_dwordx2 v[110:111], v151, s[4:5] offset:16
	v_mov_b32_e32 v152, 0
	v_mov_b32_e32 v153, 0
	v_mov_b32_e32 v154, 0
	v_mov_b32_e32 v155, 0
	s_waitcnt vmcnt(30)
	v_cvt_scalef32_pk32_bf16_fp6 v[0:15], v[16:21], 1.0
	v_dot2c_f32_bf16_e32 v152, v0, v128
	v_dot2c_f32_bf16_e32 v153, v1, v129
	v_dot2c_f32_bf16_e32 v154, v2, v130
	v_dot2c_f32_bf16_e32 v155, v3, v131
	v_dot2c_f32_bf16_e32 v152, v4, v132
	v_dot2c_f32_bf16_e32 v153, v5, v133
	v_dot2c_f32_bf16_e32 v154, v6, v134
	v_dot2c_f32_bf16_e32 v155, v7, v135
	v_dot2c_f32_bf16_e32 v152, v8, v136
	v_dot2c_f32_bf16_e32 v153, v9, v137
	v_dot2c_f32_bf16_e32 v154, v10, v138
	v_dot2c_f32_bf16_e32 v155, v11, v139
	v_dot2c_f32_bf16_e32 v152, v12, v140
	v_dot2c_f32_bf16_e32 v153, v13, v141
	v_dot2c_f32_bf16_e32 v154, v14, v142
	v_dot2c_f32_bf16_e32 v155, v15, v143
	s_nop 0
	v_add_f32_e32 v156, v152, v153
	s_nop 0
	v_add_f32_e32 v157, v154, v155
	v_add_f32_e32 v158, v156, v157
	s_nop 1
	v_add_f32_dpp v158, v158, v158 quad_perm:[1,0,3,2] row_mask:0xf bank_mask:0xf
	s_nop 1
	v_add_f32_dpp v158, v158, v158 quad_perm:[2,3,0,1] row_mask:0xf bank_mask:0xf
	s_nop 1
	v_add_f32_dpp v158, v158, v158 row_half_mirror row_mask:0xf bank_mask:0xf
	s_mov_b64 exec, s[14:15]
	ds_add_f32 v170, v158 offset:0
	s_mov_b64 exec, -1
	v_mov_b32_e32 v152, 0
	v_mov_b32_e32 v153, 0
	v_mov_b32_e32 v154, 0
	v_mov_b32_e32 v155, 0
	s_waitcnt vmcnt(28)
	v_cvt_scalef32_pk32_bf16_fp6 v[0:15], v[22:27], 1.0
	v_dot2c_f32_bf16_e32 v152, v0, v128
	v_dot2c_f32_bf16_e32 v153, v1, v129
	v_dot2c_f32_bf16_e32 v154, v2, v130
	v_dot2c_f32_bf16_e32 v155, v3, v131
	v_dot2c_f32_bf16_e32 v152, v4, v132
	v_dot2c_f32_bf16_e32 v153, v5, v133
	v_dot2c_f32_bf16_e32 v154, v6, v134
	v_dot2c_f32_bf16_e32 v155, v7, v135
	v_dot2c_f32_bf16_e32 v152, v8, v136
	v_dot2c_f32_bf16_e32 v153, v9, v137
	v_dot2c_f32_bf16_e32 v154, v10, v138
	v_dot2c_f32_bf16_e32 v155, v11, v139
	v_dot2c_f32_bf16_e32 v152, v12, v140
	v_dot2c_f32_bf16_e32 v153, v13, v141
	v_dot2c_f32_bf16_e32 v154, v14, v142
	v_dot2c_f32_bf16_e32 v155, v15, v143
	s_nop 0
	v_add_f32_e32 v156, v152, v153
	s_nop 0
	v_add_f32_e32 v157, v154, v155
	v_add_f32_e32 v158, v156, v157
	s_nop 1
	v_add_f32_dpp v158, v158, v158 quad_perm:[1,0,3,2] row_mask:0xf bank_mask:0xf
	s_nop 1
	v_add_f32_dpp v158, v158, v158 quad_perm:[2,3,0,1] row_mask:0xf bank_mask:0xf
	s_nop 1
	v_add_f32_dpp v158, v158, v158 row_half_mirror row_mask:0xf bank_mask:0xf
	s_mov_b64 exec, s[14:15]
	ds_add_f32 v170, v158 offset:32
	s_mov_b64 exec, -1
	v_mov_b32_e32 v152, 0
	v_mov_b32_e32 v153, 0
	v_mov_b32_e32 v154, 0
	v_mov_b32_e32 v155, 0
	s_waitcnt vmcnt(26)
	v_cvt_scalef32_pk32_bf16_fp6 v[0:15], v[28:33], 1.0
	v_dot2c_f32_bf16_e32 v152, v0, v128
	v_dot2c_f32_bf16_e32 v153, v1, v129
	v_dot2c_f32_bf16_e32 v154, v2, v130
	v_dot2c_f32_bf16_e32 v155, v3, v131
	v_dot2c_f32_bf16_e32 v152, v4, v132
	v_dot2c_f32_bf16_e32 v153, v5, v133
	v_dot2c_f32_bf16_e32 v154, v6, v134
	v_dot2c_f32_bf16_e32 v155, v7, v135
	v_dot2c_f32_bf16_e32 v152, v8, v136
	v_dot2c_f32_bf16_e32 v153, v9, v137
	v_dot2c_f32_bf16_e32 v154, v10, v138
	v_dot2c_f32_bf16_e32 v155, v11, v139
	v_dot2c_f32_bf16_e32 v152, v12, v140
	v_dot2c_f32_bf16_e32 v153, v13, v141
	v_dot2c_f32_bf16_e32 v154, v14, v142
	v_dot2c_f32_bf16_e32 v155, v15, v143
	s_nop 0
	v_add_f32_e32 v156, v152, v153
	s_nop 0
	v_add_f32_e32 v157, v154, v155
	v_add_f32_e32 v158, v156, v157
	s_nop 1
	v_add_f32_dpp v158, v158, v158 quad_perm:[1,0,3,2] row_mask:0xf bank_mask:0xf
	s_nop 1
	v_add_f32_dpp v158, v158, v158 quad_perm:[2,3,0,1] row_mask:0xf bank_mask:0xf
	s_nop 1
	v_add_f32_dpp v158, v158, v158 row_half_mirror row_mask:0xf bank_mask:0xf
	s_mov_b64 exec, s[14:15]
	ds_add_f32 v170, v158 offset:64
	s_mov_b64 exec, -1
	v_mov_b32_e32 v152, 0
	v_mov_b32_e32 v153, 0
	v_mov_b32_e32 v154, 0
	v_mov_b32_e32 v155, 0
	s_waitcnt vmcnt(24)
	v_cvt_scalef32_pk32_bf16_fp6 v[0:15], v[34:39], 1.0
	v_dot2c_f32_bf16_e32 v152, v0, v128
	v_dot2c_f32_bf16_e32 v153, v1, v129
	v_dot2c_f32_bf16_e32 v154, v2, v130
	v_dot2c_f32_bf16_e32 v155, v3, v131
	v_dot2c_f32_bf16_e32 v152, v4, v132
	v_dot2c_f32_bf16_e32 v153, v5, v133
	v_dot2c_f32_bf16_e32 v154, v6, v134
	v_dot2c_f32_bf16_e32 v155, v7, v135
	v_dot2c_f32_bf16_e32 v152, v8, v136
	v_dot2c_f32_bf16_e32 v153, v9, v137
	v_dot2c_f32_bf16_e32 v154, v10, v138
	v_dot2c_f32_bf16_e32 v155, v11, v139
	v_dot2c_f32_bf16_e32 v152, v12, v140
	v_dot2c_f32_bf16_e32 v153, v13, v141
	v_dot2c_f32_bf16_e32 v154, v14, v142
	v_dot2c_f32_bf16_e32 v155, v15, v143
	s_nop 0
	v_add_f32_e32 v156, v152, v153
	s_nop 0
	v_add_f32_e32 v157, v154, v155
	v_add_f32_e32 v158, v156, v157
	s_nop 1
	v_add_f32_dpp v158, v158, v158 quad_perm:[1,0,3,2] row_mask:0xf bank_mask:0xf
	s_nop 1
	v_add_f32_dpp v158, v158, v158 quad_perm:[2,3,0,1] row_mask:0xf bank_mask:0xf
	s_nop 1
	v_add_f32_dpp v158, v158, v158 row_half_mirror row_mask:0xf bank_mask:0xf
	s_mov_b64 exec, s[14:15]
	ds_add_f32 v170, v158 offset:96
	s_mov_b64 exec, -1
	v_mov_b32_e32 v152, 0
	v_mov_b32_e32 v153, 0
	v_mov_b32_e32 v154, 0
	v_mov_b32_e32 v155, 0
	s_waitcnt vmcnt(22)
	v_cvt_scalef32_pk32_bf16_fp6 v[0:15], v[40:45], 1.0
	v_dot2c_f32_bf16_e32 v152, v0, v128
	v_dot2c_f32_bf16_e32 v153, v1, v129
	v_dot2c_f32_bf16_e32 v154, v2, v130
	v_dot2c_f32_bf16_e32 v155, v3, v131
	v_dot2c_f32_bf16_e32 v152, v4, v132
	v_dot2c_f32_bf16_e32 v153, v5, v133
	v_dot2c_f32_bf16_e32 v154, v6, v134
	v_dot2c_f32_bf16_e32 v155, v7, v135
	v_dot2c_f32_bf16_e32 v152, v8, v136
	v_dot2c_f32_bf16_e32 v153, v9, v137
	v_dot2c_f32_bf16_e32 v154, v10, v138
	v_dot2c_f32_bf16_e32 v155, v11, v139
	v_dot2c_f32_bf16_e32 v152, v12, v140
	v_dot2c_f32_bf16_e32 v153, v13, v141
	v_dot2c_f32_bf16_e32 v154, v14, v142
	v_dot2c_f32_bf16_e32 v155, v15, v143
	s_nop 0
	v_add_f32_e32 v156, v152, v153
	s_nop 0
	v_add_f32_e32 v157, v154, v155
	v_add_f32_e32 v158, v156, v157
	s_nop 1
	v_add_f32_dpp v158, v158, v158 quad_perm:[1,0,3,2] row_mask:0xf bank_mask:0xf
	s_nop 1
	v_add_f32_dpp v158, v158, v158 quad_perm:[2,3,0,1] row_mask:0xf bank_mask:0xf
	s_nop 1
	v_add_f32_dpp v158, v158, v158 row_half_mirror row_mask:0xf bank_mask:0xf
	s_mov_b64 exec, s[14:15]
	ds_add_f32 v170, v158 offset:128
	s_mov_b64 exec, -1
	v_mov_b32_e32 v152, 0
	v_mov_b32_e32 v153, 0
	v_mov_b32_e32 v154, 0
	v_mov_b32_e32 v155, 0
	s_waitcnt vmcnt(20)
	v_cvt_scalef32_pk32_bf16_fp6 v[0:15], v[46:51], 1.0
	v_dot2c_f32_bf16_e32 v152, v0, v128
	v_dot2c_f32_bf16_e32 v153, v1, v129
	v_dot2c_f32_bf16_e32 v154, v2, v130
	v_dot2c_f32_bf16_e32 v155, v3, v131
	v_dot2c_f32_bf16_e32 v152, v4, v132
	v_dot2c_f32_bf16_e32 v153, v5, v133
	v_dot2c_f32_bf16_e32 v154, v6, v134
	v_dot2c_f32_bf16_e32 v155, v7, v135
	v_dot2c_f32_bf16_e32 v152, v8, v136
	v_dot2c_f32_bf16_e32 v153, v9, v137
	v_dot2c_f32_bf16_e32 v154, v10, v138
	v_dot2c_f32_bf16_e32 v155, v11, v139
	v_dot2c_f32_bf16_e32 v152, v12, v140
	v_dot2c_f32_bf16_e32 v153, v13, v141
	v_dot2c_f32_bf16_e32 v154, v14, v142
	v_dot2c_f32_bf16_e32 v155, v15, v143
	s_nop 0
	v_add_f32_e32 v156, v152, v153
	s_nop 0
	v_add_f32_e32 v157, v154, v155
	v_add_f32_e32 v158, v156, v157
	s_nop 1
	v_add_f32_dpp v158, v158, v158 quad_perm:[1,0,3,2] row_mask:0xf bank_mask:0xf
	s_nop 1
	v_add_f32_dpp v158, v158, v158 quad_perm:[2,3,0,1] row_mask:0xf bank_mask:0xf
	s_nop 1
	v_add_f32_dpp v158, v158, v158 row_half_mirror row_mask:0xf bank_mask:0xf
	s_mov_b64 exec, s[14:15]
	ds_add_f32 v170, v158 offset:160
	s_mov_b64 exec, -1
	v_mov_b32_e32 v152, 0
	v_mov_b32_e32 v153, 0
	v_mov_b32_e32 v154, 0
	v_mov_b32_e32 v155, 0
	s_waitcnt vmcnt(18)
	v_cvt_scalef32_pk32_bf16_fp6 v[0:15], v[52:57], 1.0
	v_dot2c_f32_bf16_e32 v152, v0, v128
	v_dot2c_f32_bf16_e32 v153, v1, v129
	v_dot2c_f32_bf16_e32 v154, v2, v130
	v_dot2c_f32_bf16_e32 v155, v3, v131
	v_dot2c_f32_bf16_e32 v152, v4, v132
	v_dot2c_f32_bf16_e32 v153, v5, v133
	v_dot2c_f32_bf16_e32 v154, v6, v134
	v_dot2c_f32_bf16_e32 v155, v7, v135
	v_dot2c_f32_bf16_e32 v152, v8, v136
	v_dot2c_f32_bf16_e32 v153, v9, v137
	v_dot2c_f32_bf16_e32 v154, v10, v138
	v_dot2c_f32_bf16_e32 v155, v11, v139
	v_dot2c_f32_bf16_e32 v152, v12, v140
	v_dot2c_f32_bf16_e32 v153, v13, v141
	v_dot2c_f32_bf16_e32 v154, v14, v142
	v_dot2c_f32_bf16_e32 v155, v15, v143
	s_nop 0
	v_add_f32_e32 v156, v152, v153
	s_nop 0
	v_add_f32_e32 v157, v154, v155
	v_add_f32_e32 v158, v156, v157
	s_nop 1
	v_add_f32_dpp v158, v158, v158 quad_perm:[1,0,3,2] row_mask:0xf bank_mask:0xf
	s_nop 1
	v_add_f32_dpp v158, v158, v158 quad_perm:[2,3,0,1] row_mask:0xf bank_mask:0xf
	s_nop 1
	v_add_f32_dpp v158, v158, v158 row_half_mirror row_mask:0xf bank_mask:0xf
	s_mov_b64 exec, s[14:15]
	ds_add_f32 v170, v158 offset:192
	s_mov_b64 exec, -1
	v_mov_b32_e32 v152, 0
	v_mov_b32_e32 v153, 0
	v_mov_b32_e32 v154, 0
	v_mov_b32_e32 v155, 0
	s_waitcnt vmcnt(16)
	v_cvt_scalef32_pk32_bf16_fp6 v[0:15], v[58:63], 1.0
	v_dot2c_f32_bf16_e32 v152, v0, v128
	v_dot2c_f32_bf16_e32 v153, v1, v129
	v_dot2c_f32_bf16_e32 v154, v2, v130
	v_dot2c_f32_bf16_e32 v155, v3, v131
	v_dot2c_f32_bf16_e32 v152, v4, v132
	v_dot2c_f32_bf16_e32 v153, v5, v133
	v_dot2c_f32_bf16_e32 v154, v6, v134
	v_dot2c_f32_bf16_e32 v155, v7, v135
	v_dot2c_f32_bf16_e32 v152, v8, v136
	v_dot2c_f32_bf16_e32 v153, v9, v137
	v_dot2c_f32_bf16_e32 v154, v10, v138
	v_dot2c_f32_bf16_e32 v155, v11, v139
	v_dot2c_f32_bf16_e32 v152, v12, v140
	v_dot2c_f32_bf16_e32 v153, v13, v141
	v_dot2c_f32_bf16_e32 v154, v14, v142
	v_dot2c_f32_bf16_e32 v155, v15, v143
	s_nop 0
	v_add_f32_e32 v156, v152, v153
	s_nop 0
	v_add_f32_e32 v157, v154, v155
	v_add_f32_e32 v158, v156, v157
	s_nop 1
	v_add_f32_dpp v158, v158, v158 quad_perm:[1,0,3,2] row_mask:0xf bank_mask:0xf
	s_nop 1
	v_add_f32_dpp v158, v158, v158 quad_perm:[2,3,0,1] row_mask:0xf bank_mask:0xf
	s_nop 1
	v_add_f32_dpp v158, v158, v158 row_half_mirror row_mask:0xf bank_mask:0xf
	s_mov_b64 exec, s[14:15]
	ds_add_f32 v170, v158 offset:224
	s_mov_b64 exec, -1
	s_add_u32 s16, s16, 1
	s_and_b32 s16, s16, 63
	s_and_b32 s19, s16, 15
	s_lshr_b32 s50, s16, 4
	s_lshl_b32 s51, s19, 9
	s_mul_i32 s17, s19, s65
	s_lshl_b32 s18, s50, 9
	s_add_u32 s17, s17, s18
	s_add_u32 s10, s8, s17
	s_addc_u32 s11, s9, 0
	s_mul_i32 s17, s50, 0x300000
	s_add_u32 s4, s26, 0x1800000
	s_addc_u32 s5, s27, 0
	s_add_u32 s4, s4, s17
	s_addc_u32 s5, s5, 0
	v_mov_b32_e32 v165, v164
	v_add_u32_e32 v167, s51, v161
	v_add_u32_e32 v169, s51, v162
	global_load_dwordx4 v[112:115], v163, s[10:11]
	global_load_dwordx4 v[116:119], v163, s[10:11] offset:16
	global_load_dwordx4 v[120:123], v163, s[10:11] offset:32
	global_load_dwordx4 v[124:127], v163, s[10:11] offset:48
	ds_read2_b32 v[144:145], v167 offset0:0 offset1:8
	ds_read2_b32 v[146:147], v167 offset0:16 offset1:24
	ds_read2_b32 v[148:149], v167 offset0:32 offset1:40
	ds_read2_b32 v[150:151], v167 offset0:48 offset1:56
	s_waitcnt lgkmcnt(0)
	v_mad_u32_u24 v144, v144, s64, v165
	v_mad_u32_u24 v145, v145, s64, v165
	v_mad_u32_u24 v146, v146, s64, v165
	v_mad_u32_u24 v147, v147, s64, v165
	v_mad_u32_u24 v148, v148, s64, v165
	v_mad_u32_u24 v149, v149, s64, v165
	v_mad_u32_u24 v150, v150, s64, v165
	v_mad_u32_u24 v151, v151, s64, v165
	global_load_dwordx4 v[16:19], v144, s[4:5]
	global_load_dwordx2 v[20:21], v144, s[4:5] offset:16
	global_load_dwordx4 v[22:25], v145, s[4:5]
	global_load_dwordx2 v[26:27], v145, s[4:5] offset:16
	global_load_dwordx4 v[28:31], v146, s[4:5]
	global_load_dwordx2 v[32:33], v146, s[4:5] offset:16
	global_load_dwordx4 v[34:37], v147, s[4:5]
	global_load_dwordx2 v[38:39], v147, s[4:5] offset:16
	global_load_dwordx4 v[40:43], v148, s[4:5]
	global_load_dwordx2 v[44:45], v148, s[4:5] offset:16
	global_load_dwordx4 v[46:49], v149, s[4:5]
	global_load_dwordx2 v[50:51], v149, s[4:5] offset:16
	global_load_dwordx4 v[52:55], v150, s[4:5]
	global_load_dwordx2 v[56:57], v150, s[4:5] offset:16
	global_load_dwordx4 v[58:61], v151, s[4:5]
	global_load_dwordx2 v[62:63], v151, s[4:5] offset:16
	v_mov_b32_e32 v152, 0
	v_mov_b32_e32 v153, 0
	v_mov_b32_e32 v154, 0
	v_mov_b32_e32 v155, 0
	s_waitcnt vmcnt(34)
	v_cvt_scalef32_pk32_bf16_fp6 v[0:15], v[64:69], 1.0
	v_dot2c_f32_bf16_e32 v152, v0, v128
	v_dot2c_f32_bf16_e32 v153, v1, v129
	v_dot2c_f32_bf16_e32 v154, v2, v130
	v_dot2c_f32_bf16_e32 v155, v3, v131
	v_dot2c_f32_bf16_e32 v152, v4, v132
	v_dot2c_f32_bf16_e32 v153, v5, v133
	v_dot2c_f32_bf16_e32 v154, v6, v134
	v_dot2c_f32_bf16_e32 v155, v7, v135
	v_dot2c_f32_bf16_e32 v152, v8, v136
	v_dot2c_f32_bf16_e32 v153, v9, v137
	v_dot2c_f32_bf16_e32 v154, v10, v138
	v_dot2c_f32_bf16_e32 v155, v11, v139
	v_dot2c_f32_bf16_e32 v152, v12, v140
	v_dot2c_f32_bf16_e32 v153, v13, v141
	v_dot2c_f32_bf16_e32 v154, v14, v142
	v_dot2c_f32_bf16_e32 v155, v15, v143
	s_nop 0
	v_add_f32_e32 v156, v152, v153
	s_nop 0
	v_add_f32_e32 v157, v154, v155
	v_add_f32_e32 v158, v156, v157
	s_nop 1
	v_add_f32_dpp v158, v158, v158 quad_perm:[1,0,3,2] row_mask:0xf bank_mask:0xf
	s_nop 1
	v_add_f32_dpp v158, v158, v158 quad_perm:[2,3,0,1] row_mask:0xf bank_mask:0xf
	s_nop 1
	v_add_f32_dpp v158, v158, v158 row_half_mirror row_mask:0xf bank_mask:0xf
	s_mov_b64 exec, s[14:15]
	ds_add_f32 v170, v158 offset:256
	s_mov_b64 exec, -1
	v_mov_b32_e32 v152, 0
	v_mov_b32_e32 v153, 0
	v_mov_b32_e32 v154, 0
	v_mov_b32_e32 v155, 0
	s_waitcnt vmcnt(32)
	v_cvt_scalef32_pk32_bf16_fp6 v[0:15], v[70:75], 1.0
	v_dot2c_f32_bf16_e32 v152, v0, v128
	v_dot2c_f32_bf16_e32 v153, v1, v129
	v_dot2c_f32_bf16_e32 v154, v2, v130
	v_dot2c_f32_bf16_e32 v155, v3, v131
	v_dot2c_f32_bf16_e32 v152, v4, v132
	v_dot2c_f32_bf16_e32 v153, v5, v133
	v_dot2c_f32_bf16_e32 v154, v6, v134
	v_dot2c_f32_bf16_e32 v155, v7, v135
	v_dot2c_f32_bf16_e32 v152, v8, v136
	v_dot2c_f32_bf16_e32 v153, v9, v137
	v_dot2c_f32_bf16_e32 v154, v10, v138
	v_dot2c_f32_bf16_e32 v155, v11, v139
	v_dot2c_f32_bf16_e32 v152, v12, v140
	v_dot2c_f32_bf16_e32 v153, v13, v141
	v_dot2c_f32_bf16_e32 v154, v14, v142
	v_dot2c_f32_bf16_e32 v155, v15, v143
	s_nop 0
	v_add_f32_e32 v156, v152, v153
	s_nop 0
	v_add_f32_e32 v157, v154, v155
	v_add_f32_e32 v158, v156, v157
	s_nop 1
	v_add_f32_dpp v158, v158, v158 quad_perm:[1,0,3,2] row_mask:0xf bank_mask:0xf
	s_nop 1
	v_add_f32_dpp v158, v158, v158 quad_perm:[2,3,0,1] row_mask:0xf bank_mask:0xf
	s_nop 1
	v_add_f32_dpp v158, v158, v158 row_half_mirror row_mask:0xf bank_mask:0xf
	s_mov_b64 exec, s[14:15]
	ds_add_f32 v170, v158 offset:288
	s_mov_b64 exec, -1
	v_mov_b32_e32 v152, 0
	v_mov_b32_e32 v153, 0
	v_mov_b32_e32 v154, 0
	v_mov_b32_e32 v155, 0
	s_waitcnt vmcnt(30)
	v_cvt_scalef32_pk32_bf16_fp6 v[0:15], v[76:81], 1.0
	v_dot2c_f32_bf16_e32 v152, v0, v128
	v_dot2c_f32_bf16_e32 v153, v1, v129
	v_dot2c_f32_bf16_e32 v154, v2, v130
	v_dot2c_f32_bf16_e32 v155, v3, v131
	v_dot2c_f32_bf16_e32 v152, v4, v132
	v_dot2c_f32_bf16_e32 v153, v5, v133
	v_dot2c_f32_bf16_e32 v154, v6, v134
	v_dot2c_f32_bf16_e32 v155, v7, v135
	v_dot2c_f32_bf16_e32 v152, v8, v136
	v_dot2c_f32_bf16_e32 v153, v9, v137
	v_dot2c_f32_bf16_e32 v154, v10, v138
	v_dot2c_f32_bf16_e32 v155, v11, v139
	v_dot2c_f32_bf16_e32 v152, v12, v140
	v_dot2c_f32_bf16_e32 v153, v13, v141
	v_dot2c_f32_bf16_e32 v154, v14, v142
	v_dot2c_f32_bf16_e32 v155, v15, v143
	s_nop 0
	v_add_f32_e32 v156, v152, v153
	s_nop 0
	v_add_f32_e32 v157, v154, v155
	v_add_f32_e32 v158, v156, v157
	s_nop 1
	v_add_f32_dpp v158, v158, v158 quad_perm:[1,0,3,2] row_mask:0xf bank_mask:0xf
	s_nop 1
	v_add_f32_dpp v158, v158, v158 quad_perm:[2,3,0,1] row_mask:0xf bank_mask:0xf
	s_nop 1
	v_add_f32_dpp v158, v158, v158 row_half_mirror row_mask:0xf bank_mask:0xf
	s_mov_b64 exec, s[14:15]
	ds_add_f32 v170, v158 offset:320
	s_mov_b64 exec, -1
	v_mov_b32_e32 v152, 0
	v_mov_b32_e32 v153, 0
	v_mov_b32_e32 v154, 0
	v_mov_b32_e32 v155, 0
	s_waitcnt vmcnt(28)
	v_cvt_scalef32_pk32_bf16_fp6 v[0:15], v[82:87], 1.0
	v_dot2c_f32_bf16_e32 v152, v0, v128
	v_dot2c_f32_bf16_e32 v153, v1, v129
	v_dot2c_f32_bf16_e32 v154, v2, v130
	v_dot2c_f32_bf16_e32 v155, v3, v131
	v_dot2c_f32_bf16_e32 v152, v4, v132
	v_dot2c_f32_bf16_e32 v153, v5, v133
	v_dot2c_f32_bf16_e32 v154, v6, v134
	v_dot2c_f32_bf16_e32 v155, v7, v135
	v_dot2c_f32_bf16_e32 v152, v8, v136
	v_dot2c_f32_bf16_e32 v153, v9, v137
	v_dot2c_f32_bf16_e32 v154, v10, v138
	v_dot2c_f32_bf16_e32 v155, v11, v139
	v_dot2c_f32_bf16_e32 v152, v12, v140
	v_dot2c_f32_bf16_e32 v153, v13, v141
	v_dot2c_f32_bf16_e32 v154, v14, v142
	v_dot2c_f32_bf16_e32 v155, v15, v143
	s_nop 0
	v_add_f32_e32 v156, v152, v153
	s_nop 0
	v_add_f32_e32 v157, v154, v155
	v_add_f32_e32 v158, v156, v157
	s_nop 1
	v_add_f32_dpp v158, v158, v158 quad_perm:[1,0,3,2] row_mask:0xf bank_mask:0xf
	s_nop 1
	v_add_f32_dpp v158, v158, v158 quad_perm:[2,3,0,1] row_mask:0xf bank_mask:0xf
	s_nop 1
	v_add_f32_dpp v158, v158, v158 row_half_mirror row_mask:0xf bank_mask:0xf
	s_mov_b64 exec, s[14:15]
	ds_add_f32 v170, v158 offset:352
	s_mov_b64 exec, -1
	v_mov_b32_e32 v152, 0
	v_mov_b32_e32 v153, 0
	v_mov_b32_e32 v154, 0
	v_mov_b32_e32 v155, 0
	s_waitcnt vmcnt(26)
	v_cvt_scalef32_pk32_bf16_fp6 v[0:15], v[88:93], 1.0
	v_dot2c_f32_bf16_e32 v152, v0, v128
	v_dot2c_f32_bf16_e32 v153, v1, v129
	v_dot2c_f32_bf16_e32 v154, v2, v130
	v_dot2c_f32_bf16_e32 v155, v3, v131
	v_dot2c_f32_bf16_e32 v152, v4, v132
	v_dot2c_f32_bf16_e32 v153, v5, v133
	v_dot2c_f32_bf16_e32 v154, v6, v134
	v_dot2c_f32_bf16_e32 v155, v7, v135
	v_dot2c_f32_bf16_e32 v152, v8, v136
	v_dot2c_f32_bf16_e32 v153, v9, v137
	v_dot2c_f32_bf16_e32 v154, v10, v138
	v_dot2c_f32_bf16_e32 v155, v11, v139
	v_dot2c_f32_bf16_e32 v152, v12, v140
	v_dot2c_f32_bf16_e32 v153, v13, v141
	v_dot2c_f32_bf16_e32 v154, v14, v142
	v_dot2c_f32_bf16_e32 v155, v15, v143
	s_nop 0
	v_add_f32_e32 v156, v152, v153
	s_nop 0
	v_add_f32_e32 v157, v154, v155
	v_add_f32_e32 v158, v156, v157
	s_nop 1
	v_add_f32_dpp v158, v158, v158 quad_perm:[1,0,3,2] row_mask:0xf bank_mask:0xf
	s_nop 1
	v_add_f32_dpp v158, v158, v158 quad_perm:[2,3,0,1] row_mask:0xf bank_mask:0xf
	s_nop 1
	v_add_f32_dpp v158, v158, v158 row_half_mirror row_mask:0xf bank_mask:0xf
	s_mov_b64 exec, s[14:15]
	ds_add_f32 v170, v158 offset:384
	s_mov_b64 exec, -1
	v_mov_b32_e32 v152, 0
	v_mov_b32_e32 v153, 0
	v_mov_b32_e32 v154, 0
	v_mov_b32_e32 v155, 0
	s_waitcnt vmcnt(24)
	v_cvt_scalef32_pk32_bf16_fp6 v[0:15], v[94:99], 1.0
	v_dot2c_f32_bf16_e32 v152, v0, v128
	v_dot2c_f32_bf16_e32 v153, v1, v129
	v_dot2c_f32_bf16_e32 v154, v2, v130
	v_dot2c_f32_bf16_e32 v155, v3, v131
	v_dot2c_f32_bf16_e32 v152, v4, v132
	v_dot2c_f32_bf16_e32 v153, v5, v133
	v_dot2c_f32_bf16_e32 v154, v6, v134
	v_dot2c_f32_bf16_e32 v155, v7, v135
	v_dot2c_f32_bf16_e32 v152, v8, v136
	v_dot2c_f32_bf16_e32 v153, v9, v137
	v_dot2c_f32_bf16_e32 v154, v10, v138
	v_dot2c_f32_bf16_e32 v155, v11, v139
	v_dot2c_f32_bf16_e32 v152, v12, v140
	v_dot2c_f32_bf16_e32 v153, v13, v141
	v_dot2c_f32_bf16_e32 v154, v14, v142
	v_dot2c_f32_bf16_e32 v155, v15, v143
	s_nop 0
	v_add_f32_e32 v156, v152, v153
	s_nop 0
	v_add_f32_e32 v157, v154, v155
	v_add_f32_e32 v158, v156, v157
	s_nop 1
	v_add_f32_dpp v158, v158, v158 quad_perm:[1,0,3,2] row_mask:0xf bank_mask:0xf
	s_nop 1
	v_add_f32_dpp v158, v158, v158 quad_perm:[2,3,0,1] row_mask:0xf bank_mask:0xf
	s_nop 1
	v_add_f32_dpp v158, v158, v158 row_half_mirror row_mask:0xf bank_mask:0xf
	s_mov_b64 exec, s[14:15]
	ds_add_f32 v170, v158 offset:416
	s_mov_b64 exec, -1
	v_mov_b32_e32 v152, 0
	v_mov_b32_e32 v153, 0
	v_mov_b32_e32 v154, 0
	v_mov_b32_e32 v155, 0
	s_waitcnt vmcnt(22)
	v_cvt_scalef32_pk32_bf16_fp6 v[0:15], v[100:105], 1.0
	v_dot2c_f32_bf16_e32 v152, v0, v128
	v_dot2c_f32_bf16_e32 v153, v1, v129
	v_dot2c_f32_bf16_e32 v154, v2, v130
	v_dot2c_f32_bf16_e32 v155, v3, v131
	v_dot2c_f32_bf16_e32 v152, v4, v132
	v_dot2c_f32_bf16_e32 v153, v5, v133
	v_dot2c_f32_bf16_e32 v154, v6, v134
	v_dot2c_f32_bf16_e32 v155, v7, v135
	v_dot2c_f32_bf16_e32 v152, v8, v136
	v_dot2c_f32_bf16_e32 v153, v9, v137
	v_dot2c_f32_bf16_e32 v154, v10, v138
	v_dot2c_f32_bf16_e32 v155, v11, v139
	v_dot2c_f32_bf16_e32 v152, v12, v140
	v_dot2c_f32_bf16_e32 v153, v13, v141
	v_dot2c_f32_bf16_e32 v154, v14, v142
	v_dot2c_f32_bf16_e32 v155, v15, v143
	s_nop 0
	v_add_f32_e32 v156, v152, v153
	s_nop 0
	v_add_f32_e32 v157, v154, v155
	v_add_f32_e32 v158, v156, v157
	s_nop 1
	v_add_f32_dpp v158, v158, v158 quad_perm:[1,0,3,2] row_mask:0xf bank_mask:0xf
	s_nop 1
	v_add_f32_dpp v158, v158, v158 quad_perm:[2,3,0,1] row_mask:0xf bank_mask:0xf
	s_nop 1
	v_add_f32_dpp v158, v158, v158 row_half_mirror row_mask:0xf bank_mask:0xf
	s_mov_b64 exec, s[14:15]
	ds_add_f32 v170, v158 offset:448
	s_mov_b64 exec, -1
	v_mov_b32_e32 v152, 0
	v_mov_b32_e32 v153, 0
	v_mov_b32_e32 v154, 0
	v_mov_b32_e32 v155, 0
	s_waitcnt vmcnt(20)
	v_cvt_scalef32_pk32_bf16_fp6 v[0:15], v[106:111], 1.0
	v_dot2c_f32_bf16_e32 v152, v0, v128
	v_dot2c_f32_bf16_e32 v153, v1, v129
	v_dot2c_f32_bf16_e32 v154, v2, v130
	v_dot2c_f32_bf16_e32 v155, v3, v131
	v_dot2c_f32_bf16_e32 v152, v4, v132
	v_dot2c_f32_bf16_e32 v153, v5, v133
	v_dot2c_f32_bf16_e32 v154, v6, v134
	v_dot2c_f32_bf16_e32 v155, v7, v135
	v_dot2c_f32_bf16_e32 v152, v8, v136
	v_dot2c_f32_bf16_e32 v153, v9, v137
	v_dot2c_f32_bf16_e32 v154, v10, v138
	v_dot2c_f32_bf16_e32 v155, v11, v139
	v_dot2c_f32_bf16_e32 v152, v12, v140
	v_dot2c_f32_bf16_e32 v153, v13, v141
	v_dot2c_f32_bf16_e32 v154, v14, v142
	v_dot2c_f32_bf16_e32 v155, v15, v143
	s_nop 0
	v_add_f32_e32 v156, v152, v153
	s_nop 0
	v_add_f32_e32 v157, v154, v155
	v_add_f32_e32 v158, v156, v157
	s_nop 1
	v_add_f32_dpp v158, v158, v158 quad_perm:[1,0,3,2] row_mask:0xf bank_mask:0xf
	s_nop 1
	v_add_f32_dpp v158, v158, v158 quad_perm:[2,3,0,1] row_mask:0xf bank_mask:0xf
	s_nop 1
	v_add_f32_dpp v158, v158, v158 row_half_mirror row_mask:0xf bank_mask:0xf
	s_mov_b64 exec, s[14:15]
	ds_add_f32 v170, v158 offset:480
	s_mov_b64 exec, -1
	s_cmp_lg_u32 s16, 0
	s_cbranch_scc1 .Lgu0_loop
	s_waitcnt vmcnt(0) lgkmcnt(0)
	s_add_u32 s4, s26, 0x1400000
	s_addc_u32 s5, s27, 0
	s_add_u32 s8, s26, 0x1410000
	s_addc_u32 s9, s27, 0
	s_lshl_b32 s17, s69, 9
	s_add_u32 s10, s26, 0xe800000
	s_addc_u32 s11, s27, 0
	s_add_u32 s10, s10, s17
	s_addc_u32 s11, s11, 0
	s_add_u32 s12, s26, 0xf800000
	s_addc_u32 s13, s27, 0
	s_add_u32 s12, s12, s17
	s_addc_u32 s13, s13, 0
	s_lshl_b32 s18, s92, 11
	s_mov_b32 s16, 0x378e98ab
	s_mov_b32 s19, 0x3b7cd369
	s_mov_b32 s50, 0xbcc618b2
	s_mov_b32 s51, 0x3dda74e4
	s_mov_b32 s64, 0x3f228afd
	s_mov_b32 s65, 0x3e03c728
	s_mov_b32 s98, 0xbfb8aa3b
	s_mov_b32 s70, 0x42ce8ed0
	s_mov_b32 s71, 0xc2b17218
	s_mov_b32 s14, 0x7fffffff
	v_mov_b32_e32 v176, 0x3ba10414
	v_mov_b32_e32 v177, 0xb9c68948
	v_mov_b32_e32 v178, 0x7f800000
	ds_read2st64_b32 v[16:17], v174 offset0:0 offset1:1
	ds_read2st64_b32 v[80:81], v175 offset0:0 offset1:1
	ds_read2st64_b32 v[18:19], v174 offset0:2 offset1:3
	ds_read2st64_b32 v[82:83], v175 offset0:2 offset1:3
	ds_read2st64_b32 v[20:21], v174 offset0:4 offset1:5
	ds_read2st64_b32 v[84:85], v175 offset0:4 offset1:5
	ds_read2st64_b32 v[22:23], v174 offset0:6 offset1:7
	ds_read2st64_b32 v[86:87], v175 offset0:6 offset1:7
	ds_read2st64_b32 v[24:25], v174 offset0:8 offset1:9
	ds_read2st64_b32 v[88:89], v175 offset0:8 offset1:9
	ds_read2st64_b32 v[26:27], v174 offset0:10 offset1:11
	ds_read2st64_b32 v[90:91], v175 offset0:10 offset1:11
	ds_read2st64_b32 v[28:29], v174 offset0:12 offset1:13
	ds_read2st64_b32 v[92:93], v175 offset0:12 offset1:13
	ds_read2st64_b32 v[30:31], v174 offset0:14 offset1:15
	ds_read2st64_b32 v[94:95], v175 offset0:14 offset1:15
	s_waitcnt lgkmcnt(0)
	v_lshlrev_b32_e32 v16, 2, v16
	v_lshlrev_b32_e32 v17, 2, v17
	v_lshlrev_b32_e32 v18, 2, v18
	v_lshlrev_b32_e32 v19, 2, v19
	v_lshlrev_b32_e32 v20, 2, v20
	v_lshlrev_b32_e32 v21, 2, v21
	v_lshlrev_b32_e32 v22, 2, v22
	v_lshlrev_b32_e32 v23, 2, v23
	v_lshlrev_b32_e32 v24, 2, v24
	v_lshlrev_b32_e32 v25, 2, v25
	v_lshlrev_b32_e32 v26, 2, v26
	v_lshlrev_b32_e32 v27, 2, v27
	v_lshlrev_b32_e32 v28, 2, v28
	v_lshlrev_b32_e32 v29, 2, v29
	v_lshlrev_b32_e32 v30, 2, v30
	v_lshlrev_b32_e32 v31, 2, v31
	global_load_dword v32, v160, s[10:11]
	global_load_dword v33, v160, s[10:11] offset:256
	global_load_dword v34, v16, s[4:5]
	global_load_dword v35, v17, s[4:5]
	global_load_dword v36, v16, s[8:9]
	global_load_dword v37, v17, s[8:9]
	s_add_u32 s10, s10, s18
	s_addc_u32 s11, s11, 0
	global_load_dword v38, v160, s[10:11]
	global_load_dword v39, v160, s[10:11] offset:256
	global_load_dword v40, v18, s[4:5]
	global_load_dword v41, v19, s[4:5]
	global_load_dword v42, v18, s[8:9]
	global_load_dword v43, v19, s[8:9]
	s_add_u32 s10, s10, s18
	s_addc_u32 s11, s11, 0
	global_load_dword v44, v160, s[10:11]
	global_load_dword v45, v160, s[10:11] offset:256
	global_load_dword v46, v20, s[4:5]
	global_load_dword v47, v21, s[4:5]
	global_load_dword v48, v20, s[8:9]
	global_load_dword v49, v21, s[8:9]
	s_add_u32 s10, s10, s18
	s_addc_u32 s11, s11, 0
	global_load_dword v50, v160, s[10:11]
	global_load_dword v51, v160, s[10:11] offset:256
	global_load_dword v52, v22, s[4:5]
	global_load_dword v53, v23, s[4:5]
	global_load_dword v54, v22, s[8:9]
	global_load_dword v55, v23, s[8:9]
	s_add_u32 s10, s10, s18
	s_addc_u32 s11, s11, 0
	global_load_dword v56, v160, s[10:11]
	global_load_dword v57, v160, s[10:11] offset:256
	global_load_dword v58, v24, s[4:5]
	global_load_dword v59, v25, s[4:5]
	global_load_dword v60, v24, s[8:9]
	global_load_dword v61, v25, s[8:9]
	s_add_u32 s10, s10, s18
	s_addc_u32 s11, s11, 0
	global_load_dword v62, v160, s[10:11]
	global_load_dword v63, v160, s[10:11] offset:256
	global_load_dword v64, v26, s[4:5]
	global_load_dword v65, v27, s[4:5]
	global_load_dword v66, v26, s[8:9]
	global_load_dword v67, v27, s[8:9]
	s_add_u32 s10, s10, s18
	s_addc_u32 s11, s11, 0
	global_load_dword v68, v160, s[10:11]
	global_load_dword v69, v160, s[10:11] offset:256
	global_load_dword v70, v28, s[4:5]
	global_load_dword v71, v29, s[4:5]
	global_load_dword v72, v28, s[8:9]
	global_load_dword v73, v29, s[8:9]
	s_add_u32 s10, s10, s18
	s_addc_u32 s11, s11, 0
	global_load_dword v74, v160, s[10:11]
	global_load_dword v75, v160, s[10:11] offset:256
	global_load_dword v76, v30, s[4:5]
	global_load_dword v77, v31, s[4:5]
	global_load_dword v78, v30, s[8:9]
	global_load_dword v79, v31, s[8:9]
	s_add_u32 s10, s10, s18
	s_addc_u32 s11, s11, 0
	s_waitcnt vmcnt(0)
	v_mul_f32_e32 v80, v34, v80
	v_mul_f32_e32 v180, 0x3f3504f3, v80
	v_fma_f32 v182, |v180|, s16, v177
	v_fma_f32 v182, |v180|, v182, s19
	v_fma_f32 v182, |v180|, v182, s50
	v_fma_f32 v182, |v180|, v182, s51
	v_fma_f32 v182, |v180|, v182, s64
	v_fma_f32 v182, |v180|, v182, s65
	v_fma_f32 v182, |v180|, v182, |v180|
	v_mul_f32_e32 v184, 0xbfb8aa3b, v182
	v_fma_f32 v185, v182, s98, -v184
	v_rndne_f32_e32 v186, v184
	v_fmac_f32_e32 v185, 0xb2a5705f, v182
	v_sub_f32_e32 v184, v184, v186
	v_add_f32_e32 v184, v184, v185
	v_cvt_i32_f32_e32 v185, v186
	v_exp_f32_e32 v184, v184
	v_cmp_nlt_f32_e32 vcc, s70, v182
	v_ldexp_f32 v184, v184, v185
	s_nop 0
	v_cndmask_b32_e32 v184, 0, v184, vcc
	v_cmp_ngt_f32_e32 vcc, s71, v182
	s_nop 1
	v_cndmask_b32_e32 v184, v178, v184, vcc
	v_sub_f32_e32 v184, 1.0, v184
	v_mul_f32_e32 v183, v180, v180
	v_fmamk_f32 v185, v183, 0xba1345e1, v176
	v_fmaak_f32 v185, v183, v185, 0xbcdac9b8
	v_fmaak_f32 v185, v183, v185, 0x3de703be
	v_fmaak_f32 v185, v183, v185, 0xbec09330
	v_fmaak_f32 v183, v183, v185, 0x3e0375d0
	v_fma_f32 v183, |v180|, v183, |v180|
	v_cmp_nlt_f32_e64 vcc, |v180|, 1.0
	s_nop 1
	v_cndmask_b32_e32 v184, v183, v184, vcc
	v_bfi_b32 v184, s14, v184, v180
	v_add_f32_e32 v184, 1.0, v184
	v_mul_f32_e32 v80, 0.5, v80
	v_mul_f32_e32 v32, v32, v36
	v_mul_f32_e32 v80, v80, v184
	v_mul_f32_e32 v80, v32, v80
	v_mul_f32_e32 v81, v35, v81
	v_mul_f32_e32 v180, 0x3f3504f3, v81
	v_fma_f32 v182, |v180|, s16, v177
	v_fma_f32 v182, |v180|, v182, s19
	v_fma_f32 v182, |v180|, v182, s50
	v_fma_f32 v182, |v180|, v182, s51
	v_fma_f32 v182, |v180|, v182, s64
	v_fma_f32 v182, |v180|, v182, s65
	v_fma_f32 v182, |v180|, v182, |v180|
	v_mul_f32_e32 v184, 0xbfb8aa3b, v182
	v_fma_f32 v185, v182, s98, -v184
	v_rndne_f32_e32 v186, v184
	v_fmac_f32_e32 v185, 0xb2a5705f, v182
	v_sub_f32_e32 v184, v184, v186
	v_add_f32_e32 v184, v184, v185
	v_cvt_i32_f32_e32 v185, v186
	v_exp_f32_e32 v184, v184
	v_cmp_nlt_f32_e32 vcc, s70, v182
	v_ldexp_f32 v184, v184, v185
	s_nop 0
	v_cndmask_b32_e32 v184, 0, v184, vcc
	v_cmp_ngt_f32_e32 vcc, s71, v182
	s_nop 1
	v_cndmask_b32_e32 v184, v178, v184, vcc
	v_sub_f32_e32 v184, 1.0, v184
	v_mul_f32_e32 v183, v180, v180
	v_fmamk_f32 v185, v183, 0xba1345e1, v176
	v_fmaak_f32 v185, v183, v185, 0xbcdac9b8
	v_fmaak_f32 v185, v183, v185, 0x3de703be
	v_fmaak_f32 v185, v183, v185, 0xbec09330
	v_fmaak_f32 v183, v183, v185, 0x3e0375d0
	v_fma_f32 v183, |v180|, v183, |v180|
	v_cmp_nlt_f32_e64 vcc, |v180|, 1.0
	s_nop 1
	v_cndmask_b32_e32 v184, v183, v184, vcc
	v_bfi_b32 v184, s14, v184, v180
	v_add_f32_e32 v184, 1.0, v184
	v_mul_f32_e32 v81, 0.5, v81
	v_mul_f32_e32 v33, v33, v37
	v_mul_f32_e32 v81, v81, v184
	v_mul_f32_e32 v81, v33, v81
	global_store_dword v160, v80, s[12:13]
	global_store_dword v160, v81, s[12:13] offset:256
	s_add_u32 s12, s12, s18
	s_addc_u32 s13, s13, 0
	v_mul_f32_e32 v82, v40, v82
	v_mul_f32_e32 v180, 0x3f3504f3, v82
	v_fma_f32 v182, |v180|, s16, v177
	v_fma_f32 v182, |v180|, v182, s19
	v_fma_f32 v182, |v180|, v182, s50
	v_fma_f32 v182, |v180|, v182, s51
	v_fma_f32 v182, |v180|, v182, s64
	v_fma_f32 v182, |v180|, v182, s65
	v_fma_f32 v182, |v180|, v182, |v180|
	v_mul_f32_e32 v184, 0xbfb8aa3b, v182
	v_fma_f32 v185, v182, s98, -v184
	v_rndne_f32_e32 v186, v184
	v_fmac_f32_e32 v185, 0xb2a5705f, v182
	v_sub_f32_e32 v184, v184, v186
	v_add_f32_e32 v184, v184, v185
	v_cvt_i32_f32_e32 v185, v186
	v_exp_f32_e32 v184, v184
	v_cmp_nlt_f32_e32 vcc, s70, v182
	v_ldexp_f32 v184, v184, v185
	s_nop 0
	v_cndmask_b32_e32 v184, 0, v184, vcc
	v_cmp_ngt_f32_e32 vcc, s71, v182
	s_nop 1
	v_cndmask_b32_e32 v184, v178, v184, vcc
	v_sub_f32_e32 v184, 1.0, v184
	v_mul_f32_e32 v183, v180, v180
	v_fmamk_f32 v185, v183, 0xba1345e1, v176
	v_fmaak_f32 v185, v183, v185, 0xbcdac9b8
	v_fmaak_f32 v185, v183, v185, 0x3de703be
	v_fmaak_f32 v185, v183, v185, 0xbec09330
	v_fmaak_f32 v183, v183, v185, 0x3e0375d0
	v_fma_f32 v183, |v180|, v183, |v180|
	v_cmp_nlt_f32_e64 vcc, |v180|, 1.0
	s_nop 1
	v_cndmask_b32_e32 v184, v183, v184, vcc
	v_bfi_b32 v184, s14, v184, v180
	v_add_f32_e32 v184, 1.0, v184
	v_mul_f32_e32 v82, 0.5, v82
	v_mul_f32_e32 v38, v38, v42
	v_mul_f32_e32 v82, v82, v184
	v_mul_f32_e32 v82, v38, v82
	v_mul_f32_e32 v83, v41, v83
	v_mul_f32_e32 v180, 0x3f3504f3, v83
	v_fma_f32 v182, |v180|, s16, v177
	v_fma_f32 v182, |v180|, v182, s19
	v_fma_f32 v182, |v180|, v182, s50
	v_fma_f32 v182, |v180|, v182, s51
	v_fma_f32 v182, |v180|, v182, s64
	v_fma_f32 v182, |v180|, v182, s65
	v_fma_f32 v182, |v180|, v182, |v180|
	v_mul_f32_e32 v184, 0xbfb8aa3b, v182
	v_fma_f32 v185, v182, s98, -v184
	v_rndne_f32_e32 v186, v184
	v_fmac_f32_e32 v185, 0xb2a5705f, v182
	v_sub_f32_e32 v184, v184, v186
	v_add_f32_e32 v184, v184, v185
	v_cvt_i32_f32_e32 v185, v186
	v_exp_f32_e32 v184, v184
	v_cmp_nlt_f32_e32 vcc, s70, v182
	v_ldexp_f32 v184, v184, v185
	s_nop 0
	v_cndmask_b32_e32 v184, 0, v184, vcc
	v_cmp_ngt_f32_e32 vcc, s71, v182
	s_nop 1
	v_cndmask_b32_e32 v184, v178, v184, vcc
	v_sub_f32_e32 v184, 1.0, v184
	v_mul_f32_e32 v183, v180, v180
	v_fmamk_f32 v185, v183, 0xba1345e1, v176
	v_fmaak_f32 v185, v183, v185, 0xbcdac9b8
	v_fmaak_f32 v185, v183, v185, 0x3de703be
	v_fmaak_f32 v185, v183, v185, 0xbec09330
	v_fmaak_f32 v183, v183, v185, 0x3e0375d0
	v_fma_f32 v183, |v180|, v183, |v180|
	v_cmp_nlt_f32_e64 vcc, |v180|, 1.0
	s_nop 1
	v_cndmask_b32_e32 v184, v183, v184, vcc
	v_bfi_b32 v184, s14, v184, v180
	v_add_f32_e32 v184, 1.0, v184
	v_mul_f32_e32 v83, 0.5, v83
	v_mul_f32_e32 v39, v39, v43
	v_mul_f32_e32 v83, v83, v184
	v_mul_f32_e32 v83, v39, v83
	global_store_dword v160, v82, s[12:13]
	global_store_dword v160, v83, s[12:13] offset:256
	s_add_u32 s12, s12, s18
	s_addc_u32 s13, s13, 0
	v_mul_f32_e32 v84, v46, v84
	v_mul_f32_e32 v180, 0x3f3504f3, v84
	v_fma_f32 v182, |v180|, s16, v177
	v_fma_f32 v182, |v180|, v182, s19
	v_fma_f32 v182, |v180|, v182, s50
	v_fma_f32 v182, |v180|, v182, s51
	v_fma_f32 v182, |v180|, v182, s64
	v_fma_f32 v182, |v180|, v182, s65
	v_fma_f32 v182, |v180|, v182, |v180|
	v_mul_f32_e32 v184, 0xbfb8aa3b, v182
	v_fma_f32 v185, v182, s98, -v184
	v_rndne_f32_e32 v186, v184
	v_fmac_f32_e32 v185, 0xb2a5705f, v182
	v_sub_f32_e32 v184, v184, v186
	v_add_f32_e32 v184, v184, v185
	v_cvt_i32_f32_e32 v185, v186
	v_exp_f32_e32 v184, v184
	v_cmp_nlt_f32_e32 vcc, s70, v182
	v_ldexp_f32 v184, v184, v185
	s_nop 0
	v_cndmask_b32_e32 v184, 0, v184, vcc
	v_cmp_ngt_f32_e32 vcc, s71, v182
	s_nop 1
	v_cndmask_b32_e32 v184, v178, v184, vcc
	v_sub_f32_e32 v184, 1.0, v184
	v_mul_f32_e32 v183, v180, v180
	v_fmamk_f32 v185, v183, 0xba1345e1, v176
	v_fmaak_f32 v185, v183, v185, 0xbcdac9b8
	v_fmaak_f32 v185, v183, v185, 0x3de703be
	v_fmaak_f32 v185, v183, v185, 0xbec09330
	v_fmaak_f32 v183, v183, v185, 0x3e0375d0
	v_fma_f32 v183, |v180|, v183, |v180|
	v_cmp_nlt_f32_e64 vcc, |v180|, 1.0
	s_nop 1
	v_cndmask_b32_e32 v184, v183, v184, vcc
	v_bfi_b32 v184, s14, v184, v180
	v_add_f32_e32 v184, 1.0, v184
	v_mul_f32_e32 v84, 0.5, v84
	v_mul_f32_e32 v44, v44, v48
	v_mul_f32_e32 v84, v84, v184
	v_mul_f32_e32 v84, v44, v84
	v_mul_f32_e32 v85, v47, v85
	v_mul_f32_e32 v180, 0x3f3504f3, v85
	v_fma_f32 v182, |v180|, s16, v177
	v_fma_f32 v182, |v180|, v182, s19
	v_fma_f32 v182, |v180|, v182, s50
	v_fma_f32 v182, |v180|, v182, s51
	v_fma_f32 v182, |v180|, v182, s64
	v_fma_f32 v182, |v180|, v182, s65
	v_fma_f32 v182, |v180|, v182, |v180|
	v_mul_f32_e32 v184, 0xbfb8aa3b, v182
	v_fma_f32 v185, v182, s98, -v184
	v_rndne_f32_e32 v186, v184
	v_fmac_f32_e32 v185, 0xb2a5705f, v182
	v_sub_f32_e32 v184, v184, v186
	v_add_f32_e32 v184, v184, v185
	v_cvt_i32_f32_e32 v185, v186
	v_exp_f32_e32 v184, v184
	v_cmp_nlt_f32_e32 vcc, s70, v182
	v_ldexp_f32 v184, v184, v185
	s_nop 0
	v_cndmask_b32_e32 v184, 0, v184, vcc
	v_cmp_ngt_f32_e32 vcc, s71, v182
	s_nop 1
	v_cndmask_b32_e32 v184, v178, v184, vcc
	v_sub_f32_e32 v184, 1.0, v184
	v_mul_f32_e32 v183, v180, v180
	v_fmamk_f32 v185, v183, 0xba1345e1, v176
	v_fmaak_f32 v185, v183, v185, 0xbcdac9b8
	v_fmaak_f32 v185, v183, v185, 0x3de703be
	v_fmaak_f32 v185, v183, v185, 0xbec09330
	v_fmaak_f32 v183, v183, v185, 0x3e0375d0
	v_fma_f32 v183, |v180|, v183, |v180|
	v_cmp_nlt_f32_e64 vcc, |v180|, 1.0
	s_nop 1
	v_cndmask_b32_e32 v184, v183, v184, vcc
	v_bfi_b32 v184, s14, v184, v180
	v_add_f32_e32 v184, 1.0, v184
	v_mul_f32_e32 v85, 0.5, v85
	v_mul_f32_e32 v45, v45, v49
	v_mul_f32_e32 v85, v85, v184
	v_mul_f32_e32 v85, v45, v85
	global_store_dword v160, v84, s[12:13]
	global_store_dword v160, v85, s[12:13] offset:256
	s_add_u32 s12, s12, s18
	s_addc_u32 s13, s13, 0
	v_mul_f32_e32 v86, v52, v86
	v_mul_f32_e32 v180, 0x3f3504f3, v86
	v_fma_f32 v182, |v180|, s16, v177
	v_fma_f32 v182, |v180|, v182, s19
	v_fma_f32 v182, |v180|, v182, s50
	v_fma_f32 v182, |v180|, v182, s51
	v_fma_f32 v182, |v180|, v182, s64
	v_fma_f32 v182, |v180|, v182, s65
	v_fma_f32 v182, |v180|, v182, |v180|
	v_mul_f32_e32 v184, 0xbfb8aa3b, v182
	v_fma_f32 v185, v182, s98, -v184
	v_rndne_f32_e32 v186, v184
	v_fmac_f32_e32 v185, 0xb2a5705f, v182
	v_sub_f32_e32 v184, v184, v186
	v_add_f32_e32 v184, v184, v185
	v_cvt_i32_f32_e32 v185, v186
	v_exp_f32_e32 v184, v184
	v_cmp_nlt_f32_e32 vcc, s70, v182
	v_ldexp_f32 v184, v184, v185
	s_nop 0
	v_cndmask_b32_e32 v184, 0, v184, vcc
	v_cmp_ngt_f32_e32 vcc, s71, v182
	s_nop 1
	v_cndmask_b32_e32 v184, v178, v184, vcc
	v_sub_f32_e32 v184, 1.0, v184
	v_mul_f32_e32 v183, v180, v180
	v_fmamk_f32 v185, v183, 0xba1345e1, v176
	v_fmaak_f32 v185, v183, v185, 0xbcdac9b8
	v_fmaak_f32 v185, v183, v185, 0x3de703be
	v_fmaak_f32 v185, v183, v185, 0xbec09330
	v_fmaak_f32 v183, v183, v185, 0x3e0375d0
	v_fma_f32 v183, |v180|, v183, |v180|
	v_cmp_nlt_f32_e64 vcc, |v180|, 1.0
	s_nop 1
	v_cndmask_b32_e32 v184, v183, v184, vcc
	v_bfi_b32 v184, s14, v184, v180
	v_add_f32_e32 v184, 1.0, v184
	v_mul_f32_e32 v86, 0.5, v86
	v_mul_f32_e32 v50, v50, v54
	v_mul_f32_e32 v86, v86, v184
	v_mul_f32_e32 v86, v50, v86
	v_mul_f32_e32 v87, v53, v87
	v_mul_f32_e32 v180, 0x3f3504f3, v87
	v_fma_f32 v182, |v180|, s16, v177
	v_fma_f32 v182, |v180|, v182, s19
	v_fma_f32 v182, |v180|, v182, s50
	v_fma_f32 v182, |v180|, v182, s51
	v_fma_f32 v182, |v180|, v182, s64
	v_fma_f32 v182, |v180|, v182, s65
	v_fma_f32 v182, |v180|, v182, |v180|
	v_mul_f32_e32 v184, 0xbfb8aa3b, v182
	v_fma_f32 v185, v182, s98, -v184
	v_rndne_f32_e32 v186, v184
	v_fmac_f32_e32 v185, 0xb2a5705f, v182
	v_sub_f32_e32 v184, v184, v186
	v_add_f32_e32 v184, v184, v185
	v_cvt_i32_f32_e32 v185, v186
	v_exp_f32_e32 v184, v184
	v_cmp_nlt_f32_e32 vcc, s70, v182
	v_ldexp_f32 v184, v184, v185
	s_nop 0
	v_cndmask_b32_e32 v184, 0, v184, vcc
	v_cmp_ngt_f32_e32 vcc, s71, v182
	s_nop 1
	v_cndmask_b32_e32 v184, v178, v184, vcc
	v_sub_f32_e32 v184, 1.0, v184
	v_mul_f32_e32 v183, v180, v180
	v_fmamk_f32 v185, v183, 0xba1345e1, v176
	v_fmaak_f32 v185, v183, v185, 0xbcdac9b8
	v_fmaak_f32 v185, v183, v185, 0x3de703be
	v_fmaak_f32 v185, v183, v185, 0xbec09330
	v_fmaak_f32 v183, v183, v185, 0x3e0375d0
	v_fma_f32 v183, |v180|, v183, |v180|
	v_cmp_nlt_f32_e64 vcc, |v180|, 1.0
	s_nop 1
	v_cndmask_b32_e32 v184, v183, v184, vcc
	v_bfi_b32 v184, s14, v184, v180
	v_add_f32_e32 v184, 1.0, v184
	v_mul_f32_e32 v87, 0.5, v87
	v_mul_f32_e32 v51, v51, v55
	v_mul_f32_e32 v87, v87, v184
	v_mul_f32_e32 v87, v51, v87
	global_store_dword v160, v86, s[12:13]
	global_store_dword v160, v87, s[12:13] offset:256
	s_add_u32 s12, s12, s18
	s_addc_u32 s13, s13, 0
	v_mul_f32_e32 v88, v58, v88
	v_mul_f32_e32 v180, 0x3f3504f3, v88
	v_fma_f32 v182, |v180|, s16, v177
	v_fma_f32 v182, |v180|, v182, s19
	v_fma_f32 v182, |v180|, v182, s50
	v_fma_f32 v182, |v180|, v182, s51
	v_fma_f32 v182, |v180|, v182, s64
	v_fma_f32 v182, |v180|, v182, s65
	v_fma_f32 v182, |v180|, v182, |v180|
	v_mul_f32_e32 v184, 0xbfb8aa3b, v182
	v_fma_f32 v185, v182, s98, -v184
	v_rndne_f32_e32 v186, v184
	v_fmac_f32_e32 v185, 0xb2a5705f, v182
	v_sub_f32_e32 v184, v184, v186
	v_add_f32_e32 v184, v184, v185
	v_cvt_i32_f32_e32 v185, v186
	v_exp_f32_e32 v184, v184
	v_cmp_nlt_f32_e32 vcc, s70, v182
	v_ldexp_f32 v184, v184, v185
	s_nop 0
	v_cndmask_b32_e32 v184, 0, v184, vcc
	v_cmp_ngt_f32_e32 vcc, s71, v182
	s_nop 1
	v_cndmask_b32_e32 v184, v178, v184, vcc
	v_sub_f32_e32 v184, 1.0, v184
	v_mul_f32_e32 v183, v180, v180
	v_fmamk_f32 v185, v183, 0xba1345e1, v176
	v_fmaak_f32 v185, v183, v185, 0xbcdac9b8
	v_fmaak_f32 v185, v183, v185, 0x3de703be
	v_fmaak_f32 v185, v183, v185, 0xbec09330
	v_fmaak_f32 v183, v183, v185, 0x3e0375d0
	v_fma_f32 v183, |v180|, v183, |v180|
	v_cmp_nlt_f32_e64 vcc, |v180|, 1.0
	s_nop 1
	v_cndmask_b32_e32 v184, v183, v184, vcc
	v_bfi_b32 v184, s14, v184, v180
	v_add_f32_e32 v184, 1.0, v184
	v_mul_f32_e32 v88, 0.5, v88
	v_mul_f32_e32 v56, v56, v60
	v_mul_f32_e32 v88, v88, v184
	v_mul_f32_e32 v88, v56, v88
	v_mul_f32_e32 v89, v59, v89
	v_mul_f32_e32 v180, 0x3f3504f3, v89
	v_fma_f32 v182, |v180|, s16, v177
	v_fma_f32 v182, |v180|, v182, s19
	v_fma_f32 v182, |v180|, v182, s50
	v_fma_f32 v182, |v180|, v182, s51
	v_fma_f32 v182, |v180|, v182, s64
	v_fma_f32 v182, |v180|, v182, s65
	v_fma_f32 v182, |v180|, v182, |v180|
	v_mul_f32_e32 v184, 0xbfb8aa3b, v182
	v_fma_f32 v185, v182, s98, -v184
	v_rndne_f32_e32 v186, v184
	v_fmac_f32_e32 v185, 0xb2a5705f, v182
	v_sub_f32_e32 v184, v184, v186
	v_add_f32_e32 v184, v184, v185
	v_cvt_i32_f32_e32 v185, v186
	v_exp_f32_e32 v184, v184
	v_cmp_nlt_f32_e32 vcc, s70, v182
	v_ldexp_f32 v184, v184, v185
	s_nop 0
	v_cndmask_b32_e32 v184, 0, v184, vcc
	v_cmp_ngt_f32_e32 vcc, s71, v182
	s_nop 1
	v_cndmask_b32_e32 v184, v178, v184, vcc
	v_sub_f32_e32 v184, 1.0, v184
	v_mul_f32_e32 v183, v180, v180
	v_fmamk_f32 v185, v183, 0xba1345e1, v176
	v_fmaak_f32 v185, v183, v185, 0xbcdac9b8
	v_fmaak_f32 v185, v183, v185, 0x3de703be
	v_fmaak_f32 v185, v183, v185, 0xbec09330
	v_fmaak_f32 v183, v183, v185, 0x3e0375d0
	v_fma_f32 v183, |v180|, v183, |v180|
	v_cmp_nlt_f32_e64 vcc, |v180|, 1.0
	s_nop 1
	v_cndmask_b32_e32 v184, v183, v184, vcc
	v_bfi_b32 v184, s14, v184, v180
	v_add_f32_e32 v184, 1.0, v184
	v_mul_f32_e32 v89, 0.5, v89
	v_mul_f32_e32 v57, v57, v61
	v_mul_f32_e32 v89, v89, v184
	v_mul_f32_e32 v89, v57, v89
	global_store_dword v160, v88, s[12:13]
	global_store_dword v160, v89, s[12:13] offset:256
	s_add_u32 s12, s12, s18
	s_addc_u32 s13, s13, 0
	v_mul_f32_e32 v90, v64, v90
	v_mul_f32_e32 v180, 0x3f3504f3, v90
	v_fma_f32 v182, |v180|, s16, v177
	v_fma_f32 v182, |v180|, v182, s19
	v_fma_f32 v182, |v180|, v182, s50
	v_fma_f32 v182, |v180|, v182, s51
	v_fma_f32 v182, |v180|, v182, s64
	v_fma_f32 v182, |v180|, v182, s65
	v_fma_f32 v182, |v180|, v182, |v180|
	v_mul_f32_e32 v184, 0xbfb8aa3b, v182
	v_fma_f32 v185, v182, s98, -v184
	v_rndne_f32_e32 v186, v184
	v_fmac_f32_e32 v185, 0xb2a5705f, v182
	v_sub_f32_e32 v184, v184, v186
	v_add_f32_e32 v184, v184, v185
	v_cvt_i32_f32_e32 v185, v186
	v_exp_f32_e32 v184, v184
	v_cmp_nlt_f32_e32 vcc, s70, v182
	v_ldexp_f32 v184, v184, v185
	s_nop 0
	v_cndmask_b32_e32 v184, 0, v184, vcc
	v_cmp_ngt_f32_e32 vcc, s71, v182
	s_nop 1
	v_cndmask_b32_e32 v184, v178, v184, vcc
	v_sub_f32_e32 v184, 1.0, v184
	v_mul_f32_e32 v183, v180, v180
	v_fmamk_f32 v185, v183, 0xba1345e1, v176
	v_fmaak_f32 v185, v183, v185, 0xbcdac9b8
	v_fmaak_f32 v185, v183, v185, 0x3de703be
	v_fmaak_f32 v185, v183, v185, 0xbec09330
	v_fmaak_f32 v183, v183, v185, 0x3e0375d0
	v_fma_f32 v183, |v180|, v183, |v180|
	v_cmp_nlt_f32_e64 vcc, |v180|, 1.0
	s_nop 1
	v_cndmask_b32_e32 v184, v183, v184, vcc
	v_bfi_b32 v184, s14, v184, v180
	v_add_f32_e32 v184, 1.0, v184
	v_mul_f32_e32 v90, 0.5, v90
	v_mul_f32_e32 v62, v62, v66
	v_mul_f32_e32 v90, v90, v184
	v_mul_f32_e32 v90, v62, v90
	v_mul_f32_e32 v91, v65, v91
	v_mul_f32_e32 v180, 0x3f3504f3, v91
	v_fma_f32 v182, |v180|, s16, v177
	v_fma_f32 v182, |v180|, v182, s19
	v_fma_f32 v182, |v180|, v182, s50
	v_fma_f32 v182, |v180|, v182, s51
	v_fma_f32 v182, |v180|, v182, s64
	v_fma_f32 v182, |v180|, v182, s65
	v_fma_f32 v182, |v180|, v182, |v180|
	v_mul_f32_e32 v184, 0xbfb8aa3b, v182
	v_fma_f32 v185, v182, s98, -v184
	v_rndne_f32_e32 v186, v184
	v_fmac_f32_e32 v185, 0xb2a5705f, v182
	v_sub_f32_e32 v184, v184, v186
	v_add_f32_e32 v184, v184, v185
	v_cvt_i32_f32_e32 v185, v186
	v_exp_f32_e32 v184, v184
	v_cmp_nlt_f32_e32 vcc, s70, v182
	v_ldexp_f32 v184, v184, v185
	s_nop 0
	v_cndmask_b32_e32 v184, 0, v184, vcc
	v_cmp_ngt_f32_e32 vcc, s71, v182
	s_nop 1
	v_cndmask_b32_e32 v184, v178, v184, vcc
	v_sub_f32_e32 v184, 1.0, v184
	v_mul_f32_e32 v183, v180, v180
	v_fmamk_f32 v185, v183, 0xba1345e1, v176
	v_fmaak_f32 v185, v183, v185, 0xbcdac9b8
	v_fmaak_f32 v185, v183, v185, 0x3de703be
	v_fmaak_f32 v185, v183, v185, 0xbec09330
	v_fmaak_f32 v183, v183, v185, 0x3e0375d0
	v_fma_f32 v183, |v180|, v183, |v180|
	v_cmp_nlt_f32_e64 vcc, |v180|, 1.0
	s_nop 1
	v_cndmask_b32_e32 v184, v183, v184, vcc
	v_bfi_b32 v184, s14, v184, v180
	v_add_f32_e32 v184, 1.0, v184
	v_mul_f32_e32 v91, 0.5, v91
	v_mul_f32_e32 v63, v63, v67
	v_mul_f32_e32 v91, v91, v184
	v_mul_f32_e32 v91, v63, v91
	global_store_dword v160, v90, s[12:13]
	global_store_dword v160, v91, s[12:13] offset:256
	s_add_u32 s12, s12, s18
	s_addc_u32 s13, s13, 0
	v_mul_f32_e32 v92, v70, v92
	v_mul_f32_e32 v180, 0x3f3504f3, v92
	v_fma_f32 v182, |v180|, s16, v177
	v_fma_f32 v182, |v180|, v182, s19
	v_fma_f32 v182, |v180|, v182, s50
	v_fma_f32 v182, |v180|, v182, s51
	v_fma_f32 v182, |v180|, v182, s64
	v_fma_f32 v182, |v180|, v182, s65
	v_fma_f32 v182, |v180|, v182, |v180|
	v_mul_f32_e32 v184, 0xbfb8aa3b, v182
	v_fma_f32 v185, v182, s98, -v184
	v_rndne_f32_e32 v186, v184
	v_fmac_f32_e32 v185, 0xb2a5705f, v182
	v_sub_f32_e32 v184, v184, v186
	v_add_f32_e32 v184, v184, v185
	v_cvt_i32_f32_e32 v185, v186
	v_exp_f32_e32 v184, v184
	v_cmp_nlt_f32_e32 vcc, s70, v182
	v_ldexp_f32 v184, v184, v185
	s_nop 0
	v_cndmask_b32_e32 v184, 0, v184, vcc
	v_cmp_ngt_f32_e32 vcc, s71, v182
	s_nop 1
	v_cndmask_b32_e32 v184, v178, v184, vcc
	v_sub_f32_e32 v184, 1.0, v184
	v_mul_f32_e32 v183, v180, v180
	v_fmamk_f32 v185, v183, 0xba1345e1, v176
	v_fmaak_f32 v185, v183, v185, 0xbcdac9b8
	v_fmaak_f32 v185, v183, v185, 0x3de703be
	v_fmaak_f32 v185, v183, v185, 0xbec09330
	v_fmaak_f32 v183, v183, v185, 0x3e0375d0
	v_fma_f32 v183, |v180|, v183, |v180|
	v_cmp_nlt_f32_e64 vcc, |v180|, 1.0
	s_nop 1
	v_cndmask_b32_e32 v184, v183, v184, vcc
	v_bfi_b32 v184, s14, v184, v180
	v_add_f32_e32 v184, 1.0, v184
	v_mul_f32_e32 v92, 0.5, v92
	v_mul_f32_e32 v68, v68, v72
	v_mul_f32_e32 v92, v92, v184
	v_mul_f32_e32 v92, v68, v92
	v_mul_f32_e32 v93, v71, v93
	v_mul_f32_e32 v180, 0x3f3504f3, v93
	v_fma_f32 v182, |v180|, s16, v177
	v_fma_f32 v182, |v180|, v182, s19
	v_fma_f32 v182, |v180|, v182, s50
	v_fma_f32 v182, |v180|, v182, s51
	v_fma_f32 v182, |v180|, v182, s64
	v_fma_f32 v182, |v180|, v182, s65
	v_fma_f32 v182, |v180|, v182, |v180|
	v_mul_f32_e32 v184, 0xbfb8aa3b, v182
	v_fma_f32 v185, v182, s98, -v184
	v_rndne_f32_e32 v186, v184
	v_fmac_f32_e32 v185, 0xb2a5705f, v182
	v_sub_f32_e32 v184, v184, v186
	v_add_f32_e32 v184, v184, v185
	v_cvt_i32_f32_e32 v185, v186
	v_exp_f32_e32 v184, v184
	v_cmp_nlt_f32_e32 vcc, s70, v182
	v_ldexp_f32 v184, v184, v185
	s_nop 0
	v_cndmask_b32_e32 v184, 0, v184, vcc
	v_cmp_ngt_f32_e32 vcc, s71, v182
	s_nop 1
	v_cndmask_b32_e32 v184, v178, v184, vcc
	v_sub_f32_e32 v184, 1.0, v184
	v_mul_f32_e32 v183, v180, v180
	v_fmamk_f32 v185, v183, 0xba1345e1, v176
	v_fmaak_f32 v185, v183, v185, 0xbcdac9b8
	v_fmaak_f32 v185, v183, v185, 0x3de703be
	v_fmaak_f32 v185, v183, v185, 0xbec09330
	v_fmaak_f32 v183, v183, v185, 0x3e0375d0
	v_fma_f32 v183, |v180|, v183, |v180|
	v_cmp_nlt_f32_e64 vcc, |v180|, 1.0
	s_nop 1
	v_cndmask_b32_e32 v184, v183, v184, vcc
	v_bfi_b32 v184, s14, v184, v180
	v_add_f32_e32 v184, 1.0, v184
	v_mul_f32_e32 v93, 0.5, v93
	v_mul_f32_e32 v69, v69, v73
	v_mul_f32_e32 v93, v93, v184
	v_mul_f32_e32 v93, v69, v93
	global_store_dword v160, v92, s[12:13]
	global_store_dword v160, v93, s[12:13] offset:256
	s_add_u32 s12, s12, s18
	s_addc_u32 s13, s13, 0
	v_mul_f32_e32 v94, v76, v94
	v_mul_f32_e32 v180, 0x3f3504f3, v94
	v_fma_f32 v182, |v180|, s16, v177
	v_fma_f32 v182, |v180|, v182, s19
	v_fma_f32 v182, |v180|, v182, s50
	v_fma_f32 v182, |v180|, v182, s51
	v_fma_f32 v182, |v180|, v182, s64
	v_fma_f32 v182, |v180|, v182, s65
	v_fma_f32 v182, |v180|, v182, |v180|
	v_mul_f32_e32 v184, 0xbfb8aa3b, v182
	v_fma_f32 v185, v182, s98, -v184
	v_rndne_f32_e32 v186, v184
	v_fmac_f32_e32 v185, 0xb2a5705f, v182
	v_sub_f32_e32 v184, v184, v186
	v_add_f32_e32 v184, v184, v185
	v_cvt_i32_f32_e32 v185, v186
	v_exp_f32_e32 v184, v184
	v_cmp_nlt_f32_e32 vcc, s70, v182
	v_ldexp_f32 v184, v184, v185
	s_nop 0
	v_cndmask_b32_e32 v184, 0, v184, vcc
	v_cmp_ngt_f32_e32 vcc, s71, v182
	s_nop 1
	v_cndmask_b32_e32 v184, v178, v184, vcc
	v_sub_f32_e32 v184, 1.0, v184
	v_mul_f32_e32 v183, v180, v180
	v_fmamk_f32 v185, v183, 0xba1345e1, v176
	v_fmaak_f32 v185, v183, v185, 0xbcdac9b8
	v_fmaak_f32 v185, v183, v185, 0x3de703be
	v_fmaak_f32 v185, v183, v185, 0xbec09330
	v_fmaak_f32 v183, v183, v185, 0x3e0375d0
	v_fma_f32 v183, |v180|, v183, |v180|
	v_cmp_nlt_f32_e64 vcc, |v180|, 1.0
	s_nop 1
	v_cndmask_b32_e32 v184, v183, v184, vcc
	v_bfi_b32 v184, s14, v184, v180
	v_add_f32_e32 v184, 1.0, v184
	v_mul_f32_e32 v94, 0.5, v94
	v_mul_f32_e32 v74, v74, v78
	v_mul_f32_e32 v94, v94, v184
	v_mul_f32_e32 v94, v74, v94
	v_mul_f32_e32 v95, v77, v95
	v_mul_f32_e32 v180, 0x3f3504f3, v95
	v_fma_f32 v182, |v180|, s16, v177
	v_fma_f32 v182, |v180|, v182, s19
	v_fma_f32 v182, |v180|, v182, s50
	v_fma_f32 v182, |v180|, v182, s51
	v_fma_f32 v182, |v180|, v182, s64
	v_fma_f32 v182, |v180|, v182, s65
	v_fma_f32 v182, |v180|, v182, |v180|
	v_mul_f32_e32 v184, 0xbfb8aa3b, v182
	v_fma_f32 v185, v182, s98, -v184
	v_rndne_f32_e32 v186, v184
	v_fmac_f32_e32 v185, 0xb2a5705f, v182
	v_sub_f32_e32 v184, v184, v186
	v_add_f32_e32 v184, v184, v185
	v_cvt_i32_f32_e32 v185, v186
	v_exp_f32_e32 v184, v184
	v_cmp_nlt_f32_e32 vcc, s70, v182
	v_ldexp_f32 v184, v184, v185
	s_nop 0
	v_cndmask_b32_e32 v184, 0, v184, vcc
	v_cmp_ngt_f32_e32 vcc, s71, v182
	s_nop 1
	v_cndmask_b32_e32 v184, v178, v184, vcc
	v_sub_f32_e32 v184, 1.0, v184
	v_mul_f32_e32 v183, v180, v180
	v_fmamk_f32 v185, v183, 0xba1345e1, v176
	v_fmaak_f32 v185, v183, v185, 0xbcdac9b8
	v_fmaak_f32 v185, v183, v185, 0x3de703be
	v_fmaak_f32 v185, v183, v185, 0xbec09330
	v_fmaak_f32 v183, v183, v185, 0x3e0375d0
	v_fma_f32 v183, |v180|, v183, |v180|
	v_cmp_nlt_f32_e64 vcc, |v180|, 1.0
	s_nop 1
	v_cndmask_b32_e32 v184, v183, v184, vcc
	v_bfi_b32 v184, s14, v184, v180
	v_add_f32_e32 v184, 1.0, v184
	v_mul_f32_e32 v95, 0.5, v95
	v_mul_f32_e32 v75, v75, v79
	v_mul_f32_e32 v95, v95, v184
	v_mul_f32_e32 v95, v75, v95
	global_store_dword v160, v94, s[12:13]
	global_store_dword v160, v95, s[12:13] offset:256
	s_add_u32 s12, s12, s18
	s_addc_u32 s13, s13, 0
	ds_read2st64_b32 v[16:17], v174 offset0:16 offset1:17
	ds_read2st64_b32 v[80:81], v175 offset0:16 offset1:17
	ds_read2st64_b32 v[18:19], v174 offset0:18 offset1:19
	ds_read2st64_b32 v[82:83], v175 offset0:18 offset1:19
	ds_read2st64_b32 v[20:21], v174 offset0:20 offset1:21
	ds_read2st64_b32 v[84:85], v175 offset0:20 offset1:21
	ds_read2st64_b32 v[22:23], v174 offset0:22 offset1:23
	ds_read2st64_b32 v[86:87], v175 offset0:22 offset1:23
	ds_read2st64_b32 v[24:25], v174 offset0:24 offset1:25
	ds_read2st64_b32 v[88:89], v175 offset0:24 offset1:25
	ds_read2st64_b32 v[26:27], v174 offset0:26 offset1:27
	ds_read2st64_b32 v[90:91], v175 offset0:26 offset1:27
	ds_read2st64_b32 v[28:29], v174 offset0:28 offset1:29
	ds_read2st64_b32 v[92:93], v175 offset0:28 offset1:29
	ds_read2st64_b32 v[30:31], v174 offset0:30 offset1:31
	ds_read2st64_b32 v[94:95], v175 offset0:30 offset1:31
	s_waitcnt lgkmcnt(0)
	v_lshlrev_b32_e32 v16, 2, v16
	v_lshlrev_b32_e32 v17, 2, v17
	v_lshlrev_b32_e32 v18, 2, v18
	v_lshlrev_b32_e32 v19, 2, v19
	v_lshlrev_b32_e32 v20, 2, v20
	v_lshlrev_b32_e32 v21, 2, v21
	v_lshlrev_b32_e32 v22, 2, v22
	v_lshlrev_b32_e32 v23, 2, v23
	v_lshlrev_b32_e32 v24, 2, v24
	v_lshlrev_b32_e32 v25, 2, v25
	v_lshlrev_b32_e32 v26, 2, v26
	v_lshlrev_b32_e32 v27, 2, v27
	v_lshlrev_b32_e32 v28, 2, v28
	v_lshlrev_b32_e32 v29, 2, v29
	v_lshlrev_b32_e32 v30, 2, v30
	v_lshlrev_b32_e32 v31, 2, v31
	global_load_dword v32, v160, s[10:11]
	global_load_dword v33, v160, s[10:11] offset:256
	global_load_dword v34, v16, s[4:5]
	global_load_dword v35, v17, s[4:5]
	global_load_dword v36, v16, s[8:9]
	global_load_dword v37, v17, s[8:9]
	s_add_u32 s10, s10, s18
	s_addc_u32 s11, s11, 0
	global_load_dword v38, v160, s[10:11]
	global_load_dword v39, v160, s[10:11] offset:256
	global_load_dword v40, v18, s[4:5]
	global_load_dword v41, v19, s[4:5]
	global_load_dword v42, v18, s[8:9]
	global_load_dword v43, v19, s[8:9]
	s_add_u32 s10, s10, s18
	s_addc_u32 s11, s11, 0
	global_load_dword v44, v160, s[10:11]
	global_load_dword v45, v160, s[10:11] offset:256
	global_load_dword v46, v20, s[4:5]
	global_load_dword v47, v21, s[4:5]
	global_load_dword v48, v20, s[8:9]
	global_load_dword v49, v21, s[8:9]
	s_add_u32 s10, s10, s18
	s_addc_u32 s11, s11, 0
	global_load_dword v50, v160, s[10:11]
	global_load_dword v51, v160, s[10:11] offset:256
	global_load_dword v52, v22, s[4:5]
	global_load_dword v53, v23, s[4:5]
	global_load_dword v54, v22, s[8:9]
	global_load_dword v55, v23, s[8:9]
	s_add_u32 s10, s10, s18
	s_addc_u32 s11, s11, 0
	global_load_dword v56, v160, s[10:11]
	global_load_dword v57, v160, s[10:11] offset:256
	global_load_dword v58, v24, s[4:5]
	global_load_dword v59, v25, s[4:5]
	global_load_dword v60, v24, s[8:9]
	global_load_dword v61, v25, s[8:9]
	s_add_u32 s10, s10, s18
	s_addc_u32 s11, s11, 0
	global_load_dword v62, v160, s[10:11]
	global_load_dword v63, v160, s[10:11] offset:256
	global_load_dword v64, v26, s[4:5]
	global_load_dword v65, v27, s[4:5]
	global_load_dword v66, v26, s[8:9]
	global_load_dword v67, v27, s[8:9]
	s_add_u32 s10, s10, s18
	s_addc_u32 s11, s11, 0
	global_load_dword v68, v160, s[10:11]
	global_load_dword v69, v160, s[10:11] offset:256
	global_load_dword v70, v28, s[4:5]
	global_load_dword v71, v29, s[4:5]
	global_load_dword v72, v28, s[8:9]
	global_load_dword v73, v29, s[8:9]
	s_add_u32 s10, s10, s18
	s_addc_u32 s11, s11, 0
	global_load_dword v74, v160, s[10:11]
	global_load_dword v75, v160, s[10:11] offset:256
	global_load_dword v76, v30, s[4:5]
	global_load_dword v77, v31, s[4:5]
	global_load_dword v78, v30, s[8:9]
	global_load_dword v79, v31, s[8:9]
	s_add_u32 s10, s10, s18
	s_addc_u32 s11, s11, 0
	s_waitcnt vmcnt(0)
	v_mul_f32_e32 v80, v34, v80
	v_mul_f32_e32 v180, 0x3f3504f3, v80
	v_fma_f32 v182, |v180|, s16, v177
	v_fma_f32 v182, |v180|, v182, s19
	v_fma_f32 v182, |v180|, v182, s50
	v_fma_f32 v182, |v180|, v182, s51
	v_fma_f32 v182, |v180|, v182, s64
	v_fma_f32 v182, |v180|, v182, s65
	v_fma_f32 v182, |v180|, v182, |v180|
	v_mul_f32_e32 v184, 0xbfb8aa3b, v182
	v_fma_f32 v185, v182, s98, -v184
	v_rndne_f32_e32 v186, v184
	v_fmac_f32_e32 v185, 0xb2a5705f, v182
	v_sub_f32_e32 v184, v184, v186
	v_add_f32_e32 v184, v184, v185
	v_cvt_i32_f32_e32 v185, v186
	v_exp_f32_e32 v184, v184
	v_cmp_nlt_f32_e32 vcc, s70, v182
	v_ldexp_f32 v184, v184, v185
	s_nop 0
	v_cndmask_b32_e32 v184, 0, v184, vcc
	v_cmp_ngt_f32_e32 vcc, s71, v182
	s_nop 1
	v_cndmask_b32_e32 v184, v178, v184, vcc
	v_sub_f32_e32 v184, 1.0, v184
	v_mul_f32_e32 v183, v180, v180
	v_fmamk_f32 v185, v183, 0xba1345e1, v176
	v_fmaak_f32 v185, v183, v185, 0xbcdac9b8
	v_fmaak_f32 v185, v183, v185, 0x3de703be
	v_fmaak_f32 v185, v183, v185, 0xbec09330
	v_fmaak_f32 v183, v183, v185, 0x3e0375d0
	v_fma_f32 v183, |v180|, v183, |v180|
	v_cmp_nlt_f32_e64 vcc, |v180|, 1.0
	s_nop 1
	v_cndmask_b32_e32 v184, v183, v184, vcc
	v_bfi_b32 v184, s14, v184, v180
	v_add_f32_e32 v184, 1.0, v184
	v_mul_f32_e32 v80, 0.5, v80
	v_mul_f32_e32 v32, v32, v36
	v_mul_f32_e32 v80, v80, v184
	v_mul_f32_e32 v80, v32, v80
	v_mul_f32_e32 v81, v35, v81
	v_mul_f32_e32 v180, 0x3f3504f3, v81
	v_fma_f32 v182, |v180|, s16, v177
	v_fma_f32 v182, |v180|, v182, s19
	v_fma_f32 v182, |v180|, v182, s50
	v_fma_f32 v182, |v180|, v182, s51
	v_fma_f32 v182, |v180|, v182, s64
	v_fma_f32 v182, |v180|, v182, s65
	v_fma_f32 v182, |v180|, v182, |v180|
	v_mul_f32_e32 v184, 0xbfb8aa3b, v182
	v_fma_f32 v185, v182, s98, -v184
	v_rndne_f32_e32 v186, v184
	v_fmac_f32_e32 v185, 0xb2a5705f, v182
	v_sub_f32_e32 v184, v184, v186
	v_add_f32_e32 v184, v184, v185
	v_cvt_i32_f32_e32 v185, v186
	v_exp_f32_e32 v184, v184
	v_cmp_nlt_f32_e32 vcc, s70, v182
	v_ldexp_f32 v184, v184, v185
	s_nop 0
	v_cndmask_b32_e32 v184, 0, v184, vcc
	v_cmp_ngt_f32_e32 vcc, s71, v182
	s_nop 1
	v_cndmask_b32_e32 v184, v178, v184, vcc
	v_sub_f32_e32 v184, 1.0, v184
	v_mul_f32_e32 v183, v180, v180
	v_fmamk_f32 v185, v183, 0xba1345e1, v176
	v_fmaak_f32 v185, v183, v185, 0xbcdac9b8
	v_fmaak_f32 v185, v183, v185, 0x3de703be
	v_fmaak_f32 v185, v183, v185, 0xbec09330
	v_fmaak_f32 v183, v183, v185, 0x3e0375d0
	v_fma_f32 v183, |v180|, v183, |v180|
	v_cmp_nlt_f32_e64 vcc, |v180|, 1.0
	s_nop 1
	v_cndmask_b32_e32 v184, v183, v184, vcc
	v_bfi_b32 v184, s14, v184, v180
	v_add_f32_e32 v184, 1.0, v184
	v_mul_f32_e32 v81, 0.5, v81
	v_mul_f32_e32 v33, v33, v37
	v_mul_f32_e32 v81, v81, v184
	v_mul_f32_e32 v81, v33, v81
	global_store_dword v160, v80, s[12:13]
	global_store_dword v160, v81, s[12:13] offset:256
	s_add_u32 s12, s12, s18
	s_addc_u32 s13, s13, 0
	v_mul_f32_e32 v82, v40, v82
	v_mul_f32_e32 v180, 0x3f3504f3, v82
	v_fma_f32 v182, |v180|, s16, v177
	v_fma_f32 v182, |v180|, v182, s19
	v_fma_f32 v182, |v180|, v182, s50
	v_fma_f32 v182, |v180|, v182, s51
	v_fma_f32 v182, |v180|, v182, s64
	v_fma_f32 v182, |v180|, v182, s65
	v_fma_f32 v182, |v180|, v182, |v180|
	v_mul_f32_e32 v184, 0xbfb8aa3b, v182
	v_fma_f32 v185, v182, s98, -v184
	v_rndne_f32_e32 v186, v184
	v_fmac_f32_e32 v185, 0xb2a5705f, v182
	v_sub_f32_e32 v184, v184, v186
	v_add_f32_e32 v184, v184, v185
	v_cvt_i32_f32_e32 v185, v186
	v_exp_f32_e32 v184, v184
	v_cmp_nlt_f32_e32 vcc, s70, v182
	v_ldexp_f32 v184, v184, v185
	s_nop 0
	v_cndmask_b32_e32 v184, 0, v184, vcc
	v_cmp_ngt_f32_e32 vcc, s71, v182
	s_nop 1
	v_cndmask_b32_e32 v184, v178, v184, vcc
	v_sub_f32_e32 v184, 1.0, v184
	v_mul_f32_e32 v183, v180, v180
	v_fmamk_f32 v185, v183, 0xba1345e1, v176
	v_fmaak_f32 v185, v183, v185, 0xbcdac9b8
	v_fmaak_f32 v185, v183, v185, 0x3de703be
	v_fmaak_f32 v185, v183, v185, 0xbec09330
	v_fmaak_f32 v183, v183, v185, 0x3e0375d0
	v_fma_f32 v183, |v180|, v183, |v180|
	v_cmp_nlt_f32_e64 vcc, |v180|, 1.0
	s_nop 1
	v_cndmask_b32_e32 v184, v183, v184, vcc
	v_bfi_b32 v184, s14, v184, v180
	v_add_f32_e32 v184, 1.0, v184
	v_mul_f32_e32 v82, 0.5, v82
	v_mul_f32_e32 v38, v38, v42
	v_mul_f32_e32 v82, v82, v184
	v_mul_f32_e32 v82, v38, v82
	v_mul_f32_e32 v83, v41, v83
	v_mul_f32_e32 v180, 0x3f3504f3, v83
	v_fma_f32 v182, |v180|, s16, v177
	v_fma_f32 v182, |v180|, v182, s19
	v_fma_f32 v182, |v180|, v182, s50
	v_fma_f32 v182, |v180|, v182, s51
	v_fma_f32 v182, |v180|, v182, s64
	v_fma_f32 v182, |v180|, v182, s65
	v_fma_f32 v182, |v180|, v182, |v180|
	v_mul_f32_e32 v184, 0xbfb8aa3b, v182
	v_fma_f32 v185, v182, s98, -v184
	v_rndne_f32_e32 v186, v184
	v_fmac_f32_e32 v185, 0xb2a5705f, v182
	v_sub_f32_e32 v184, v184, v186
	v_add_f32_e32 v184, v184, v185
	v_cvt_i32_f32_e32 v185, v186
	v_exp_f32_e32 v184, v184
	v_cmp_nlt_f32_e32 vcc, s70, v182
	v_ldexp_f32 v184, v184, v185
	s_nop 0
	v_cndmask_b32_e32 v184, 0, v184, vcc
	v_cmp_ngt_f32_e32 vcc, s71, v182
	s_nop 1
	v_cndmask_b32_e32 v184, v178, v184, vcc
	v_sub_f32_e32 v184, 1.0, v184
	v_mul_f32_e32 v183, v180, v180
	v_fmamk_f32 v185, v183, 0xba1345e1, v176
	v_fmaak_f32 v185, v183, v185, 0xbcdac9b8
	v_fmaak_f32 v185, v183, v185, 0x3de703be
	v_fmaak_f32 v185, v183, v185, 0xbec09330
	v_fmaak_f32 v183, v183, v185, 0x3e0375d0
	v_fma_f32 v183, |v180|, v183, |v180|
	v_cmp_nlt_f32_e64 vcc, |v180|, 1.0
	s_nop 1
	v_cndmask_b32_e32 v184, v183, v184, vcc
	v_bfi_b32 v184, s14, v184, v180
	v_add_f32_e32 v184, 1.0, v184
	v_mul_f32_e32 v83, 0.5, v83
	v_mul_f32_e32 v39, v39, v43
	v_mul_f32_e32 v83, v83, v184
	v_mul_f32_e32 v83, v39, v83
	global_store_dword v160, v82, s[12:13]
	global_store_dword v160, v83, s[12:13] offset:256
	s_add_u32 s12, s12, s18
	s_addc_u32 s13, s13, 0
	v_mul_f32_e32 v84, v46, v84
	v_mul_f32_e32 v180, 0x3f3504f3, v84
	v_fma_f32 v182, |v180|, s16, v177
	v_fma_f32 v182, |v180|, v182, s19
	v_fma_f32 v182, |v180|, v182, s50
	v_fma_f32 v182, |v180|, v182, s51
	v_fma_f32 v182, |v180|, v182, s64
	v_fma_f32 v182, |v180|, v182, s65
	v_fma_f32 v182, |v180|, v182, |v180|
	v_mul_f32_e32 v184, 0xbfb8aa3b, v182
	v_fma_f32 v185, v182, s98, -v184
	v_rndne_f32_e32 v186, v184
	v_fmac_f32_e32 v185, 0xb2a5705f, v182
	v_sub_f32_e32 v184, v184, v186
	v_add_f32_e32 v184, v184, v185
	v_cvt_i32_f32_e32 v185, v186
	v_exp_f32_e32 v184, v184
	v_cmp_nlt_f32_e32 vcc, s70, v182
	v_ldexp_f32 v184, v184, v185
	s_nop 0
	v_cndmask_b32_e32 v184, 0, v184, vcc
	v_cmp_ngt_f32_e32 vcc, s71, v182
	s_nop 1
	v_cndmask_b32_e32 v184, v178, v184, vcc
	v_sub_f32_e32 v184, 1.0, v184
	v_mul_f32_e32 v183, v180, v180
	v_fmamk_f32 v185, v183, 0xba1345e1, v176
	v_fmaak_f32 v185, v183, v185, 0xbcdac9b8
	v_fmaak_f32 v185, v183, v185, 0x3de703be
	v_fmaak_f32 v185, v183, v185, 0xbec09330
	v_fmaak_f32 v183, v183, v185, 0x3e0375d0
	v_fma_f32 v183, |v180|, v183, |v180|
	v_cmp_nlt_f32_e64 vcc, |v180|, 1.0
	s_nop 1
	v_cndmask_b32_e32 v184, v183, v184, vcc
	v_bfi_b32 v184, s14, v184, v180
	v_add_f32_e32 v184, 1.0, v184
	v_mul_f32_e32 v84, 0.5, v84
	v_mul_f32_e32 v44, v44, v48
	v_mul_f32_e32 v84, v84, v184
	v_mul_f32_e32 v84, v44, v84
	v_mul_f32_e32 v85, v47, v85
	v_mul_f32_e32 v180, 0x3f3504f3, v85
	v_fma_f32 v182, |v180|, s16, v177
	v_fma_f32 v182, |v180|, v182, s19
	v_fma_f32 v182, |v180|, v182, s50
	v_fma_f32 v182, |v180|, v182, s51
	v_fma_f32 v182, |v180|, v182, s64
	v_fma_f32 v182, |v180|, v182, s65
	v_fma_f32 v182, |v180|, v182, |v180|
	v_mul_f32_e32 v184, 0xbfb8aa3b, v182
	v_fma_f32 v185, v182, s98, -v184
	v_rndne_f32_e32 v186, v184
	v_fmac_f32_e32 v185, 0xb2a5705f, v182
	v_sub_f32_e32 v184, v184, v186
	v_add_f32_e32 v184, v184, v185
	v_cvt_i32_f32_e32 v185, v186
	v_exp_f32_e32 v184, v184
	v_cmp_nlt_f32_e32 vcc, s70, v182
	v_ldexp_f32 v184, v184, v185
	s_nop 0
	v_cndmask_b32_e32 v184, 0, v184, vcc
	v_cmp_ngt_f32_e32 vcc, s71, v182
	s_nop 1
	v_cndmask_b32_e32 v184, v178, v184, vcc
	v_sub_f32_e32 v184, 1.0, v184
	v_mul_f32_e32 v183, v180, v180
	v_fmamk_f32 v185, v183, 0xba1345e1, v176
	v_fmaak_f32 v185, v183, v185, 0xbcdac9b8
	v_fmaak_f32 v185, v183, v185, 0x3de703be
	v_fmaak_f32 v185, v183, v185, 0xbec09330
	v_fmaak_f32 v183, v183, v185, 0x3e0375d0
	v_fma_f32 v183, |v180|, v183, |v180|
	v_cmp_nlt_f32_e64 vcc, |v180|, 1.0
	s_nop 1
	v_cndmask_b32_e32 v184, v183, v184, vcc
	v_bfi_b32 v184, s14, v184, v180
	v_add_f32_e32 v184, 1.0, v184
	v_mul_f32_e32 v85, 0.5, v85
	v_mul_f32_e32 v45, v45, v49
	v_mul_f32_e32 v85, v85, v184
	v_mul_f32_e32 v85, v45, v85
	global_store_dword v160, v84, s[12:13]
	global_store_dword v160, v85, s[12:13] offset:256
	s_add_u32 s12, s12, s18
	s_addc_u32 s13, s13, 0
	v_mul_f32_e32 v86, v52, v86
	v_mul_f32_e32 v180, 0x3f3504f3, v86
	v_fma_f32 v182, |v180|, s16, v177
	v_fma_f32 v182, |v180|, v182, s19
	v_fma_f32 v182, |v180|, v182, s50
	v_fma_f32 v182, |v180|, v182, s51
	v_fma_f32 v182, |v180|, v182, s64
	v_fma_f32 v182, |v180|, v182, s65
	v_fma_f32 v182, |v180|, v182, |v180|
	v_mul_f32_e32 v184, 0xbfb8aa3b, v182
	v_fma_f32 v185, v182, s98, -v184
	v_rndne_f32_e32 v186, v184
	v_fmac_f32_e32 v185, 0xb2a5705f, v182
	v_sub_f32_e32 v184, v184, v186
	v_add_f32_e32 v184, v184, v185
	v_cvt_i32_f32_e32 v185, v186
	v_exp_f32_e32 v184, v184
	v_cmp_nlt_f32_e32 vcc, s70, v182
	v_ldexp_f32 v184, v184, v185
	s_nop 0
	v_cndmask_b32_e32 v184, 0, v184, vcc
	v_cmp_ngt_f32_e32 vcc, s71, v182
	s_nop 1
	v_cndmask_b32_e32 v184, v178, v184, vcc
	v_sub_f32_e32 v184, 1.0, v184
	v_mul_f32_e32 v183, v180, v180
	v_fmamk_f32 v185, v183, 0xba1345e1, v176
	v_fmaak_f32 v185, v183, v185, 0xbcdac9b8
	v_fmaak_f32 v185, v183, v185, 0x3de703be
	v_fmaak_f32 v185, v183, v185, 0xbec09330
	v_fmaak_f32 v183, v183, v185, 0x3e0375d0
	v_fma_f32 v183, |v180|, v183, |v180|
	v_cmp_nlt_f32_e64 vcc, |v180|, 1.0
	s_nop 1
	v_cndmask_b32_e32 v184, v183, v184, vcc
	v_bfi_b32 v184, s14, v184, v180
	v_add_f32_e32 v184, 1.0, v184
	v_mul_f32_e32 v86, 0.5, v86
	v_mul_f32_e32 v50, v50, v54
	v_mul_f32_e32 v86, v86, v184
	v_mul_f32_e32 v86, v50, v86
	v_mul_f32_e32 v87, v53, v87
	v_mul_f32_e32 v180, 0x3f3504f3, v87
	v_fma_f32 v182, |v180|, s16, v177
	v_fma_f32 v182, |v180|, v182, s19
	v_fma_f32 v182, |v180|, v182, s50
	v_fma_f32 v182, |v180|, v182, s51
	v_fma_f32 v182, |v180|, v182, s64
	v_fma_f32 v182, |v180|, v182, s65
	v_fma_f32 v182, |v180|, v182, |v180|
	v_mul_f32_e32 v184, 0xbfb8aa3b, v182
	v_fma_f32 v185, v182, s98, -v184
	v_rndne_f32_e32 v186, v184
	v_fmac_f32_e32 v185, 0xb2a5705f, v182
	v_sub_f32_e32 v184, v184, v186
	v_add_f32_e32 v184, v184, v185
	v_cvt_i32_f32_e32 v185, v186
	v_exp_f32_e32 v184, v184
	v_cmp_nlt_f32_e32 vcc, s70, v182
	v_ldexp_f32 v184, v184, v185
	s_nop 0
	v_cndmask_b32_e32 v184, 0, v184, vcc
	v_cmp_ngt_f32_e32 vcc, s71, v182
	s_nop 1
	v_cndmask_b32_e32 v184, v178, v184, vcc
	v_sub_f32_e32 v184, 1.0, v184
	v_mul_f32_e32 v183, v180, v180
	v_fmamk_f32 v185, v183, 0xba1345e1, v176
	v_fmaak_f32 v185, v183, v185, 0xbcdac9b8
	v_fmaak_f32 v185, v183, v185, 0x3de703be
	v_fmaak_f32 v185, v183, v185, 0xbec09330
	v_fmaak_f32 v183, v183, v185, 0x3e0375d0
	v_fma_f32 v183, |v180|, v183, |v180|
	v_cmp_nlt_f32_e64 vcc, |v180|, 1.0
	s_nop 1
	v_cndmask_b32_e32 v184, v183, v184, vcc
	v_bfi_b32 v184, s14, v184, v180
	v_add_f32_e32 v184, 1.0, v184
	v_mul_f32_e32 v87, 0.5, v87
	v_mul_f32_e32 v51, v51, v55
	v_mul_f32_e32 v87, v87, v184
	v_mul_f32_e32 v87, v51, v87
	global_store_dword v160, v86, s[12:13]
	global_store_dword v160, v87, s[12:13] offset:256
	s_add_u32 s12, s12, s18
	s_addc_u32 s13, s13, 0
	v_mul_f32_e32 v88, v58, v88
	v_mul_f32_e32 v180, 0x3f3504f3, v88
	v_fma_f32 v182, |v180|, s16, v177
	v_fma_f32 v182, |v180|, v182, s19
	v_fma_f32 v182, |v180|, v182, s50
	v_fma_f32 v182, |v180|, v182, s51
	v_fma_f32 v182, |v180|, v182, s64
	v_fma_f32 v182, |v180|, v182, s65
	v_fma_f32 v182, |v180|, v182, |v180|
	v_mul_f32_e32 v184, 0xbfb8aa3b, v182
	v_fma_f32 v185, v182, s98, -v184
	v_rndne_f32_e32 v186, v184
	v_fmac_f32_e32 v185, 0xb2a5705f, v182
	v_sub_f32_e32 v184, v184, v186
	v_add_f32_e32 v184, v184, v185
	v_cvt_i32_f32_e32 v185, v186
	v_exp_f32_e32 v184, v184
	v_cmp_nlt_f32_e32 vcc, s70, v182
	v_ldexp_f32 v184, v184, v185
	s_nop 0
	v_cndmask_b32_e32 v184, 0, v184, vcc
	v_cmp_ngt_f32_e32 vcc, s71, v182
	s_nop 1
	v_cndmask_b32_e32 v184, v178, v184, vcc
	v_sub_f32_e32 v184, 1.0, v184
	v_mul_f32_e32 v183, v180, v180
	v_fmamk_f32 v185, v183, 0xba1345e1, v176
	v_fmaak_f32 v185, v183, v185, 0xbcdac9b8
	v_fmaak_f32 v185, v183, v185, 0x3de703be
	v_fmaak_f32 v185, v183, v185, 0xbec09330
	v_fmaak_f32 v183, v183, v185, 0x3e0375d0
	v_fma_f32 v183, |v180|, v183, |v180|
	v_cmp_nlt_f32_e64 vcc, |v180|, 1.0
	s_nop 1
	v_cndmask_b32_e32 v184, v183, v184, vcc
	v_bfi_b32 v184, s14, v184, v180
	v_add_f32_e32 v184, 1.0, v184
	v_mul_f32_e32 v88, 0.5, v88
	v_mul_f32_e32 v56, v56, v60
	v_mul_f32_e32 v88, v88, v184
	v_mul_f32_e32 v88, v56, v88
	v_mul_f32_e32 v89, v59, v89
	v_mul_f32_e32 v180, 0x3f3504f3, v89
	v_fma_f32 v182, |v180|, s16, v177
	v_fma_f32 v182, |v180|, v182, s19
	v_fma_f32 v182, |v180|, v182, s50
	v_fma_f32 v182, |v180|, v182, s51
	v_fma_f32 v182, |v180|, v182, s64
	v_fma_f32 v182, |v180|, v182, s65
	v_fma_f32 v182, |v180|, v182, |v180|
	v_mul_f32_e32 v184, 0xbfb8aa3b, v182
	v_fma_f32 v185, v182, s98, -v184
	v_rndne_f32_e32 v186, v184
	v_fmac_f32_e32 v185, 0xb2a5705f, v182
	v_sub_f32_e32 v184, v184, v186
	v_add_f32_e32 v184, v184, v185
	v_cvt_i32_f32_e32 v185, v186
	v_exp_f32_e32 v184, v184
	v_cmp_nlt_f32_e32 vcc, s70, v182
	v_ldexp_f32 v184, v184, v185
	s_nop 0
	v_cndmask_b32_e32 v184, 0, v184, vcc
	v_cmp_ngt_f32_e32 vcc, s71, v182
	s_nop 1
	v_cndmask_b32_e32 v184, v178, v184, vcc
	v_sub_f32_e32 v184, 1.0, v184
	v_mul_f32_e32 v183, v180, v180
	v_fmamk_f32 v185, v183, 0xba1345e1, v176
	v_fmaak_f32 v185, v183, v185, 0xbcdac9b8
	v_fmaak_f32 v185, v183, v185, 0x3de703be
	v_fmaak_f32 v185, v183, v185, 0xbec09330
	v_fmaak_f32 v183, v183, v185, 0x3e0375d0
	v_fma_f32 v183, |v180|, v183, |v180|
	v_cmp_nlt_f32_e64 vcc, |v180|, 1.0
	s_nop 1
	v_cndmask_b32_e32 v184, v183, v184, vcc
	v_bfi_b32 v184, s14, v184, v180
	v_add_f32_e32 v184, 1.0, v184
	v_mul_f32_e32 v89, 0.5, v89
	v_mul_f32_e32 v57, v57, v61
	v_mul_f32_e32 v89, v89, v184
	v_mul_f32_e32 v89, v57, v89
	global_store_dword v160, v88, s[12:13]
	global_store_dword v160, v89, s[12:13] offset:256
	s_add_u32 s12, s12, s18
	s_addc_u32 s13, s13, 0
	v_mul_f32_e32 v90, v64, v90
	v_mul_f32_e32 v180, 0x3f3504f3, v90
	v_fma_f32 v182, |v180|, s16, v177
	v_fma_f32 v182, |v180|, v182, s19
	v_fma_f32 v182, |v180|, v182, s50
	v_fma_f32 v182, |v180|, v182, s51
	v_fma_f32 v182, |v180|, v182, s64
	v_fma_f32 v182, |v180|, v182, s65
	v_fma_f32 v182, |v180|, v182, |v180|
	v_mul_f32_e32 v184, 0xbfb8aa3b, v182
	v_fma_f32 v185, v182, s98, -v184
	v_rndne_f32_e32 v186, v184
	v_fmac_f32_e32 v185, 0xb2a5705f, v182
	v_sub_f32_e32 v184, v184, v186
	v_add_f32_e32 v184, v184, v185
	v_cvt_i32_f32_e32 v185, v186
	v_exp_f32_e32 v184, v184
	v_cmp_nlt_f32_e32 vcc, s70, v182
	v_ldexp_f32 v184, v184, v185
	s_nop 0
	v_cndmask_b32_e32 v184, 0, v184, vcc
	v_cmp_ngt_f32_e32 vcc, s71, v182
	s_nop 1
	v_cndmask_b32_e32 v184, v178, v184, vcc
	v_sub_f32_e32 v184, 1.0, v184
	v_mul_f32_e32 v183, v180, v180
	v_fmamk_f32 v185, v183, 0xba1345e1, v176
	v_fmaak_f32 v185, v183, v185, 0xbcdac9b8
	v_fmaak_f32 v185, v183, v185, 0x3de703be
	v_fmaak_f32 v185, v183, v185, 0xbec09330
	v_fmaak_f32 v183, v183, v185, 0x3e0375d0
	v_fma_f32 v183, |v180|, v183, |v180|
	v_cmp_nlt_f32_e64 vcc, |v180|, 1.0
	s_nop 1
	v_cndmask_b32_e32 v184, v183, v184, vcc
	v_bfi_b32 v184, s14, v184, v180
	v_add_f32_e32 v184, 1.0, v184
	v_mul_f32_e32 v90, 0.5, v90
	v_mul_f32_e32 v62, v62, v66
	v_mul_f32_e32 v90, v90, v184
	v_mul_f32_e32 v90, v62, v90
	v_mul_f32_e32 v91, v65, v91
	v_mul_f32_e32 v180, 0x3f3504f3, v91
	v_fma_f32 v182, |v180|, s16, v177
	v_fma_f32 v182, |v180|, v182, s19
	v_fma_f32 v182, |v180|, v182, s50
	v_fma_f32 v182, |v180|, v182, s51
	v_fma_f32 v182, |v180|, v182, s64
	v_fma_f32 v182, |v180|, v182, s65
	v_fma_f32 v182, |v180|, v182, |v180|
	v_mul_f32_e32 v184, 0xbfb8aa3b, v182
	v_fma_f32 v185, v182, s98, -v184
	v_rndne_f32_e32 v186, v184
	v_fmac_f32_e32 v185, 0xb2a5705f, v182
	v_sub_f32_e32 v184, v184, v186
	v_add_f32_e32 v184, v184, v185
	v_cvt_i32_f32_e32 v185, v186
	v_exp_f32_e32 v184, v184
	v_cmp_nlt_f32_e32 vcc, s70, v182
	v_ldexp_f32 v184, v184, v185
	s_nop 0
	v_cndmask_b32_e32 v184, 0, v184, vcc
	v_cmp_ngt_f32_e32 vcc, s71, v182
	s_nop 1
	v_cndmask_b32_e32 v184, v178, v184, vcc
	v_sub_f32_e32 v184, 1.0, v184
	v_mul_f32_e32 v183, v180, v180
	v_fmamk_f32 v185, v183, 0xba1345e1, v176
	v_fmaak_f32 v185, v183, v185, 0xbcdac9b8
	v_fmaak_f32 v185, v183, v185, 0x3de703be
	v_fmaak_f32 v185, v183, v185, 0xbec09330
	v_fmaak_f32 v183, v183, v185, 0x3e0375d0
	v_fma_f32 v183, |v180|, v183, |v180|
	v_cmp_nlt_f32_e64 vcc, |v180|, 1.0
	s_nop 1
	v_cndmask_b32_e32 v184, v183, v184, vcc
	v_bfi_b32 v184, s14, v184, v180
	v_add_f32_e32 v184, 1.0, v184
	v_mul_f32_e32 v91, 0.5, v91
	v_mul_f32_e32 v63, v63, v67
	v_mul_f32_e32 v91, v91, v184
	v_mul_f32_e32 v91, v63, v91
	global_store_dword v160, v90, s[12:13]
	global_store_dword v160, v91, s[12:13] offset:256
	s_add_u32 s12, s12, s18
	s_addc_u32 s13, s13, 0
	v_mul_f32_e32 v92, v70, v92
	v_mul_f32_e32 v180, 0x3f3504f3, v92
	v_fma_f32 v182, |v180|, s16, v177
	v_fma_f32 v182, |v180|, v182, s19
	v_fma_f32 v182, |v180|, v182, s50
	v_fma_f32 v182, |v180|, v182, s51
	v_fma_f32 v182, |v180|, v182, s64
	v_fma_f32 v182, |v180|, v182, s65
	v_fma_f32 v182, |v180|, v182, |v180|
	v_mul_f32_e32 v184, 0xbfb8aa3b, v182
	v_fma_f32 v185, v182, s98, -v184
	v_rndne_f32_e32 v186, v184
	v_fmac_f32_e32 v185, 0xb2a5705f, v182
	v_sub_f32_e32 v184, v184, v186
	v_add_f32_e32 v184, v184, v185
	v_cvt_i32_f32_e32 v185, v186
	v_exp_f32_e32 v184, v184
	v_cmp_nlt_f32_e32 vcc, s70, v182
	v_ldexp_f32 v184, v184, v185
	s_nop 0
	v_cndmask_b32_e32 v184, 0, v184, vcc
	v_cmp_ngt_f32_e32 vcc, s71, v182
	s_nop 1
	v_cndmask_b32_e32 v184, v178, v184, vcc
	v_sub_f32_e32 v184, 1.0, v184
	v_mul_f32_e32 v183, v180, v180
	v_fmamk_f32 v185, v183, 0xba1345e1, v176
	v_fmaak_f32 v185, v183, v185, 0xbcdac9b8
	v_fmaak_f32 v185, v183, v185, 0x3de703be
	v_fmaak_f32 v185, v183, v185, 0xbec09330
	v_fmaak_f32 v183, v183, v185, 0x3e0375d0
	v_fma_f32 v183, |v180|, v183, |v180|
	v_cmp_nlt_f32_e64 vcc, |v180|, 1.0
	s_nop 1
	v_cndmask_b32_e32 v184, v183, v184, vcc
	v_bfi_b32 v184, s14, v184, v180
	v_add_f32_e32 v184, 1.0, v184
	v_mul_f32_e32 v92, 0.5, v92
	v_mul_f32_e32 v68, v68, v72
	v_mul_f32_e32 v92, v92, v184
	v_mul_f32_e32 v92, v68, v92
	v_mul_f32_e32 v93, v71, v93
	v_mul_f32_e32 v180, 0x3f3504f3, v93
	v_fma_f32 v182, |v180|, s16, v177
	v_fma_f32 v182, |v180|, v182, s19
	v_fma_f32 v182, |v180|, v182, s50
	v_fma_f32 v182, |v180|, v182, s51
	v_fma_f32 v182, |v180|, v182, s64
	v_fma_f32 v182, |v180|, v182, s65
	v_fma_f32 v182, |v180|, v182, |v180|
	v_mul_f32_e32 v184, 0xbfb8aa3b, v182
	v_fma_f32 v185, v182, s98, -v184
	v_rndne_f32_e32 v186, v184
	v_fmac_f32_e32 v185, 0xb2a5705f, v182
	v_sub_f32_e32 v184, v184, v186
	v_add_f32_e32 v184, v184, v185
	v_cvt_i32_f32_e32 v185, v186
	v_exp_f32_e32 v184, v184
	v_cmp_nlt_f32_e32 vcc, s70, v182
	v_ldexp_f32 v184, v184, v185
	s_nop 0
	v_cndmask_b32_e32 v184, 0, v184, vcc
	v_cmp_ngt_f32_e32 vcc, s71, v182
	s_nop 1
	v_cndmask_b32_e32 v184, v178, v184, vcc
	v_sub_f32_e32 v184, 1.0, v184
	v_mul_f32_e32 v183, v180, v180
	v_fmamk_f32 v185, v183, 0xba1345e1, v176
	v_fmaak_f32 v185, v183, v185, 0xbcdac9b8
	v_fmaak_f32 v185, v183, v185, 0x3de703be
	v_fmaak_f32 v185, v183, v185, 0xbec09330
	v_fmaak_f32 v183, v183, v185, 0x3e0375d0
	v_fma_f32 v183, |v180|, v183, |v180|
	v_cmp_nlt_f32_e64 vcc, |v180|, 1.0
	s_nop 1
	v_cndmask_b32_e32 v184, v183, v184, vcc
	v_bfi_b32 v184, s14, v184, v180
	v_add_f32_e32 v184, 1.0, v184
	v_mul_f32_e32 v93, 0.5, v93
	v_mul_f32_e32 v69, v69, v73
	v_mul_f32_e32 v93, v93, v184
	v_mul_f32_e32 v93, v69, v93
	global_store_dword v160, v92, s[12:13]
	global_store_dword v160, v93, s[12:13] offset:256
	s_add_u32 s12, s12, s18
	s_addc_u32 s13, s13, 0
	v_mul_f32_e32 v94, v76, v94
	v_mul_f32_e32 v180, 0x3f3504f3, v94
	v_fma_f32 v182, |v180|, s16, v177
	v_fma_f32 v182, |v180|, v182, s19
	v_fma_f32 v182, |v180|, v182, s50
	v_fma_f32 v182, |v180|, v182, s51
	v_fma_f32 v182, |v180|, v182, s64
	v_fma_f32 v182, |v180|, v182, s65
	v_fma_f32 v182, |v180|, v182, |v180|
	v_mul_f32_e32 v184, 0xbfb8aa3b, v182
	v_fma_f32 v185, v182, s98, -v184
	v_rndne_f32_e32 v186, v184
	v_fmac_f32_e32 v185, 0xb2a5705f, v182
	v_sub_f32_e32 v184, v184, v186
	v_add_f32_e32 v184, v184, v185
	v_cvt_i32_f32_e32 v185, v186
	v_exp_f32_e32 v184, v184
	v_cmp_nlt_f32_e32 vcc, s70, v182
	v_ldexp_f32 v184, v184, v185
	s_nop 0
	v_cndmask_b32_e32 v184, 0, v184, vcc
	v_cmp_ngt_f32_e32 vcc, s71, v182
	s_nop 1
	v_cndmask_b32_e32 v184, v178, v184, vcc
	v_sub_f32_e32 v184, 1.0, v184
	v_mul_f32_e32 v183, v180, v180
	v_fmamk_f32 v185, v183, 0xba1345e1, v176
	v_fmaak_f32 v185, v183, v185, 0xbcdac9b8
	v_fmaak_f32 v185, v183, v185, 0x3de703be
	v_fmaak_f32 v185, v183, v185, 0xbec09330
	v_fmaak_f32 v183, v183, v185, 0x3e0375d0
	v_fma_f32 v183, |v180|, v183, |v180|
	v_cmp_nlt_f32_e64 vcc, |v180|, 1.0
	s_nop 1
	v_cndmask_b32_e32 v184, v183, v184, vcc
	v_bfi_b32 v184, s14, v184, v180
	v_add_f32_e32 v184, 1.0, v184
	v_mul_f32_e32 v94, 0.5, v94
	v_mul_f32_e32 v74, v74, v78
	v_mul_f32_e32 v94, v94, v184
	v_mul_f32_e32 v94, v74, v94
	v_mul_f32_e32 v95, v77, v95
	v_mul_f32_e32 v180, 0x3f3504f3, v95
	v_fma_f32 v182, |v180|, s16, v177
	v_fma_f32 v182, |v180|, v182, s19
	v_fma_f32 v182, |v180|, v182, s50
	v_fma_f32 v182, |v180|, v182, s51
	v_fma_f32 v182, |v180|, v182, s64
	v_fma_f32 v182, |v180|, v182, s65
	v_fma_f32 v182, |v180|, v182, |v180|
	v_mul_f32_e32 v184, 0xbfb8aa3b, v182
	v_fma_f32 v185, v182, s98, -v184
	v_rndne_f32_e32 v186, v184
	v_fmac_f32_e32 v185, 0xb2a5705f, v182
	v_sub_f32_e32 v184, v184, v186
	v_add_f32_e32 v184, v184, v185
	v_cvt_i32_f32_e32 v185, v186
	v_exp_f32_e32 v184, v184
	v_cmp_nlt_f32_e32 vcc, s70, v182
	v_ldexp_f32 v184, v184, v185
	s_nop 0
	v_cndmask_b32_e32 v184, 0, v184, vcc
	v_cmp_ngt_f32_e32 vcc, s71, v182
	s_nop 1
	v_cndmask_b32_e32 v184, v178, v184, vcc
	v_sub_f32_e32 v184, 1.0, v184
	v_mul_f32_e32 v183, v180, v180
	v_fmamk_f32 v185, v183, 0xba1345e1, v176
	v_fmaak_f32 v185, v183, v185, 0xbcdac9b8
	v_fmaak_f32 v185, v183, v185, 0x3de703be
	v_fmaak_f32 v185, v183, v185, 0xbec09330
	v_fmaak_f32 v183, v183, v185, 0x3e0375d0
	v_fma_f32 v183, |v180|, v183, |v180|
	v_cmp_nlt_f32_e64 vcc, |v180|, 1.0
	s_nop 1
	v_cndmask_b32_e32 v184, v183, v184, vcc
	v_bfi_b32 v184, s14, v184, v180
	v_add_f32_e32 v184, 1.0, v184
	v_mul_f32_e32 v95, 0.5, v95
	v_mul_f32_e32 v75, v75, v79
	v_mul_f32_e32 v95, v95, v184
	v_mul_f32_e32 v95, v75, v95
	global_store_dword v160, v94, s[12:13]
	global_store_dword v160, v95, s[12:13] offset:256
	s_add_u32 s12, s12, s18
	s_addc_u32 s13, s13, 0
	s_lshl_b32 s17, s92, 6
	s_add_u32 s69, s69, s17
	s_cmpk_lt_u32 s69, 0x8000
	s_cbranch_scc1 .Lgu0_chunk
	s_branch .LBB0_578

.Lgu1_start:
	s_mov_b64 exec, -1
	v_and_b32_e32 v171, 63, v205
	v_lshrrev_b32_e32 v172, 6, v205
	v_lshlrev_b32_e32 v160, 2, v171
	v_readfirstlane_b32 s34, v172
	v_and_b32_e32 v172, 7, v171
	v_lshlrev_b32_e32 v163, 6, v172
	v_mul_u32_u24_e32 v164, 24, v172
	s_nop 3
	s_lshl_b32 s13, s34, 14
	s_add_i32 s35, s93, s34
	v_lshrrev_b32_e32 v172, 3, v171
	v_lshl_add_u32 v162, v172, 2, s13
	v_add_u32_e32 v161, 0x2000, v162
	v_lshl_add_u32 v173, v171, 4, s13
	v_add_u32_e32 v175, s13, v160
	v_add_u32_e32 v174, 0x2000, v175
.Lgu1_chunk:
	s_movk_i32 s18, 0xc0
	s_lshl_b32 s19, s92, 13
	s_mov_b32 s10, 0x01010101
	s_mov_b32 s11, 0x01010101
	s_add_u32 s6, s26, 0xd800000
	s_addc_u32 s7, s27, 0
	s_lshl_b32 s13, s35, 9
	s_add_u32 s6, s6, s13
	s_addc_u32 s7, s7, 0
	s_lshl_b32 s14, s92, 11
	global_load_dword v16, v160, s[6:7]
	global_load_dword v17, v160, s[6:7] offset:256
	s_add_u32 s6, s6, s14
	s_addc_u32 s7, s7, 0
	global_load_dword v18, v160, s[6:7]
	global_load_dword v19, v160, s[6:7] offset:256
	s_add_u32 s6, s6, s14
	s_addc_u32 s7, s7, 0
	global_load_dword v20, v160, s[6:7]
	global_load_dword v21, v160, s[6:7] offset:256
	s_add_u32 s6, s6, s14
	s_addc_u32 s7, s7, 0
	global_load_dword v22, v160, s[6:7]
	global_load_dword v23, v160, s[6:7] offset:256
	s_add_u32 s6, s6, s14
	s_addc_u32 s7, s7, 0
	global_load_dword v24, v160, s[6:7]
	global_load_dword v25, v160, s[6:7] offset:256
	s_add_u32 s6, s6, s14
	s_addc_u32 s7, s7, 0
	global_load_dword v26, v160, s[6:7]
	global_load_dword v27, v160, s[6:7] offset:256
	s_add_u32 s6, s6, s14
	s_addc_u32 s7, s7, 0
	global_load_dword v28, v160, s[6:7]
	global_load_dword v29, v160, s[6:7] offset:256
	s_add_u32 s6, s6, s14
	s_addc_u32 s7, s7, 0
	global_load_dword v30, v160, s[6:7]
	global_load_dword v31, v160, s[6:7] offset:256
	s_add_u32 s6, s6, s14
	s_addc_u32 s7, s7, 0
	global_load_dword v32, v160, s[6:7]
	global_load_dword v33, v160, s[6:7] offset:256
	s_add_u32 s6, s6, s14
	s_addc_u32 s7, s7, 0
	global_load_dword v34, v160, s[6:7]
	global_load_dword v35, v160, s[6:7] offset:256
	s_add_u32 s6, s6, s14
	s_addc_u32 s7, s7, 0
	global_load_dword v36, v160, s[6:7]
	global_load_dword v37, v160, s[6:7] offset:256
	s_add_u32 s6, s6, s14
	s_addc_u32 s7, s7, 0
	global_load_dword v38, v160, s[6:7]
	global_load_dword v39, v160, s[6:7] offset:256
	s_add_u32 s6, s6, s14
	s_addc_u32 s7, s7, 0
	global_load_dword v40, v160, s[6:7]
	global_load_dword v41, v160, s[6:7] offset:256
	s_add_u32 s6, s6, s14
	s_addc_u32 s7, s7, 0
	global_load_dword v42, v160, s[6:7]
	global_load_dword v43, v160, s[6:7] offset:256
	s_add_u32 s6, s6, s14
	s_addc_u32 s7, s7, 0
	global_load_dword v44, v160, s[6:7]
	global_load_dword v45, v160, s[6:7] offset:256
	s_add_u32 s6, s6, s14
	s_addc_u32 s7, s7, 0
	global_load_dword v46, v160, s[6:7]
	global_load_dword v47, v160, s[6:7] offset:256
	s_add_u32 s6, s6, s14
	s_addc_u32 s7, s7, 0
	v_mov_b32_e32 v0, 0
	v_mov_b32_e32 v1, 0
	v_mov_b32_e32 v2, 0
	v_mov_b32_e32 v3, 0
	ds_write_b128 v173, v[0:3] offset:0
	ds_write_b128 v173, v[0:3] offset:1024
	ds_write_b128 v173, v[0:3] offset:2048
	ds_write_b128 v173, v[0:3] offset:3072
	ds_write_b128 v173, v[0:3] offset:4096
	ds_write_b128 v173, v[0:3] offset:5120
	ds_write_b128 v173, v[0:3] offset:6144
	ds_write_b128 v173, v[0:3] offset:7168
	s_waitcnt vmcnt(0)
	ds_write2st64_b32 v174, v16, v17 offset0:0 offset1:1
	ds_write2st64_b32 v174, v18, v19 offset0:2 offset1:3
	ds_write2st64_b32 v174, v20, v21 offset0:4 offset1:5
	ds_write2st64_b32 v174, v22, v23 offset0:6 offset1:7
	ds_write2st64_b32 v174, v24, v25 offset0:8 offset1:9
	ds_write2st64_b32 v174, v26, v27 offset0:10 offset1:11
	ds_write2st64_b32 v174, v28, v29 offset0:12 offset1:13
	ds_write2st64_b32 v174, v30, v31 offset0:14 offset1:15
	ds_write2st64_b32 v174, v32, v33 offset0:16 offset1:17
	ds_write2st64_b32 v174, v34, v35 offset0:18 offset1:19
	ds_write2st64_b32 v174, v36, v37 offset0:20 offset1:21
	ds_write2st64_b32 v174, v38, v39 offset0:22 offset1:23
	ds_write2st64_b32 v174, v40, v41 offset0:24 offset1:25
	ds_write2st64_b32 v174, v42, v43 offset0:26 offset1:27
	ds_write2st64_b32 v174, v44, v45 offset0:28 offset1:29
	ds_write2st64_b32 v174, v46, v47 offset0:30 offset1:31
	s_waitcnt lgkmcnt(0)
	s_add_u32 s0, s26, 0x2800000
	s_addc_u32 s1, s27, 0
	s_add_u32 s4, s26, 0x5800000
	s_addc_u32 s5, s27, 0
	s_lshl_b32 s13, s35, 11
	s_add_u32 s4, s4, s13
	s_addc_u32 s5, s5, 0
	s_mov_b32 s12, 0
	s_and_b32 s15, s12, 15
	s_lshr_b32 s16, s12, 4
	s_lshl_b32 s17, s15, 9
	s_mul_i32 s13, s15, s19
	s_lshl_b32 s14, s16, 9
	s_add_u32 s13, s13, s14
	s_add_u32 s6, s4, s13
	s_addc_u32 s7, s5, 0
	s_mul_i32 s13, s16, 0x300000
	s_add_u32 s0, s26, 0x2800000
	s_addc_u32 s1, s27, 0
	s_add_u32 s0, s0, s13
	s_addc_u32 s1, s1, 0
	v_mov_b32_e32 v165, v164
	v_add_u32_e32 v167, s17, v161
	v_add_u32_e32 v169, s17, v162
	global_load_dwordx4 v[112:115], v163, s[6:7]
	global_load_dwordx4 v[116:119], v163, s[6:7] offset:16
	global_load_dwordx4 v[120:123], v163, s[6:7] offset:32
	global_load_dwordx4 v[124:127], v163, s[6:7] offset:48
	ds_read2_b32 v[144:145], v167 offset0:0 offset1:8
	ds_read2_b32 v[146:147], v167 offset0:16 offset1:24
	ds_read2_b32 v[148:149], v167 offset0:32 offset1:40
	ds_read2_b32 v[150:151], v167 offset0:48 offset1:56
	s_waitcnt lgkmcnt(0)
	v_mad_u32_u24 v144, v144, s18, v165
	v_mad_u32_u24 v145, v145, s18, v165
	v_mad_u32_u24 v146, v146, s18, v165
	v_mad_u32_u24 v147, v147, s18, v165
	v_mad_u32_u24 v148, v148, s18, v165
	v_mad_u32_u24 v149, v149, s18, v165
	v_mad_u32_u24 v150, v150, s18, v165
	v_mad_u32_u24 v151, v151, s18, v165
	global_load_dwordx4 v[16:19], v144, s[0:1]
	global_load_dwordx2 v[20:21], v144, s[0:1] offset:16
	global_load_dwordx4 v[22:25], v145, s[0:1]
	global_load_dwordx2 v[26:27], v145, s[0:1] offset:16
	global_load_dwordx4 v[28:31], v146, s[0:1]
	global_load_dwordx2 v[32:33], v146, s[0:1] offset:16
	global_load_dwordx4 v[34:37], v147, s[0:1]
	global_load_dwordx2 v[38:39], v147, s[0:1] offset:16
	global_load_dwordx4 v[40:43], v148, s[0:1]
	global_load_dwordx2 v[44:45], v148, s[0:1] offset:16
	global_load_dwordx4 v[46:49], v149, s[0:1]
	global_load_dwordx2 v[50:51], v149, s[0:1] offset:16
	global_load_dwordx4 v[52:55], v150, s[0:1]
	global_load_dwordx2 v[56:57], v150, s[0:1] offset:16
	global_load_dwordx4 v[58:61], v151, s[0:1]
	global_load_dwordx2 v[62:63], v151, s[0:1] offset:16
.Lgu1_loop:
	ds_read2_b32 v[144:145], v167 offset0:64 offset1:72
	ds_read2_b32 v[146:147], v167 offset0:80 offset1:88
	ds_read2_b32 v[148:149], v167 offset0:96 offset1:104
	ds_read2_b32 v[150:151], v167 offset0:112 offset1:120
	s_waitcnt lgkmcnt(0)
	v_mad_u32_u24 v144, v144, s18, v165
	v_mad_u32_u24 v145, v145, s18, v165
	v_mad_u32_u24 v146, v146, s18, v165
	v_mad_u32_u24 v147, v147, s18, v165
	v_mad_u32_u24 v148, v148, s18, v165
	v_mad_u32_u24 v149, v149, s18, v165
	v_mad_u32_u24 v150, v150, s18, v165
	v_mad_u32_u24 v151, v151, s18, v165
	global_load_dwordx4 v[64:67], v144, s[0:1]
	global_load_dwordx2 v[68:69], v144, s[0:1] offset:16
	global_load_dwordx4 v[70:73], v145, s[0:1]
	global_load_dwordx2 v[74:75], v145, s[0:1] offset:16
	global_load_dwordx4 v[76:79], v146, s[0:1]
	global_load_dwordx2 v[80:81], v146, s[0:1] offset:16
	global_load_dwordx4 v[82:85], v147, s[0:1]
	global_load_dwordx2 v[86:87], v147, s[0:1] offset:16
	global_load_dwordx4 v[88:91], v148, s[0:1]
	global_load_dwordx2 v[92:93], v148, s[0:1] offset:16
	global_load_dwordx4 v[94:97], v149, s[0:1]
	global_load_dwordx2 v[98:99], v149, s[0:1] offset:16
	global_load_dwordx4 v[100:103], v150, s[0:1]
	global_load_dwordx2 v[104:105], v150, s[0:1] offset:16
	global_load_dwordx4 v[106:109], v151, s[0:1]
	global_load_dwordx2 v[110:111], v151, s[0:1] offset:16
	v_mov_b32_e32 v152, 0
	v_mov_b32_e32 v153, 0
	v_mov_b32_e32 v154, 0
	v_mov_b32_e32 v155, 0
	s_waitcnt vmcnt(30)
	v_cvt_scalef32_pk32_bf16_fp6 v[0:15], v[16:21], 1.0
	v_dot2c_f32_bf16_e32 v152, v0, v112
	v_dot2c_f32_bf16_e32 v153, v1, v113
	v_dot2c_f32_bf16_e32 v154, v2, v114
	v_dot2c_f32_bf16_e32 v155, v3, v115
	v_dot2c_f32_bf16_e32 v152, v4, v116
	v_dot2c_f32_bf16_e32 v153, v5, v117
	v_dot2c_f32_bf16_e32 v154, v6, v118
	v_dot2c_f32_bf16_e32 v155, v7, v119
	v_dot2c_f32_bf16_e32 v152, v8, v120
	v_dot2c_f32_bf16_e32 v153, v9, v121
	v_dot2c_f32_bf16_e32 v154, v10, v122
	v_dot2c_f32_bf16_e32 v155, v11, v123
	v_dot2c_f32_bf16_e32 v152, v12, v124
	v_dot2c_f32_bf16_e32 v153, v13, v125
	v_dot2c_f32_bf16_e32 v154, v14, v126
	v_dot2c_f32_bf16_e32 v155, v15, v127
	s_nop 0
	v_add_f32_e32 v156, v152, v153
	s_nop 0
	v_add_f32_e32 v157, v154, v155
	v_add_f32_e32 v158, v156, v157
	s_nop 1
	v_add_f32_dpp v158, v158, v158 quad_perm:[1,0,3,2] row_mask:0xf bank_mask:0xf
	s_nop 1
	v_add_f32_dpp v158, v158, v158 quad_perm:[2,3,0,1] row_mask:0xf bank_mask:0xf
	s_nop 1
	v_add_f32_dpp v158, v158, v158 row_half_mirror row_mask:0xf bank_mask:0xf
	s_mov_b64 exec, s[10:11]
	ds_add_f32 v169, v158 offset:0
	s_mov_b64 exec, -1
	v_mov_b32_e32 v152, 0
	v_mov_b32_e32 v153, 0
	v_mov_b32_e32 v154, 0
	v_mov_b32_e32 v155, 0
	s_waitcnt vmcnt(28)
	v_cvt_scalef32_pk32_bf16_fp6 v[0:15], v[22:27], 1.0
	v_dot2c_f32_bf16_e32 v152, v0, v112
	v_dot2c_f32_bf16_e32 v153, v1, v113
	v_dot2c_f32_bf16_e32 v154, v2, v114
	v_dot2c_f32_bf16_e32 v155, v3, v115
	v_dot2c_f32_bf16_e32 v152, v4, v116
	v_dot2c_f32_bf16_e32 v153, v5, v117
	v_dot2c_f32_bf16_e32 v154, v6, v118
	v_dot2c_f32_bf16_e32 v155, v7, v119
	v_dot2c_f32_bf16_e32 v152, v8, v120
	v_dot2c_f32_bf16_e32 v153, v9, v121
	v_dot2c_f32_bf16_e32 v154, v10, v122
	v_dot2c_f32_bf16_e32 v155, v11, v123
	v_dot2c_f32_bf16_e32 v152, v12, v124
	v_dot2c_f32_bf16_e32 v153, v13, v125
	v_dot2c_f32_bf16_e32 v154, v14, v126
	v_dot2c_f32_bf16_e32 v155, v15, v127
	s_nop 0
	v_add_f32_e32 v156, v152, v153
	s_nop 0
	v_add_f32_e32 v157, v154, v155
	v_add_f32_e32 v158, v156, v157
	s_nop 1
	v_add_f32_dpp v158, v158, v158 quad_perm:[1,0,3,2] row_mask:0xf bank_mask:0xf
	s_nop 1
	v_add_f32_dpp v158, v158, v158 quad_perm:[2,3,0,1] row_mask:0xf bank_mask:0xf
	s_nop 1
	v_add_f32_dpp v158, v158, v158 row_half_mirror row_mask:0xf bank_mask:0xf
	s_mov_b64 exec, s[10:11]
	ds_add_f32 v169, v158 offset:32
	s_mov_b64 exec, -1
	v_mov_b32_e32 v152, 0
	v_mov_b32_e32 v153, 0
	v_mov_b32_e32 v154, 0
	v_mov_b32_e32 v155, 0
	s_waitcnt vmcnt(26)
	v_cvt_scalef32_pk32_bf16_fp6 v[0:15], v[28:33], 1.0
	v_dot2c_f32_bf16_e32 v152, v0, v112
	v_dot2c_f32_bf16_e32 v153, v1, v113
	v_dot2c_f32_bf16_e32 v154, v2, v114
	v_dot2c_f32_bf16_e32 v155, v3, v115
	v_dot2c_f32_bf16_e32 v152, v4, v116
	v_dot2c_f32_bf16_e32 v153, v5, v117
	v_dot2c_f32_bf16_e32 v154, v6, v118
	v_dot2c_f32_bf16_e32 v155, v7, v119
	v_dot2c_f32_bf16_e32 v152, v8, v120
	v_dot2c_f32_bf16_e32 v153, v9, v121
	v_dot2c_f32_bf16_e32 v154, v10, v122
	v_dot2c_f32_bf16_e32 v155, v11, v123
	v_dot2c_f32_bf16_e32 v152, v12, v124
	v_dot2c_f32_bf16_e32 v153, v13, v125
	v_dot2c_f32_bf16_e32 v154, v14, v126
	v_dot2c_f32_bf16_e32 v155, v15, v127
	s_nop 0
	v_add_f32_e32 v156, v152, v153
	s_nop 0
	v_add_f32_e32 v157, v154, v155
	v_add_f32_e32 v158, v156, v157
	s_nop 1
	v_add_f32_dpp v158, v158, v158 quad_perm:[1,0,3,2] row_mask:0xf bank_mask:0xf
	s_nop 1
	v_add_f32_dpp v158, v158, v158 quad_perm:[2,3,0,1] row_mask:0xf bank_mask:0xf
	s_nop 1
	v_add_f32_dpp v158, v158, v158 row_half_mirror row_mask:0xf bank_mask:0xf
	s_mov_b64 exec, s[10:11]
	ds_add_f32 v169, v158 offset:64
	s_mov_b64 exec, -1
	v_mov_b32_e32 v152, 0
	v_mov_b32_e32 v153, 0
	v_mov_b32_e32 v154, 0
	v_mov_b32_e32 v155, 0
	s_waitcnt vmcnt(24)
	v_cvt_scalef32_pk32_bf16_fp6 v[0:15], v[34:39], 1.0
	v_dot2c_f32_bf16_e32 v152, v0, v112
	v_dot2c_f32_bf16_e32 v153, v1, v113
	v_dot2c_f32_bf16_e32 v154, v2, v114
	v_dot2c_f32_bf16_e32 v155, v3, v115
	v_dot2c_f32_bf16_e32 v152, v4, v116
	v_dot2c_f32_bf16_e32 v153, v5, v117
	v_dot2c_f32_bf16_e32 v154, v6, v118
	v_dot2c_f32_bf16_e32 v155, v7, v119
	v_dot2c_f32_bf16_e32 v152, v8, v120
	v_dot2c_f32_bf16_e32 v153, v9, v121
	v_dot2c_f32_bf16_e32 v154, v10, v122
	v_dot2c_f32_bf16_e32 v155, v11, v123
	v_dot2c_f32_bf16_e32 v152, v12, v124
	v_dot2c_f32_bf16_e32 v153, v13, v125
	v_dot2c_f32_bf16_e32 v154, v14, v126
	v_dot2c_f32_bf16_e32 v155, v15, v127
	s_nop 0
	v_add_f32_e32 v156, v152, v153
	s_nop 0
	v_add_f32_e32 v157, v154, v155
	v_add_f32_e32 v158, v156, v157
	s_nop 1
	v_add_f32_dpp v158, v158, v158 quad_perm:[1,0,3,2] row_mask:0xf bank_mask:0xf
	s_nop 1
	v_add_f32_dpp v158, v158, v158 quad_perm:[2,3,0,1] row_mask:0xf bank_mask:0xf
	s_nop 1
	v_add_f32_dpp v158, v158, v158 row_half_mirror row_mask:0xf bank_mask:0xf
	s_mov_b64 exec, s[10:11]
	ds_add_f32 v169, v158 offset:96
	s_mov_b64 exec, -1
	v_mov_b32_e32 v152, 0
	v_mov_b32_e32 v153, 0
	v_mov_b32_e32 v154, 0
	v_mov_b32_e32 v155, 0
	s_waitcnt vmcnt(22)
	v_cvt_scalef32_pk32_bf16_fp6 v[0:15], v[40:45], 1.0
	v_dot2c_f32_bf16_e32 v152, v0, v112
	v_dot2c_f32_bf16_e32 v153, v1, v113
	v_dot2c_f32_bf16_e32 v154, v2, v114
	v_dot2c_f32_bf16_e32 v155, v3, v115
	v_dot2c_f32_bf16_e32 v152, v4, v116
	v_dot2c_f32_bf16_e32 v153, v5, v117
	v_dot2c_f32_bf16_e32 v154, v6, v118
	v_dot2c_f32_bf16_e32 v155, v7, v119
	v_dot2c_f32_bf16_e32 v152, v8, v120
	v_dot2c_f32_bf16_e32 v153, v9, v121
	v_dot2c_f32_bf16_e32 v154, v10, v122
	v_dot2c_f32_bf16_e32 v155, v11, v123
	v_dot2c_f32_bf16_e32 v152, v12, v124
	v_dot2c_f32_bf16_e32 v153, v13, v125
	v_dot2c_f32_bf16_e32 v154, v14, v126
	v_dot2c_f32_bf16_e32 v155, v15, v127
	s_nop 0
	v_add_f32_e32 v156, v152, v153
	s_nop 0
	v_add_f32_e32 v157, v154, v155
	v_add_f32_e32 v158, v156, v157
	s_nop 1
	v_add_f32_dpp v158, v158, v158 quad_perm:[1,0,3,2] row_mask:0xf bank_mask:0xf
	s_nop 1
	v_add_f32_dpp v158, v158, v158 quad_perm:[2,3,0,1] row_mask:0xf bank_mask:0xf
	s_nop 1
	v_add_f32_dpp v158, v158, v158 row_half_mirror row_mask:0xf bank_mask:0xf
	s_mov_b64 exec, s[10:11]
	ds_add_f32 v169, v158 offset:128
	s_mov_b64 exec, -1
	v_mov_b32_e32 v152, 0
	v_mov_b32_e32 v153, 0
	v_mov_b32_e32 v154, 0
	v_mov_b32_e32 v155, 0
	s_waitcnt vmcnt(20)
	v_cvt_scalef32_pk32_bf16_fp6 v[0:15], v[46:51], 1.0
	v_dot2c_f32_bf16_e32 v152, v0, v112
	v_dot2c_f32_bf16_e32 v153, v1, v113
	v_dot2c_f32_bf16_e32 v154, v2, v114
	v_dot2c_f32_bf16_e32 v155, v3, v115
	v_dot2c_f32_bf16_e32 v152, v4, v116
	v_dot2c_f32_bf16_e32 v153, v5, v117
	v_dot2c_f32_bf16_e32 v154, v6, v118
	v_dot2c_f32_bf16_e32 v155, v7, v119
	v_dot2c_f32_bf16_e32 v152, v8, v120
	v_dot2c_f32_bf16_e32 v153, v9, v121
	v_dot2c_f32_bf16_e32 v154, v10, v122
	v_dot2c_f32_bf16_e32 v155, v11, v123
	v_dot2c_f32_bf16_e32 v152, v12, v124
	v_dot2c_f32_bf16_e32 v153, v13, v125
	v_dot2c_f32_bf16_e32 v154, v14, v126
	v_dot2c_f32_bf16_e32 v155, v15, v127
	s_nop 0
	v_add_f32_e32 v156, v152, v153
	s_nop 0
	v_add_f32_e32 v157, v154, v155
	v_add_f32_e32 v158, v156, v157
	s_nop 1
	v_add_f32_dpp v158, v158, v158 quad_perm:[1,0,3,2] row_mask:0xf bank_mask:0xf
	s_nop 1
	v_add_f32_dpp v158, v158, v158 quad_perm:[2,3,0,1] row_mask:0xf bank_mask:0xf
	s_nop 1
	v_add_f32_dpp v158, v158, v158 row_half_mirror row_mask:0xf bank_mask:0xf
	s_mov_b64 exec, s[10:11]
	ds_add_f32 v169, v158 offset:160
	s_mov_b64 exec, -1
	v_mov_b32_e32 v152, 0
	v_mov_b32_e32 v153, 0
	v_mov_b32_e32 v154, 0
	v_mov_b32_e32 v155, 0
	s_waitcnt vmcnt(18)
	v_cvt_scalef32_pk32_bf16_fp6 v[0:15], v[52:57], 1.0
	v_dot2c_f32_bf16_e32 v152, v0, v112
	v_dot2c_f32_bf16_e32 v153, v1, v113
	v_dot2c_f32_bf16_e32 v154, v2, v114
	v_dot2c_f32_bf16_e32 v155, v3, v115
	v_dot2c_f32_bf16_e32 v152, v4, v116
	v_dot2c_f32_bf16_e32 v153, v5, v117
	v_dot2c_f32_bf16_e32 v154, v6, v118
	v_dot2c_f32_bf16_e32 v155, v7, v119
	v_dot2c_f32_bf16_e32 v152, v8, v120
	v_dot2c_f32_bf16_e32 v153, v9, v121
	v_dot2c_f32_bf16_e32 v154, v10, v122
	v_dot2c_f32_bf16_e32 v155, v11, v123
	v_dot2c_f32_bf16_e32 v152, v12, v124
	v_dot2c_f32_bf16_e32 v153, v13, v125
	v_dot2c_f32_bf16_e32 v154, v14, v126
	v_dot2c_f32_bf16_e32 v155, v15, v127
	s_nop 0
	v_add_f32_e32 v156, v152, v153
	s_nop 0
	v_add_f32_e32 v157, v154, v155
	v_add_f32_e32 v158, v156, v157
	s_nop 1
	v_add_f32_dpp v158, v158, v158 quad_perm:[1,0,3,2] row_mask:0xf bank_mask:0xf
	s_nop 1
	v_add_f32_dpp v158, v158, v158 quad_perm:[2,3,0,1] row_mask:0xf bank_mask:0xf
	s_nop 1
	v_add_f32_dpp v158, v158, v158 row_half_mirror row_mask:0xf bank_mask:0xf
	s_mov_b64 exec, s[10:11]
	ds_add_f32 v169, v158 offset:192
	s_mov_b64 exec, -1
	v_mov_b32_e32 v152, 0
	v_mov_b32_e32 v153, 0
	v_mov_b32_e32 v154, 0
	v_mov_b32_e32 v155, 0
	s_waitcnt vmcnt(16)
	v_cvt_scalef32_pk32_bf16_fp6 v[0:15], v[58:63], 1.0
	v_dot2c_f32_bf16_e32 v152, v0, v112
	v_dot2c_f32_bf16_e32 v153, v1, v113
	v_dot2c_f32_bf16_e32 v154, v2, v114
	v_dot2c_f32_bf16_e32 v155, v3, v115
	v_dot2c_f32_bf16_e32 v152, v4, v116
	v_dot2c_f32_bf16_e32 v153, v5, v117
	v_dot2c_f32_bf16_e32 v154, v6, v118
	v_dot2c_f32_bf16_e32 v155, v7, v119
	v_dot2c_f32_bf16_e32 v152, v8, v120
	v_dot2c_f32_bf16_e32 v153, v9, v121
	v_dot2c_f32_bf16_e32 v154, v10, v122
	v_dot2c_f32_bf16_e32 v155, v11, v123
	v_dot2c_f32_bf16_e32 v152, v12, v124
	v_dot2c_f32_bf16_e32 v153, v13, v125
	v_dot2c_f32_bf16_e32 v154, v14, v126
	v_dot2c_f32_bf16_e32 v155, v15, v127
	s_nop 0
	v_add_f32_e32 v156, v152, v153
	s_nop 0
	v_add_f32_e32 v157, v154, v155
	v_add_f32_e32 v158, v156, v157
	s_nop 1
	v_add_f32_dpp v158, v158, v158 quad_perm:[1,0,3,2] row_mask:0xf bank_mask:0xf
	s_nop 1
	v_add_f32_dpp v158, v158, v158 quad_perm:[2,3,0,1] row_mask:0xf bank_mask:0xf
	s_nop 1
	v_add_f32_dpp v158, v158, v158 row_half_mirror row_mask:0xf bank_mask:0xf
	s_mov_b64 exec, s[10:11]
	ds_add_f32 v169, v158 offset:224
	s_mov_b64 exec, -1
	s_add_u32 s12, s12, 1
	s_and_b32 s15, s12, 15
	s_lshr_b32 s16, s12, 4
	s_lshl_b32 s17, s15, 9
	s_mul_i32 s13, s15, s19
	s_lshl_b32 s14, s16, 9
	s_add_u32 s13, s13, s14
	s_add_u32 s8, s4, s13
	s_addc_u32 s9, s5, 0
	s_mul_i32 s13, s16, 0x300000
	s_add_u32 s0, s26, 0x2800000
	s_addc_u32 s1, s27, 0
	s_add_u32 s0, s0, s13
	s_addc_u32 s1, s1, 0
	v_mov_b32_e32 v166, v164
	v_add_u32_e32 v168, s17, v161
	v_add_u32_e32 v170, s17, v162
	global_load_dwordx4 v[128:131], v163, s[8:9]
	global_load_dwordx4 v[132:135], v163, s[8:9] offset:16
	global_load_dwordx4 v[136:139], v163, s[8:9] offset:32
	global_load_dwordx4 v[140:143], v163, s[8:9] offset:48
	ds_read2_b32 v[144:145], v168 offset0:0 offset1:8
	ds_read2_b32 v[146:147], v168 offset0:16 offset1:24
	ds_read2_b32 v[148:149], v168 offset0:32 offset1:40
	ds_read2_b32 v[150:151], v168 offset0:48 offset1:56
	s_waitcnt lgkmcnt(0)
	v_mad_u32_u24 v144, v144, s18, v166
	v_mad_u32_u24 v145, v145, s18, v166
	v_mad_u32_u24 v146, v146, s18, v166
	v_mad_u32_u24 v147, v147, s18, v166
	v_mad_u32_u24 v148, v148, s18, v166
	v_mad_u32_u24 v149, v149, s18, v166
	v_mad_u32_u24 v150, v150, s18, v166
	v_mad_u32_u24 v151, v151, s18, v166
	global_load_dwordx4 v[16:19], v144, s[0:1]
	global_load_dwordx2 v[20:21], v144, s[0:1] offset:16
	global_load_dwordx4 v[22:25], v145, s[0:1]
	global_load_dwordx2 v[26:27], v145, s[0:1] offset:16
	global_load_dwordx4 v[28:31], v146, s[0:1]
	global_load_dwordx2 v[32:33], v146, s[0:1] offset:16
	global_load_dwordx4 v[34:37], v147, s[0:1]
	global_load_dwordx2 v[38:39], v147, s[0:1] offset:16
	global_load_dwordx4 v[40:43], v148, s[0:1]
	global_load_dwordx2 v[44:45], v148, s[0:1] offset:16
	global_load_dwordx4 v[46:49], v149, s[0:1]
	global_load_dwordx2 v[50:51], v149, s[0:1] offset:16
	global_load_dwordx4 v[52:55], v150, s[0:1]
	global_load_dwordx2 v[56:57], v150, s[0:1] offset:16
	global_load_dwordx4 v[58:61], v151, s[0:1]
	global_load_dwordx2 v[62:63], v151, s[0:1] offset:16
	v_mov_b32_e32 v152, 0
	v_mov_b32_e32 v153, 0
	v_mov_b32_e32 v154, 0
	v_mov_b32_e32 v155, 0
	s_waitcnt vmcnt(34)
	v_cvt_scalef32_pk32_bf16_fp6 v[0:15], v[64:69], 1.0
	v_dot2c_f32_bf16_e32 v152, v0, v112
	v_dot2c_f32_bf16_e32 v153, v1, v113
	v_dot2c_f32_bf16_e32 v154, v2, v114
	v_dot2c_f32_bf16_e32 v155, v3, v115
	v_dot2c_f32_bf16_e32 v152, v4, v116
	v_dot2c_f32_bf16_e32 v153, v5, v117
	v_dot2c_f32_bf16_e32 v154, v6, v118
	v_dot2c_f32_bf16_e32 v155, v7, v119
	v_dot2c_f32_bf16_e32 v152, v8, v120
	v_dot2c_f32_bf16_e32 v153, v9, v121
	v_dot2c_f32_bf16_e32 v154, v10, v122
	v_dot2c_f32_bf16_e32 v155, v11, v123
	v_dot2c_f32_bf16_e32 v152, v12, v124
	v_dot2c_f32_bf16_e32 v153, v13, v125
	v_dot2c_f32_bf16_e32 v154, v14, v126
	v_dot2c_f32_bf16_e32 v155, v15, v127
	s_nop 0
	v_add_f32_e32 v156, v152, v153
	s_nop 0
	v_add_f32_e32 v157, v154, v155
	v_add_f32_e32 v158, v156, v157
	s_nop 1
	v_add_f32_dpp v158, v158, v158 quad_perm:[1,0,3,2] row_mask:0xf bank_mask:0xf
	s_nop 1
	v_add_f32_dpp v158, v158, v158 quad_perm:[2,3,0,1] row_mask:0xf bank_mask:0xf
	s_nop 1
	v_add_f32_dpp v158, v158, v158 row_half_mirror row_mask:0xf bank_mask:0xf
	s_mov_b64 exec, s[10:11]
	ds_add_f32 v169, v158 offset:256
	s_mov_b64 exec, -1
	v_mov_b32_e32 v152, 0
	v_mov_b32_e32 v153, 0
	v_mov_b32_e32 v154, 0
	v_mov_b32_e32 v155, 0
	s_waitcnt vmcnt(32)
	v_cvt_scalef32_pk32_bf16_fp6 v[0:15], v[70:75], 1.0
	v_dot2c_f32_bf16_e32 v152, v0, v112
	v_dot2c_f32_bf16_e32 v153, v1, v113
	v_dot2c_f32_bf16_e32 v154, v2, v114
	v_dot2c_f32_bf16_e32 v155, v3, v115
	v_dot2c_f32_bf16_e32 v152, v4, v116
	v_dot2c_f32_bf16_e32 v153, v5, v117
	v_dot2c_f32_bf16_e32 v154, v6, v118
	v_dot2c_f32_bf16_e32 v155, v7, v119
	v_dot2c_f32_bf16_e32 v152, v8, v120
	v_dot2c_f32_bf16_e32 v153, v9, v121
	v_dot2c_f32_bf16_e32 v154, v10, v122
	v_dot2c_f32_bf16_e32 v155, v11, v123
	v_dot2c_f32_bf16_e32 v152, v12, v124
	v_dot2c_f32_bf16_e32 v153, v13, v125
	v_dot2c_f32_bf16_e32 v154, v14, v126
	v_dot2c_f32_bf16_e32 v155, v15, v127
	s_nop 0
	v_add_f32_e32 v156, v152, v153
	s_nop 0
	v_add_f32_e32 v157, v154, v155
	v_add_f32_e32 v158, v156, v157
	s_nop 1
	v_add_f32_dpp v158, v158, v158 quad_perm:[1,0,3,2] row_mask:0xf bank_mask:0xf
	s_nop 1
	v_add_f32_dpp v158, v158, v158 quad_perm:[2,3,0,1] row_mask:0xf bank_mask:0xf
	s_nop 1
	v_add_f32_dpp v158, v158, v158 row_half_mirror row_mask:0xf bank_mask:0xf
	s_mov_b64 exec, s[10:11]
	ds_add_f32 v169, v158 offset:288
	s_mov_b64 exec, -1
	v_mov_b32_e32 v152, 0
	v_mov_b32_e32 v153, 0
	v_mov_b32_e32 v154, 0
	v_mov_b32_e32 v155, 0
	s_waitcnt vmcnt(30)
	v_cvt_scalef32_pk32_bf16_fp6 v[0:15], v[76:81], 1.0
	v_dot2c_f32_bf16_e32 v152, v0, v112
	v_dot2c_f32_bf16_e32 v153, v1, v113
	v_dot2c_f32_bf16_e32 v154, v2, v114
	v_dot2c_f32_bf16_e32 v155, v3, v115
	v_dot2c_f32_bf16_e32 v152, v4, v116
	v_dot2c_f32_bf16_e32 v153, v5, v117
	v_dot2c_f32_bf16_e32 v154, v6, v118
	v_dot2c_f32_bf16_e32 v155, v7, v119
	v_dot2c_f32_bf16_e32 v152, v8, v120
	v_dot2c_f32_bf16_e32 v153, v9, v121
	v_dot2c_f32_bf16_e32 v154, v10, v122
	v_dot2c_f32_bf16_e32 v155, v11, v123
	v_dot2c_f32_bf16_e32 v152, v12, v124
	v_dot2c_f32_bf16_e32 v153, v13, v125
	v_dot2c_f32_bf16_e32 v154, v14, v126
	v_dot2c_f32_bf16_e32 v155, v15, v127
	s_nop 0
	v_add_f32_e32 v156, v152, v153
	s_nop 0
	v_add_f32_e32 v157, v154, v155
	v_add_f32_e32 v158, v156, v157
	s_nop 1
	v_add_f32_dpp v158, v158, v158 quad_perm:[1,0,3,2] row_mask:0xf bank_mask:0xf
	s_nop 1
	v_add_f32_dpp v158, v158, v158 quad_perm:[2,3,0,1] row_mask:0xf bank_mask:0xf
	s_nop 1
	v_add_f32_dpp v158, v158, v158 row_half_mirror row_mask:0xf bank_mask:0xf
	s_mov_b64 exec, s[10:11]
	ds_add_f32 v169, v158 offset:320
	s_mov_b64 exec, -1
	v_mov_b32_e32 v152, 0
	v_mov_b32_e32 v153, 0
	v_mov_b32_e32 v154, 0
	v_mov_b32_e32 v155, 0
	s_waitcnt vmcnt(28)
	v_cvt_scalef32_pk32_bf16_fp6 v[0:15], v[82:87], 1.0
	v_dot2c_f32_bf16_e32 v152, v0, v112
	v_dot2c_f32_bf16_e32 v153, v1, v113
	v_dot2c_f32_bf16_e32 v154, v2, v114
	v_dot2c_f32_bf16_e32 v155, v3, v115
	v_dot2c_f32_bf16_e32 v152, v4, v116
	v_dot2c_f32_bf16_e32 v153, v5, v117
	v_dot2c_f32_bf16_e32 v154, v6, v118
	v_dot2c_f32_bf16_e32 v155, v7, v119
	v_dot2c_f32_bf16_e32 v152, v8, v120
	v_dot2c_f32_bf16_e32 v153, v9, v121
	v_dot2c_f32_bf16_e32 v154, v10, v122
	v_dot2c_f32_bf16_e32 v155, v11, v123
	v_dot2c_f32_bf16_e32 v152, v12, v124
	v_dot2c_f32_bf16_e32 v153, v13, v125
	v_dot2c_f32_bf16_e32 v154, v14, v126
	v_dot2c_f32_bf16_e32 v155, v15, v127
	s_nop 0
	v_add_f32_e32 v156, v152, v153
	s_nop 0
	v_add_f32_e32 v157, v154, v155
	v_add_f32_e32 v158, v156, v157
	s_nop 1
	v_add_f32_dpp v158, v158, v158 quad_perm:[1,0,3,2] row_mask:0xf bank_mask:0xf
	s_nop 1
	v_add_f32_dpp v158, v158, v158 quad_perm:[2,3,0,1] row_mask:0xf bank_mask:0xf
	s_nop 1
	v_add_f32_dpp v158, v158, v158 row_half_mirror row_mask:0xf bank_mask:0xf
	s_mov_b64 exec, s[10:11]
	ds_add_f32 v169, v158 offset:352
	s_mov_b64 exec, -1
	v_mov_b32_e32 v152, 0
	v_mov_b32_e32 v153, 0
	v_mov_b32_e32 v154, 0
	v_mov_b32_e32 v155, 0
	s_waitcnt vmcnt(26)
	v_cvt_scalef32_pk32_bf16_fp6 v[0:15], v[88:93], 1.0
	v_dot2c_f32_bf16_e32 v152, v0, v112
	v_dot2c_f32_bf16_e32 v153, v1, v113
	v_dot2c_f32_bf16_e32 v154, v2, v114
	v_dot2c_f32_bf16_e32 v155, v3, v115
	v_dot2c_f32_bf16_e32 v152, v4, v116
	v_dot2c_f32_bf16_e32 v153, v5, v117
	v_dot2c_f32_bf16_e32 v154, v6, v118
	v_dot2c_f32_bf16_e32 v155, v7, v119
	v_dot2c_f32_bf16_e32 v152, v8, v120
	v_dot2c_f32_bf16_e32 v153, v9, v121
	v_dot2c_f32_bf16_e32 v154, v10, v122
	v_dot2c_f32_bf16_e32 v155, v11, v123
	v_dot2c_f32_bf16_e32 v152, v12, v124
	v_dot2c_f32_bf16_e32 v153, v13, v125
	v_dot2c_f32_bf16_e32 v154, v14, v126
	v_dot2c_f32_bf16_e32 v155, v15, v127
	s_nop 0
	v_add_f32_e32 v156, v152, v153
	s_nop 0
	v_add_f32_e32 v157, v154, v155
	v_add_f32_e32 v158, v156, v157
	s_nop 1
	v_add_f32_dpp v158, v158, v158 quad_perm:[1,0,3,2] row_mask:0xf bank_mask:0xf
	s_nop 1
	v_add_f32_dpp v158, v158, v158 quad_perm:[2,3,0,1] row_mask:0xf bank_mask:0xf
	s_nop 1
	v_add_f32_dpp v158, v158, v158 row_half_mirror row_mask:0xf bank_mask:0xf
	s_mov_b64 exec, s[10:11]
	ds_add_f32 v169, v158 offset:384
	s_mov_b64 exec, -1
	v_mov_b32_e32 v152, 0
	v_mov_b32_e32 v153, 0
	v_mov_b32_e32 v154, 0
	v_mov_b32_e32 v155, 0
	s_waitcnt vmcnt(24)
	v_cvt_scalef32_pk32_bf16_fp6 v[0:15], v[94:99], 1.0
	v_dot2c_f32_bf16_e32 v152, v0, v112
	v_dot2c_f32_bf16_e32 v153, v1, v113
	v_dot2c_f32_bf16_e32 v154, v2, v114
	v_dot2c_f32_bf16_e32 v155, v3, v115
	v_dot2c_f32_bf16_e32 v152, v4, v116
	v_dot2c_f32_bf16_e32 v153, v5, v117
	v_dot2c_f32_bf16_e32 v154, v6, v118
	v_dot2c_f32_bf16_e32 v155, v7, v119
	v_dot2c_f32_bf16_e32 v152, v8, v120
	v_dot2c_f32_bf16_e32 v153, v9, v121
	v_dot2c_f32_bf16_e32 v154, v10, v122
	v_dot2c_f32_bf16_e32 v155, v11, v123
	v_dot2c_f32_bf16_e32 v152, v12, v124
	v_dot2c_f32_bf16_e32 v153, v13, v125
	v_dot2c_f32_bf16_e32 v154, v14, v126
	v_dot2c_f32_bf16_e32 v155, v15, v127
	s_nop 0
	v_add_f32_e32 v156, v152, v153
	s_nop 0
	v_add_f32_e32 v157, v154, v155
	v_add_f32_e32 v158, v156, v157
	s_nop 1
	v_add_f32_dpp v158, v158, v158 quad_perm:[1,0,3,2] row_mask:0xf bank_mask:0xf
	s_nop 1
	v_add_f32_dpp v158, v158, v158 quad_perm:[2,3,0,1] row_mask:0xf bank_mask:0xf
	s_nop 1
	v_add_f32_dpp v158, v158, v158 row_half_mirror row_mask:0xf bank_mask:0xf
	s_mov_b64 exec, s[10:11]
	ds_add_f32 v169, v158 offset:416
	s_mov_b64 exec, -1
	v_mov_b32_e32 v152, 0
	v_mov_b32_e32 v153, 0
	v_mov_b32_e32 v154, 0
	v_mov_b32_e32 v155, 0
	s_waitcnt vmcnt(22)
	v_cvt_scalef32_pk32_bf16_fp6 v[0:15], v[100:105], 1.0
	v_dot2c_f32_bf16_e32 v152, v0, v112
	v_dot2c_f32_bf16_e32 v153, v1, v113
	v_dot2c_f32_bf16_e32 v154, v2, v114
	v_dot2c_f32_bf16_e32 v155, v3, v115
	v_dot2c_f32_bf16_e32 v152, v4, v116
	v_dot2c_f32_bf16_e32 v153, v5, v117
	v_dot2c_f32_bf16_e32 v154, v6, v118
	v_dot2c_f32_bf16_e32 v155, v7, v119
	v_dot2c_f32_bf16_e32 v152, v8, v120
	v_dot2c_f32_bf16_e32 v153, v9, v121
	v_dot2c_f32_bf16_e32 v154, v10, v122
	v_dot2c_f32_bf16_e32 v155, v11, v123
	v_dot2c_f32_bf16_e32 v152, v12, v124
	v_dot2c_f32_bf16_e32 v153, v13, v125
	v_dot2c_f32_bf16_e32 v154, v14, v126
	v_dot2c_f32_bf16_e32 v155, v15, v127
	s_nop 0
	v_add_f32_e32 v156, v152, v153
	s_nop 0
	v_add_f32_e32 v157, v154, v155
	v_add_f32_e32 v158, v156, v157
	s_nop 1
	v_add_f32_dpp v158, v158, v158 quad_perm:[1,0,3,2] row_mask:0xf bank_mask:0xf
	s_nop 1
	v_add_f32_dpp v158, v158, v158 quad_perm:[2,3,0,1] row_mask:0xf bank_mask:0xf
	s_nop 1
	v_add_f32_dpp v158, v158, v158 row_half_mirror row_mask:0xf bank_mask:0xf
	s_mov_b64 exec, s[10:11]
	ds_add_f32 v169, v158 offset:448
	s_mov_b64 exec, -1
	v_mov_b32_e32 v152, 0
	v_mov_b32_e32 v153, 0
	v_mov_b32_e32 v154, 0
	v_mov_b32_e32 v155, 0
	s_waitcnt vmcnt(20)
	v_cvt_scalef32_pk32_bf16_fp6 v[0:15], v[106:111], 1.0
	v_dot2c_f32_bf16_e32 v152, v0, v112
	v_dot2c_f32_bf16_e32 v153, v1, v113
	v_dot2c_f32_bf16_e32 v154, v2, v114
	v_dot2c_f32_bf16_e32 v155, v3, v115
	v_dot2c_f32_bf16_e32 v152, v4, v116
	v_dot2c_f32_bf16_e32 v153, v5, v117
	v_dot2c_f32_bf16_e32 v154, v6, v118
	v_dot2c_f32_bf16_e32 v155, v7, v119
	v_dot2c_f32_bf16_e32 v152, v8, v120
	v_dot2c_f32_bf16_e32 v153, v9, v121
	v_dot2c_f32_bf16_e32 v154, v10, v122
	v_dot2c_f32_bf16_e32 v155, v11, v123
	v_dot2c_f32_bf16_e32 v152, v12, v124
	v_dot2c_f32_bf16_e32 v153, v13, v125
	v_dot2c_f32_bf16_e32 v154, v14, v126
	v_dot2c_f32_bf16_e32 v155, v15, v127
	s_nop 0
	v_add_f32_e32 v156, v152, v153
	s_nop 0
	v_add_f32_e32 v157, v154, v155
	v_add_f32_e32 v158, v156, v157
	s_nop 1
	v_add_f32_dpp v158, v158, v158 quad_perm:[1,0,3,2] row_mask:0xf bank_mask:0xf
	s_nop 1
	v_add_f32_dpp v158, v158, v158 quad_perm:[2,3,0,1] row_mask:0xf bank_mask:0xf
	s_nop 1
	v_add_f32_dpp v158, v158, v158 row_half_mirror row_mask:0xf bank_mask:0xf
	s_mov_b64 exec, s[10:11]
	ds_add_f32 v169, v158 offset:480
	s_mov_b64 exec, -1
	ds_read2_b32 v[144:145], v168 offset0:64 offset1:72
	ds_read2_b32 v[146:147], v168 offset0:80 offset1:88
	ds_read2_b32 v[148:149], v168 offset0:96 offset1:104
	ds_read2_b32 v[150:151], v168 offset0:112 offset1:120
	s_waitcnt lgkmcnt(0)
	v_mad_u32_u24 v144, v144, s18, v166
	v_mad_u32_u24 v145, v145, s18, v166
	v_mad_u32_u24 v146, v146, s18, v166
	v_mad_u32_u24 v147, v147, s18, v166
	v_mad_u32_u24 v148, v148, s18, v166
	v_mad_u32_u24 v149, v149, s18, v166
	v_mad_u32_u24 v150, v150, s18, v166
	v_mad_u32_u24 v151, v151, s18, v166
	global_load_dwordx4 v[64:67], v144, s[0:1]
	global_load_dwordx2 v[68:69], v144, s[0:1] offset:16
	global_load_dwordx4 v[70:73], v145, s[0:1]
	global_load_dwordx2 v[74:75], v145, s[0:1] offset:16
	global_load_dwordx4 v[76:79], v146, s[0:1]
	global_load_dwordx2 v[80:81], v146, s[0:1] offset:16
	global_load_dwordx4 v[82:85], v147, s[0:1]
	global_load_dwordx2 v[86:87], v147, s[0:1] offset:16
	global_load_dwordx4 v[88:91], v148, s[0:1]
	global_load_dwordx2 v[92:93], v148, s[0:1] offset:16
	global_load_dwordx4 v[94:97], v149, s[0:1]
	global_load_dwordx2 v[98:99], v149, s[0:1] offset:16
	global_load_dwordx4 v[100:103], v150, s[0:1]
	global_load_dwordx2 v[104:105], v150, s[0:1] offset:16
	global_load_dwordx4 v[106:109], v151, s[0:1]
	global_load_dwordx2 v[110:111], v151, s[0:1] offset:16
	v_mov_b32_e32 v152, 0
	v_mov_b32_e32 v153, 0
	v_mov_b32_e32 v154, 0
	v_mov_b32_e32 v155, 0
	s_waitcnt vmcnt(30)
	v_cvt_scalef32_pk32_bf16_fp6 v[0:15], v[16:21], 1.0
	v_dot2c_f32_bf16_e32 v152, v0, v128
	v_dot2c_f32_bf16_e32 v153, v1, v129
	v_dot2c_f32_bf16_e32 v154, v2, v130
	v_dot2c_f32_bf16_e32 v155, v3, v131
	v_dot2c_f32_bf16_e32 v152, v4, v132
	v_dot2c_f32_bf16_e32 v153, v5, v133
	v_dot2c_f32_bf16_e32 v154, v6, v134
	v_dot2c_f32_bf16_e32 v155, v7, v135
	v_dot2c_f32_bf16_e32 v152, v8, v136
	v_dot2c_f32_bf16_e32 v153, v9, v137
	v_dot2c_f32_bf16_e32 v154, v10, v138
	v_dot2c_f32_bf16_e32 v155, v11, v139
	v_dot2c_f32_bf16_e32 v152, v12, v140
	v_dot2c_f32_bf16_e32 v153, v13, v141
	v_dot2c_f32_bf16_e32 v154, v14, v142
	v_dot2c_f32_bf16_e32 v155, v15, v143
	s_nop 0
	v_add_f32_e32 v156, v152, v153
	s_nop 0
	v_add_f32_e32 v157, v154, v155
	v_add_f32_e32 v158, v156, v157
	s_nop 1
	v_add_f32_dpp v158, v158, v158 quad_perm:[1,0,3,2] row_mask:0xf bank_mask:0xf
	s_nop 1
	v_add_f32_dpp v158, v158, v158 quad_perm:[2,3,0,1] row_mask:0xf bank_mask:0xf
	s_nop 1
	v_add_f32_dpp v158, v158, v158 row_half_mirror row_mask:0xf bank_mask:0xf
	s_mov_b64 exec, s[10:11]
	ds_add_f32 v170, v158 offset:0
	s_mov_b64 exec, -1
	v_mov_b32_e32 v152, 0
	v_mov_b32_e32 v153, 0
	v_mov_b32_e32 v154, 0
	v_mov_b32_e32 v155, 0
	s_waitcnt vmcnt(28)
	v_cvt_scalef32_pk32_bf16_fp6 v[0:15], v[22:27], 1.0
	v_dot2c_f32_bf16_e32 v152, v0, v128
	v_dot2c_f32_bf16_e32 v153, v1, v129
	v_dot2c_f32_bf16_e32 v154, v2, v130
	v_dot2c_f32_bf16_e32 v155, v3, v131
	v_dot2c_f32_bf16_e32 v152, v4, v132
	v_dot2c_f32_bf16_e32 v153, v5, v133
	v_dot2c_f32_bf16_e32 v154, v6, v134
	v_dot2c_f32_bf16_e32 v155, v7, v135
	v_dot2c_f32_bf16_e32 v152, v8, v136
	v_dot2c_f32_bf16_e32 v153, v9, v137
	v_dot2c_f32_bf16_e32 v154, v10, v138
	v_dot2c_f32_bf16_e32 v155, v11, v139
	v_dot2c_f32_bf16_e32 v152, v12, v140
	v_dot2c_f32_bf16_e32 v153, v13, v141
	v_dot2c_f32_bf16_e32 v154, v14, v142
	v_dot2c_f32_bf16_e32 v155, v15, v143
	s_nop 0
	v_add_f32_e32 v156, v152, v153
	s_nop 0
	v_add_f32_e32 v157, v154, v155
	v_add_f32_e32 v158, v156, v157
	s_nop 1
	v_add_f32_dpp v158, v158, v158 quad_perm:[1,0,3,2] row_mask:0xf bank_mask:0xf
	s_nop 1
	v_add_f32_dpp v158, v158, v158 quad_perm:[2,3,0,1] row_mask:0xf bank_mask:0xf
	s_nop 1
	v_add_f32_dpp v158, v158, v158 row_half_mirror row_mask:0xf bank_mask:0xf
	s_mov_b64 exec, s[10:11]
	ds_add_f32 v170, v158 offset:32
	s_mov_b64 exec, -1
	v_mov_b32_e32 v152, 0
	v_mov_b32_e32 v153, 0
	v_mov_b32_e32 v154, 0
	v_mov_b32_e32 v155, 0
	s_waitcnt vmcnt(26)
	v_cvt_scalef32_pk32_bf16_fp6 v[0:15], v[28:33], 1.0
	v_dot2c_f32_bf16_e32 v152, v0, v128
	v_dot2c_f32_bf16_e32 v153, v1, v129
	v_dot2c_f32_bf16_e32 v154, v2, v130
	v_dot2c_f32_bf16_e32 v155, v3, v131
	v_dot2c_f32_bf16_e32 v152, v4, v132
	v_dot2c_f32_bf16_e32 v153, v5, v133
	v_dot2c_f32_bf16_e32 v154, v6, v134
	v_dot2c_f32_bf16_e32 v155, v7, v135
	v_dot2c_f32_bf16_e32 v152, v8, v136
	v_dot2c_f32_bf16_e32 v153, v9, v137
	v_dot2c_f32_bf16_e32 v154, v10, v138
	v_dot2c_f32_bf16_e32 v155, v11, v139
	v_dot2c_f32_bf16_e32 v152, v12, v140
	v_dot2c_f32_bf16_e32 v153, v13, v141
	v_dot2c_f32_bf16_e32 v154, v14, v142
	v_dot2c_f32_bf16_e32 v155, v15, v143
	s_nop 0
	v_add_f32_e32 v156, v152, v153
	s_nop 0
	v_add_f32_e32 v157, v154, v155
	v_add_f32_e32 v158, v156, v157
	s_nop 1
	v_add_f32_dpp v158, v158, v158 quad_perm:[1,0,3,2] row_mask:0xf bank_mask:0xf
	s_nop 1
	v_add_f32_dpp v158, v158, v158 quad_perm:[2,3,0,1] row_mask:0xf bank_mask:0xf
	s_nop 1
	v_add_f32_dpp v158, v158, v158 row_half_mirror row_mask:0xf bank_mask:0xf
	s_mov_b64 exec, s[10:11]
	ds_add_f32 v170, v158 offset:64
	s_mov_b64 exec, -1
	v_mov_b32_e32 v152, 0
	v_mov_b32_e32 v153, 0
	v_mov_b32_e32 v154, 0
	v_mov_b32_e32 v155, 0
	s_waitcnt vmcnt(24)
	v_cvt_scalef32_pk32_bf16_fp6 v[0:15], v[34:39], 1.0
	v_dot2c_f32_bf16_e32 v152, v0, v128
	v_dot2c_f32_bf16_e32 v153, v1, v129
	v_dot2c_f32_bf16_e32 v154, v2, v130
	v_dot2c_f32_bf16_e32 v155, v3, v131
	v_dot2c_f32_bf16_e32 v152, v4, v132
	v_dot2c_f32_bf16_e32 v153, v5, v133
	v_dot2c_f32_bf16_e32 v154, v6, v134
	v_dot2c_f32_bf16_e32 v155, v7, v135
	v_dot2c_f32_bf16_e32 v152, v8, v136
	v_dot2c_f32_bf16_e32 v153, v9, v137
	v_dot2c_f32_bf16_e32 v154, v10, v138
	v_dot2c_f32_bf16_e32 v155, v11, v139
	v_dot2c_f32_bf16_e32 v152, v12, v140
	v_dot2c_f32_bf16_e32 v153, v13, v141
	v_dot2c_f32_bf16_e32 v154, v14, v142
	v_dot2c_f32_bf16_e32 v155, v15, v143
	s_nop 0
	v_add_f32_e32 v156, v152, v153
	s_nop 0
	v_add_f32_e32 v157, v154, v155
	v_add_f32_e32 v158, v156, v157
	s_nop 1
	v_add_f32_dpp v158, v158, v158 quad_perm:[1,0,3,2] row_mask:0xf bank_mask:0xf
	s_nop 1
	v_add_f32_dpp v158, v158, v158 quad_perm:[2,3,0,1] row_mask:0xf bank_mask:0xf
	s_nop 1
	v_add_f32_dpp v158, v158, v158 row_half_mirror row_mask:0xf bank_mask:0xf
	s_mov_b64 exec, s[10:11]
	ds_add_f32 v170, v158 offset:96
	s_mov_b64 exec, -1
	v_mov_b32_e32 v152, 0
	v_mov_b32_e32 v153, 0
	v_mov_b32_e32 v154, 0
	v_mov_b32_e32 v155, 0
	s_waitcnt vmcnt(22)
	v_cvt_scalef32_pk32_bf16_fp6 v[0:15], v[40:45], 1.0
	v_dot2c_f32_bf16_e32 v152, v0, v128
	v_dot2c_f32_bf16_e32 v153, v1, v129
	v_dot2c_f32_bf16_e32 v154, v2, v130
	v_dot2c_f32_bf16_e32 v155, v3, v131
	v_dot2c_f32_bf16_e32 v152, v4, v132
	v_dot2c_f32_bf16_e32 v153, v5, v133
	v_dot2c_f32_bf16_e32 v154, v6, v134
	v_dot2c_f32_bf16_e32 v155, v7, v135
	v_dot2c_f32_bf16_e32 v152, v8, v136
	v_dot2c_f32_bf16_e32 v153, v9, v137
	v_dot2c_f32_bf16_e32 v154, v10, v138
	v_dot2c_f32_bf16_e32 v155, v11, v139
	v_dot2c_f32_bf16_e32 v152, v12, v140
	v_dot2c_f32_bf16_e32 v153, v13, v141
	v_dot2c_f32_bf16_e32 v154, v14, v142
	v_dot2c_f32_bf16_e32 v155, v15, v143
	s_nop 0
	v_add_f32_e32 v156, v152, v153
	s_nop 0
	v_add_f32_e32 v157, v154, v155
	v_add_f32_e32 v158, v156, v157
	s_nop 1
	v_add_f32_dpp v158, v158, v158 quad_perm:[1,0,3,2] row_mask:0xf bank_mask:0xf
	s_nop 1
	v_add_f32_dpp v158, v158, v158 quad_perm:[2,3,0,1] row_mask:0xf bank_mask:0xf
	s_nop 1
	v_add_f32_dpp v158, v158, v158 row_half_mirror row_mask:0xf bank_mask:0xf
	s_mov_b64 exec, s[10:11]
	ds_add_f32 v170, v158 offset:128
	s_mov_b64 exec, -1
	v_mov_b32_e32 v152, 0
	v_mov_b32_e32 v153, 0
	v_mov_b32_e32 v154, 0
	v_mov_b32_e32 v155, 0
	s_waitcnt vmcnt(20)
	v_cvt_scalef32_pk32_bf16_fp6 v[0:15], v[46:51], 1.0
	v_dot2c_f32_bf16_e32 v152, v0, v128
	v_dot2c_f32_bf16_e32 v153, v1, v129
	v_dot2c_f32_bf16_e32 v154, v2, v130
	v_dot2c_f32_bf16_e32 v155, v3, v131
	v_dot2c_f32_bf16_e32 v152, v4, v132
	v_dot2c_f32_bf16_e32 v153, v5, v133
	v_dot2c_f32_bf16_e32 v154, v6, v134
	v_dot2c_f32_bf16_e32 v155, v7, v135
	v_dot2c_f32_bf16_e32 v152, v8, v136
	v_dot2c_f32_bf16_e32 v153, v9, v137
	v_dot2c_f32_bf16_e32 v154, v10, v138
	v_dot2c_f32_bf16_e32 v155, v11, v139
	v_dot2c_f32_bf16_e32 v152, v12, v140
	v_dot2c_f32_bf16_e32 v153, v13, v141
	v_dot2c_f32_bf16_e32 v154, v14, v142
	v_dot2c_f32_bf16_e32 v155, v15, v143
	s_nop 0
	v_add_f32_e32 v156, v152, v153
	s_nop 0
	v_add_f32_e32 v157, v154, v155
	v_add_f32_e32 v158, v156, v157
	s_nop 1
	v_add_f32_dpp v158, v158, v158 quad_perm:[1,0,3,2] row_mask:0xf bank_mask:0xf
	s_nop 1
	v_add_f32_dpp v158, v158, v158 quad_perm:[2,3,0,1] row_mask:0xf bank_mask:0xf
	s_nop 1
	v_add_f32_dpp v158, v158, v158 row_half_mirror row_mask:0xf bank_mask:0xf
	s_mov_b64 exec, s[10:11]
	ds_add_f32 v170, v158 offset:160
	s_mov_b64 exec, -1
	v_mov_b32_e32 v152, 0
	v_mov_b32_e32 v153, 0
	v_mov_b32_e32 v154, 0
	v_mov_b32_e32 v155, 0
	s_waitcnt vmcnt(18)
	v_cvt_scalef32_pk32_bf16_fp6 v[0:15], v[52:57], 1.0
	v_dot2c_f32_bf16_e32 v152, v0, v128
	v_dot2c_f32_bf16_e32 v153, v1, v129
	v_dot2c_f32_bf16_e32 v154, v2, v130
	v_dot2c_f32_bf16_e32 v155, v3, v131
	v_dot2c_f32_bf16_e32 v152, v4, v132
	v_dot2c_f32_bf16_e32 v153, v5, v133
	v_dot2c_f32_bf16_e32 v154, v6, v134
	v_dot2c_f32_bf16_e32 v155, v7, v135
	v_dot2c_f32_bf16_e32 v152, v8, v136
	v_dot2c_f32_bf16_e32 v153, v9, v137
	v_dot2c_f32_bf16_e32 v154, v10, v138
	v_dot2c_f32_bf16_e32 v155, v11, v139
	v_dot2c_f32_bf16_e32 v152, v12, v140
	v_dot2c_f32_bf16_e32 v153, v13, v141
	v_dot2c_f32_bf16_e32 v154, v14, v142
	v_dot2c_f32_bf16_e32 v155, v15, v143
	s_nop 0
	v_add_f32_e32 v156, v152, v153
	s_nop 0
	v_add_f32_e32 v157, v154, v155
	v_add_f32_e32 v158, v156, v157
	s_nop 1
	v_add_f32_dpp v158, v158, v158 quad_perm:[1,0,3,2] row_mask:0xf bank_mask:0xf
	s_nop 1
	v_add_f32_dpp v158, v158, v158 quad_perm:[2,3,0,1] row_mask:0xf bank_mask:0xf
	s_nop 1
	v_add_f32_dpp v158, v158, v158 row_half_mirror row_mask:0xf bank_mask:0xf
	s_mov_b64 exec, s[10:11]
	ds_add_f32 v170, v158 offset:192
	s_mov_b64 exec, -1
	v_mov_b32_e32 v152, 0
	v_mov_b32_e32 v153, 0
	v_mov_b32_e32 v154, 0
	v_mov_b32_e32 v155, 0
	s_waitcnt vmcnt(16)
	v_cvt_scalef32_pk32_bf16_fp6 v[0:15], v[58:63], 1.0
	v_dot2c_f32_bf16_e32 v152, v0, v128
	v_dot2c_f32_bf16_e32 v153, v1, v129
	v_dot2c_f32_bf16_e32 v154, v2, v130
	v_dot2c_f32_bf16_e32 v155, v3, v131
	v_dot2c_f32_bf16_e32 v152, v4, v132
	v_dot2c_f32_bf16_e32 v153, v5, v133
	v_dot2c_f32_bf16_e32 v154, v6, v134
	v_dot2c_f32_bf16_e32 v155, v7, v135
	v_dot2c_f32_bf16_e32 v152, v8, v136
	v_dot2c_f32_bf16_e32 v153, v9, v137
	v_dot2c_f32_bf16_e32 v154, v10, v138
	v_dot2c_f32_bf16_e32 v155, v11, v139
	v_dot2c_f32_bf16_e32 v152, v12, v140
	v_dot2c_f32_bf16_e32 v153, v13, v141
	v_dot2c_f32_bf16_e32 v154, v14, v142
	v_dot2c_f32_bf16_e32 v155, v15, v143
	s_nop 0
	v_add_f32_e32 v156, v152, v153
	s_nop 0
	v_add_f32_e32 v157, v154, v155
	v_add_f32_e32 v158, v156, v157
	s_nop 1
	v_add_f32_dpp v158, v158, v158 quad_perm:[1,0,3,2] row_mask:0xf bank_mask:0xf
	s_nop 1
	v_add_f32_dpp v158, v158, v158 quad_perm:[2,3,0,1] row_mask:0xf bank_mask:0xf
	s_nop 1
	v_add_f32_dpp v158, v158, v158 row_half_mirror row_mask:0xf bank_mask:0xf
	s_mov_b64 exec, s[10:11]
	ds_add_f32 v170, v158 offset:224
	s_mov_b64 exec, -1
	s_add_u32 s12, s12, 1
	s_and_b32 s12, s12, 63
	s_and_b32 s15, s12, 15
	s_lshr_b32 s16, s12, 4
	s_lshl_b32 s17, s15, 9
	s_mul_i32 s13, s15, s19
	s_lshl_b32 s14, s16, 9
	s_add_u32 s13, s13, s14
	s_add_u32 s6, s4, s13
	s_addc_u32 s7, s5, 0
	s_mul_i32 s13, s16, 0x300000
	s_add_u32 s0, s26, 0x2800000
	s_addc_u32 s1, s27, 0
	s_add_u32 s0, s0, s13
	s_addc_u32 s1, s1, 0
	v_mov_b32_e32 v165, v164
	v_add_u32_e32 v167, s17, v161
	v_add_u32_e32 v169, s17, v162
	global_load_dwordx4 v[112:115], v163, s[6:7]
	global_load_dwordx4 v[116:119], v163, s[6:7] offset:16
	global_load_dwordx4 v[120:123], v163, s[6:7] offset:32
	global_load_dwordx4 v[124:127], v163, s[6:7] offset:48
	ds_read2_b32 v[144:145], v167 offset0:0 offset1:8
	ds_read2_b32 v[146:147], v167 offset0:16 offset1:24
	ds_read2_b32 v[148:149], v167 offset0:32 offset1:40
	ds_read2_b32 v[150:151], v167 offset0:48 offset1:56
	s_waitcnt lgkmcnt(0)
	v_mad_u32_u24 v144, v144, s18, v165
	v_mad_u32_u24 v145, v145, s18, v165
	v_mad_u32_u24 v146, v146, s18, v165
	v_mad_u32_u24 v147, v147, s18, v165
	v_mad_u32_u24 v148, v148, s18, v165
	v_mad_u32_u24 v149, v149, s18, v165
	v_mad_u32_u24 v150, v150, s18, v165
	v_mad_u32_u24 v151, v151, s18, v165
	global_load_dwordx4 v[16:19], v144, s[0:1]
	global_load_dwordx2 v[20:21], v144, s[0:1] offset:16
	global_load_dwordx4 v[22:25], v145, s[0:1]
	global_load_dwordx2 v[26:27], v145, s[0:1] offset:16
	global_load_dwordx4 v[28:31], v146, s[0:1]
	global_load_dwordx2 v[32:33], v146, s[0:1] offset:16
	global_load_dwordx4 v[34:37], v147, s[0:1]
	global_load_dwordx2 v[38:39], v147, s[0:1] offset:16
	global_load_dwordx4 v[40:43], v148, s[0:1]
	global_load_dwordx2 v[44:45], v148, s[0:1] offset:16
	global_load_dwordx4 v[46:49], v149, s[0:1]
	global_load_dwordx2 v[50:51], v149, s[0:1] offset:16
	global_load_dwordx4 v[52:55], v150, s[0:1]
	global_load_dwordx2 v[56:57], v150, s[0:1] offset:16
	global_load_dwordx4 v[58:61], v151, s[0:1]
	global_load_dwordx2 v[62:63], v151, s[0:1] offset:16
	v_mov_b32_e32 v152, 0
	v_mov_b32_e32 v153, 0
	v_mov_b32_e32 v154, 0
	v_mov_b32_e32 v155, 0
	s_waitcnt vmcnt(34)
	v_cvt_scalef32_pk32_bf16_fp6 v[0:15], v[64:69], 1.0
	v_dot2c_f32_bf16_e32 v152, v0, v128
	v_dot2c_f32_bf16_e32 v153, v1, v129
	v_dot2c_f32_bf16_e32 v154, v2, v130
	v_dot2c_f32_bf16_e32 v155, v3, v131
	v_dot2c_f32_bf16_e32 v152, v4, v132
	v_dot2c_f32_bf16_e32 v153, v5, v133
	v_dot2c_f32_bf16_e32 v154, v6, v134
	v_dot2c_f32_bf16_e32 v155, v7, v135
	v_dot2c_f32_bf16_e32 v152, v8, v136
	v_dot2c_f32_bf16_e32 v153, v9, v137
	v_dot2c_f32_bf16_e32 v154, v10, v138
	v_dot2c_f32_bf16_e32 v155, v11, v139
	v_dot2c_f32_bf16_e32 v152, v12, v140
	v_dot2c_f32_bf16_e32 v153, v13, v141
	v_dot2c_f32_bf16_e32 v154, v14, v142
	v_dot2c_f32_bf16_e32 v155, v15, v143
	s_nop 0
	v_add_f32_e32 v156, v152, v153
	s_nop 0
	v_add_f32_e32 v157, v154, v155
	v_add_f32_e32 v158, v156, v157
	s_nop 1
	v_add_f32_dpp v158, v158, v158 quad_perm:[1,0,3,2] row_mask:0xf bank_mask:0xf
	s_nop 1
	v_add_f32_dpp v158, v158, v158 quad_perm:[2,3,0,1] row_mask:0xf bank_mask:0xf
	s_nop 1
	v_add_f32_dpp v158, v158, v158 row_half_mirror row_mask:0xf bank_mask:0xf
	s_mov_b64 exec, s[10:11]
	ds_add_f32 v170, v158 offset:256
	s_mov_b64 exec, -1
	v_mov_b32_e32 v152, 0
	v_mov_b32_e32 v153, 0
	v_mov_b32_e32 v154, 0
	v_mov_b32_e32 v155, 0
	s_waitcnt vmcnt(32)
	v_cvt_scalef32_pk32_bf16_fp6 v[0:15], v[70:75], 1.0
	v_dot2c_f32_bf16_e32 v152, v0, v128
	v_dot2c_f32_bf16_e32 v153, v1, v129
	v_dot2c_f32_bf16_e32 v154, v2, v130
	v_dot2c_f32_bf16_e32 v155, v3, v131
	v_dot2c_f32_bf16_e32 v152, v4, v132
	v_dot2c_f32_bf16_e32 v153, v5, v133
	v_dot2c_f32_bf16_e32 v154, v6, v134
	v_dot2c_f32_bf16_e32 v155, v7, v135
	v_dot2c_f32_bf16_e32 v152, v8, v136
	v_dot2c_f32_bf16_e32 v153, v9, v137
	v_dot2c_f32_bf16_e32 v154, v10, v138
	v_dot2c_f32_bf16_e32 v155, v11, v139
	v_dot2c_f32_bf16_e32 v152, v12, v140
	v_dot2c_f32_bf16_e32 v153, v13, v141
	v_dot2c_f32_bf16_e32 v154, v14, v142
	v_dot2c_f32_bf16_e32 v155, v15, v143
	s_nop 0
	v_add_f32_e32 v156, v152, v153
	s_nop 0
	v_add_f32_e32 v157, v154, v155
	v_add_f32_e32 v158, v156, v157
	s_nop 1
	v_add_f32_dpp v158, v158, v158 quad_perm:[1,0,3,2] row_mask:0xf bank_mask:0xf
	s_nop 1
	v_add_f32_dpp v158, v158, v158 quad_perm:[2,3,0,1] row_mask:0xf bank_mask:0xf
	s_nop 1
	v_add_f32_dpp v158, v158, v158 row_half_mirror row_mask:0xf bank_mask:0xf
	s_mov_b64 exec, s[10:11]
	ds_add_f32 v170, v158 offset:288
	s_mov_b64 exec, -1
	v_mov_b32_e32 v152, 0
	v_mov_b32_e32 v153, 0
	v_mov_b32_e32 v154, 0
	v_mov_b32_e32 v155, 0
	s_waitcnt vmcnt(30)
	v_cvt_scalef32_pk32_bf16_fp6 v[0:15], v[76:81], 1.0
	v_dot2c_f32_bf16_e32 v152, v0, v128
	v_dot2c_f32_bf16_e32 v153, v1, v129
	v_dot2c_f32_bf16_e32 v154, v2, v130
	v_dot2c_f32_bf16_e32 v155, v3, v131
	v_dot2c_f32_bf16_e32 v152, v4, v132
	v_dot2c_f32_bf16_e32 v153, v5, v133
	v_dot2c_f32_bf16_e32 v154, v6, v134
	v_dot2c_f32_bf16_e32 v155, v7, v135
	v_dot2c_f32_bf16_e32 v152, v8, v136
	v_dot2c_f32_bf16_e32 v153, v9, v137
	v_dot2c_f32_bf16_e32 v154, v10, v138
	v_dot2c_f32_bf16_e32 v155, v11, v139
	v_dot2c_f32_bf16_e32 v152, v12, v140
	v_dot2c_f32_bf16_e32 v153, v13, v141
	v_dot2c_f32_bf16_e32 v154, v14, v142
	v_dot2c_f32_bf16_e32 v155, v15, v143
	s_nop 0
	v_add_f32_e32 v156, v152, v153
	s_nop 0
	v_add_f32_e32 v157, v154, v155
	v_add_f32_e32 v158, v156, v157
	s_nop 1
	v_add_f32_dpp v158, v158, v158 quad_perm:[1,0,3,2] row_mask:0xf bank_mask:0xf
	s_nop 1
	v_add_f32_dpp v158, v158, v158 quad_perm:[2,3,0,1] row_mask:0xf bank_mask:0xf
	s_nop 1
	v_add_f32_dpp v158, v158, v158 row_half_mirror row_mask:0xf bank_mask:0xf
	s_mov_b64 exec, s[10:11]
	ds_add_f32 v170, v158 offset:320
	s_mov_b64 exec, -1
	v_mov_b32_e32 v152, 0
	v_mov_b32_e32 v153, 0
	v_mov_b32_e32 v154, 0
	v_mov_b32_e32 v155, 0
	s_waitcnt vmcnt(28)
	v_cvt_scalef32_pk32_bf16_fp6 v[0:15], v[82:87], 1.0
	v_dot2c_f32_bf16_e32 v152, v0, v128
	v_dot2c_f32_bf16_e32 v153, v1, v129
	v_dot2c_f32_bf16_e32 v154, v2, v130
	v_dot2c_f32_bf16_e32 v155, v3, v131
	v_dot2c_f32_bf16_e32 v152, v4, v132
	v_dot2c_f32_bf16_e32 v153, v5, v133
	v_dot2c_f32_bf16_e32 v154, v6, v134
	v_dot2c_f32_bf16_e32 v155, v7, v135
	v_dot2c_f32_bf16_e32 v152, v8, v136
	v_dot2c_f32_bf16_e32 v153, v9, v137
	v_dot2c_f32_bf16_e32 v154, v10, v138
	v_dot2c_f32_bf16_e32 v155, v11, v139
	v_dot2c_f32_bf16_e32 v152, v12, v140
	v_dot2c_f32_bf16_e32 v153, v13, v141
	v_dot2c_f32_bf16_e32 v154, v14, v142
	v_dot2c_f32_bf16_e32 v155, v15, v143
	s_nop 0
	v_add_f32_e32 v156, v152, v153
	s_nop 0
	v_add_f32_e32 v157, v154, v155
	v_add_f32_e32 v158, v156, v157
	s_nop 1
	v_add_f32_dpp v158, v158, v158 quad_perm:[1,0,3,2] row_mask:0xf bank_mask:0xf
	s_nop 1
	v_add_f32_dpp v158, v158, v158 quad_perm:[2,3,0,1] row_mask:0xf bank_mask:0xf
	s_nop 1
	v_add_f32_dpp v158, v158, v158 row_half_mirror row_mask:0xf bank_mask:0xf
	s_mov_b64 exec, s[10:11]
	ds_add_f32 v170, v158 offset:352
	s_mov_b64 exec, -1
	v_mov_b32_e32 v152, 0
	v_mov_b32_e32 v153, 0
	v_mov_b32_e32 v154, 0
	v_mov_b32_e32 v155, 0
	s_waitcnt vmcnt(26)
	v_cvt_scalef32_pk32_bf16_fp6 v[0:15], v[88:93], 1.0
	v_dot2c_f32_bf16_e32 v152, v0, v128
	v_dot2c_f32_bf16_e32 v153, v1, v129
	v_dot2c_f32_bf16_e32 v154, v2, v130
	v_dot2c_f32_bf16_e32 v155, v3, v131
	v_dot2c_f32_bf16_e32 v152, v4, v132
	v_dot2c_f32_bf16_e32 v153, v5, v133
	v_dot2c_f32_bf16_e32 v154, v6, v134
	v_dot2c_f32_bf16_e32 v155, v7, v135
	v_dot2c_f32_bf16_e32 v152, v8, v136
	v_dot2c_f32_bf16_e32 v153, v9, v137
	v_dot2c_f32_bf16_e32 v154, v10, v138
	v_dot2c_f32_bf16_e32 v155, v11, v139
	v_dot2c_f32_bf16_e32 v152, v12, v140
	v_dot2c_f32_bf16_e32 v153, v13, v141
	v_dot2c_f32_bf16_e32 v154, v14, v142
	v_dot2c_f32_bf16_e32 v155, v15, v143
	s_nop 0
	v_add_f32_e32 v156, v152, v153
	s_nop 0
	v_add_f32_e32 v157, v154, v155
	v_add_f32_e32 v158, v156, v157
	s_nop 1
	v_add_f32_dpp v158, v158, v158 quad_perm:[1,0,3,2] row_mask:0xf bank_mask:0xf
	s_nop 1
	v_add_f32_dpp v158, v158, v158 quad_perm:[2,3,0,1] row_mask:0xf bank_mask:0xf
	s_nop 1
	v_add_f32_dpp v158, v158, v158 row_half_mirror row_mask:0xf bank_mask:0xf
	s_mov_b64 exec, s[10:11]
	ds_add_f32 v170, v158 offset:384
	s_mov_b64 exec, -1
	v_mov_b32_e32 v152, 0
	v_mov_b32_e32 v153, 0
	v_mov_b32_e32 v154, 0
	v_mov_b32_e32 v155, 0
	s_waitcnt vmcnt(24)
	v_cvt_scalef32_pk32_bf16_fp6 v[0:15], v[94:99], 1.0
	v_dot2c_f32_bf16_e32 v152, v0, v128
	v_dot2c_f32_bf16_e32 v153, v1, v129
	v_dot2c_f32_bf16_e32 v154, v2, v130
	v_dot2c_f32_bf16_e32 v155, v3, v131
	v_dot2c_f32_bf16_e32 v152, v4, v132
	v_dot2c_f32_bf16_e32 v153, v5, v133
	v_dot2c_f32_bf16_e32 v154, v6, v134
	v_dot2c_f32_bf16_e32 v155, v7, v135
	v_dot2c_f32_bf16_e32 v152, v8, v136
	v_dot2c_f32_bf16_e32 v153, v9, v137
	v_dot2c_f32_bf16_e32 v154, v10, v138
	v_dot2c_f32_bf16_e32 v155, v11, v139
	v_dot2c_f32_bf16_e32 v152, v12, v140
	v_dot2c_f32_bf16_e32 v153, v13, v141
	v_dot2c_f32_bf16_e32 v154, v14, v142
	v_dot2c_f32_bf16_e32 v155, v15, v143
	s_nop 0
	v_add_f32_e32 v156, v152, v153
	s_nop 0
	v_add_f32_e32 v157, v154, v155
	v_add_f32_e32 v158, v156, v157
	s_nop 1
	v_add_f32_dpp v158, v158, v158 quad_perm:[1,0,3,2] row_mask:0xf bank_mask:0xf
	s_nop 1
	v_add_f32_dpp v158, v158, v158 quad_perm:[2,3,0,1] row_mask:0xf bank_mask:0xf
	s_nop 1
	v_add_f32_dpp v158, v158, v158 row_half_mirror row_mask:0xf bank_mask:0xf
	s_mov_b64 exec, s[10:11]
	ds_add_f32 v170, v158 offset:416
	s_mov_b64 exec, -1
	v_mov_b32_e32 v152, 0
	v_mov_b32_e32 v153, 0
	v_mov_b32_e32 v154, 0
	v_mov_b32_e32 v155, 0
	s_waitcnt vmcnt(22)
	v_cvt_scalef32_pk32_bf16_fp6 v[0:15], v[100:105], 1.0
	v_dot2c_f32_bf16_e32 v152, v0, v128
	v_dot2c_f32_bf16_e32 v153, v1, v129
	v_dot2c_f32_bf16_e32 v154, v2, v130
	v_dot2c_f32_bf16_e32 v155, v3, v131
	v_dot2c_f32_bf16_e32 v152, v4, v132
	v_dot2c_f32_bf16_e32 v153, v5, v133
	v_dot2c_f32_bf16_e32 v154, v6, v134
	v_dot2c_f32_bf16_e32 v155, v7, v135
	v_dot2c_f32_bf16_e32 v152, v8, v136
	v_dot2c_f32_bf16_e32 v153, v9, v137
	v_dot2c_f32_bf16_e32 v154, v10, v138
	v_dot2c_f32_bf16_e32 v155, v11, v139
	v_dot2c_f32_bf16_e32 v152, v12, v140
	v_dot2c_f32_bf16_e32 v153, v13, v141
	v_dot2c_f32_bf16_e32 v154, v14, v142
	v_dot2c_f32_bf16_e32 v155, v15, v143
	s_nop 0
	v_add_f32_e32 v156, v152, v153
	s_nop 0
	v_add_f32_e32 v157, v154, v155
	v_add_f32_e32 v158, v156, v157
	s_nop 1
	v_add_f32_dpp v158, v158, v158 quad_perm:[1,0,3,2] row_mask:0xf bank_mask:0xf
	s_nop 1
	v_add_f32_dpp v158, v158, v158 quad_perm:[2,3,0,1] row_mask:0xf bank_mask:0xf
	s_nop 1
	v_add_f32_dpp v158, v158, v158 row_half_mirror row_mask:0xf bank_mask:0xf
	s_mov_b64 exec, s[10:11]
	ds_add_f32 v170, v158 offset:448
	s_mov_b64 exec, -1
	v_mov_b32_e32 v152, 0
	v_mov_b32_e32 v153, 0
	v_mov_b32_e32 v154, 0
	v_mov_b32_e32 v155, 0
	s_waitcnt vmcnt(20)
	v_cvt_scalef32_pk32_bf16_fp6 v[0:15], v[106:111], 1.0
	v_dot2c_f32_bf16_e32 v152, v0, v128
	v_dot2c_f32_bf16_e32 v153, v1, v129
	v_dot2c_f32_bf16_e32 v154, v2, v130
	v_dot2c_f32_bf16_e32 v155, v3, v131
	v_dot2c_f32_bf16_e32 v152, v4, v132
	v_dot2c_f32_bf16_e32 v153, v5, v133
	v_dot2c_f32_bf16_e32 v154, v6, v134
	v_dot2c_f32_bf16_e32 v155, v7, v135
	v_dot2c_f32_bf16_e32 v152, v8, v136
	v_dot2c_f32_bf16_e32 v153, v9, v137
	v_dot2c_f32_bf16_e32 v154, v10, v138
	v_dot2c_f32_bf16_e32 v155, v11, v139
	v_dot2c_f32_bf16_e32 v152, v12, v140
	v_dot2c_f32_bf16_e32 v153, v13, v141
	v_dot2c_f32_bf16_e32 v154, v14, v142
	v_dot2c_f32_bf16_e32 v155, v15, v143
	s_nop 0
	v_add_f32_e32 v156, v152, v153
	s_nop 0
	v_add_f32_e32 v157, v154, v155
	v_add_f32_e32 v158, v156, v157
	s_nop 1
	v_add_f32_dpp v158, v158, v158 quad_perm:[1,0,3,2] row_mask:0xf bank_mask:0xf
	s_nop 1
	v_add_f32_dpp v158, v158, v158 quad_perm:[2,3,0,1] row_mask:0xf bank_mask:0xf
	s_nop 1
	v_add_f32_dpp v158, v158, v158 row_half_mirror row_mask:0xf bank_mask:0xf
	s_mov_b64 exec, s[10:11]
	ds_add_f32 v170, v158 offset:480
	s_mov_b64 exec, -1
	s_cmp_lg_u32 s12, 0
	s_cbranch_scc1 .Lgu1_loop
	s_waitcnt vmcnt(0) lgkmcnt(0)
	s_add_u32 s0, s26, 0x1420000
	s_addc_u32 s1, s27, 0
	s_add_u32 s4, s26, 0x1430000
	s_addc_u32 s5, s27, 0
	s_lshl_b32 s13, s35, 9
	s_add_u32 s6, s26, 0xe800000
	s_addc_u32 s7, s27, 0
	s_add_u32 s6, s6, s13
	s_addc_u32 s7, s7, 0
	s_add_u32 s8, s26, 0xf800000
	s_addc_u32 s9, s27, 0
	s_add_u32 s8, s8, s13
	s_addc_u32 s9, s9, 0
	s_lshl_b32 s14, s92, 11
	s_mov_b32 s12, 0x378e98ab
	s_mov_b32 s15, 0x3b7cd369
	s_mov_b32 s16, 0xbcc618b2
	s_mov_b32 s17, 0x3dda74e4
	s_mov_b32 s18, 0x3f228afd
	s_mov_b32 s19, 0x3e03c728
	s_mov_b32 s98, 0xbfb8aa3b
	s_mov_b32 s38, 0x42ce8ed0
	s_mov_b32 s39, 0xc2b17218
	s_mov_b32 s10, 0x7fffffff
	v_mov_b32_e32 v176, 0x3ba10414
	v_mov_b32_e32 v177, 0xb9c68948
	v_mov_b32_e32 v178, 0x7f800000
	ds_read2st64_b32 v[16:17], v174 offset0:0 offset1:1
	ds_read2st64_b32 v[80:81], v175 offset0:0 offset1:1
	ds_read2st64_b32 v[18:19], v174 offset0:2 offset1:3
	ds_read2st64_b32 v[82:83], v175 offset0:2 offset1:3
	ds_read2st64_b32 v[20:21], v174 offset0:4 offset1:5
	ds_read2st64_b32 v[84:85], v175 offset0:4 offset1:5
	ds_read2st64_b32 v[22:23], v174 offset0:6 offset1:7
	ds_read2st64_b32 v[86:87], v175 offset0:6 offset1:7
	ds_read2st64_b32 v[24:25], v174 offset0:8 offset1:9
	ds_read2st64_b32 v[88:89], v175 offset0:8 offset1:9
	ds_read2st64_b32 v[26:27], v174 offset0:10 offset1:11
	ds_read2st64_b32 v[90:91], v175 offset0:10 offset1:11
	ds_read2st64_b32 v[28:29], v174 offset0:12 offset1:13
	ds_read2st64_b32 v[92:93], v175 offset0:12 offset1:13
	ds_read2st64_b32 v[30:31], v174 offset0:14 offset1:15
	ds_read2st64_b32 v[94:95], v175 offset0:14 offset1:15
	s_waitcnt lgkmcnt(0)
	v_lshlrev_b32_e32 v16, 2, v16
	v_lshlrev_b32_e32 v17, 2, v17
	v_lshlrev_b32_e32 v18, 2, v18
	v_lshlrev_b32_e32 v19, 2, v19
	v_lshlrev_b32_e32 v20, 2, v20
	v_lshlrev_b32_e32 v21, 2, v21
	v_lshlrev_b32_e32 v22, 2, v22
	v_lshlrev_b32_e32 v23, 2, v23
	v_lshlrev_b32_e32 v24, 2, v24
	v_lshlrev_b32_e32 v25, 2, v25
	v_lshlrev_b32_e32 v26, 2, v26
	v_lshlrev_b32_e32 v27, 2, v27
	v_lshlrev_b32_e32 v28, 2, v28
	v_lshlrev_b32_e32 v29, 2, v29
	v_lshlrev_b32_e32 v30, 2, v30
	v_lshlrev_b32_e32 v31, 2, v31
	global_load_dword v32, v160, s[6:7]
	global_load_dword v33, v160, s[6:7] offset:256
	global_load_dword v34, v16, s[0:1]
	global_load_dword v35, v17, s[0:1]
	global_load_dword v36, v16, s[4:5]
	global_load_dword v37, v17, s[4:5]
	s_add_u32 s6, s6, s14
	s_addc_u32 s7, s7, 0
	global_load_dword v38, v160, s[6:7]
	global_load_dword v39, v160, s[6:7] offset:256
	global_load_dword v40, v18, s[0:1]
	global_load_dword v41, v19, s[0:1]
	global_load_dword v42, v18, s[4:5]
	global_load_dword v43, v19, s[4:5]
	s_add_u32 s6, s6, s14
	s_addc_u32 s7, s7, 0
	global_load_dword v44, v160, s[6:7]
	global_load_dword v45, v160, s[6:7] offset:256
	global_load_dword v46, v20, s[0:1]
	global_load_dword v47, v21, s[0:1]
	global_load_dword v48, v20, s[4:5]
	global_load_dword v49, v21, s[4:5]
	s_add_u32 s6, s6, s14
	s_addc_u32 s7, s7, 0
	global_load_dword v50, v160, s[6:7]
	global_load_dword v51, v160, s[6:7] offset:256
	global_load_dword v52, v22, s[0:1]
	global_load_dword v53, v23, s[0:1]
	global_load_dword v54, v22, s[4:5]
	global_load_dword v55, v23, s[4:5]
	s_add_u32 s6, s6, s14
	s_addc_u32 s7, s7, 0
	global_load_dword v56, v160, s[6:7]
	global_load_dword v57, v160, s[6:7] offset:256
	global_load_dword v58, v24, s[0:1]
	global_load_dword v59, v25, s[0:1]
	global_load_dword v60, v24, s[4:5]
	global_load_dword v61, v25, s[4:5]
	s_add_u32 s6, s6, s14
	s_addc_u32 s7, s7, 0
	global_load_dword v62, v160, s[6:7]
	global_load_dword v63, v160, s[6:7] offset:256
	global_load_dword v64, v26, s[0:1]
	global_load_dword v65, v27, s[0:1]
	global_load_dword v66, v26, s[4:5]
	global_load_dword v67, v27, s[4:5]
	s_add_u32 s6, s6, s14
	s_addc_u32 s7, s7, 0
	global_load_dword v68, v160, s[6:7]
	global_load_dword v69, v160, s[6:7] offset:256
	global_load_dword v70, v28, s[0:1]
	global_load_dword v71, v29, s[0:1]
	global_load_dword v72, v28, s[4:5]
	global_load_dword v73, v29, s[4:5]
	s_add_u32 s6, s6, s14
	s_addc_u32 s7, s7, 0
	global_load_dword v74, v160, s[6:7]
	global_load_dword v75, v160, s[6:7] offset:256
	global_load_dword v76, v30, s[0:1]
	global_load_dword v77, v31, s[0:1]
	global_load_dword v78, v30, s[4:5]
	global_load_dword v79, v31, s[4:5]
	s_add_u32 s6, s6, s14
	s_addc_u32 s7, s7, 0
	s_waitcnt vmcnt(0)
	v_mul_f32_e32 v80, v34, v80
	v_mul_f32_e32 v180, 0x3f3504f3, v80
	v_fma_f32 v182, |v180|, s12, v177
	v_fma_f32 v182, |v180|, v182, s15
	v_fma_f32 v182, |v180|, v182, s16
	v_fma_f32 v182, |v180|, v182, s17
	v_fma_f32 v182, |v180|, v182, s18
	v_fma_f32 v182, |v180|, v182, s19
	v_fma_f32 v182, |v180|, v182, |v180|
	v_mul_f32_e32 v184, 0xbfb8aa3b, v182
	v_fma_f32 v185, v182, s98, -v184
	v_rndne_f32_e32 v186, v184
	v_fmac_f32_e32 v185, 0xb2a5705f, v182
	v_sub_f32_e32 v184, v184, v186
	v_add_f32_e32 v184, v184, v185
	v_cvt_i32_f32_e32 v185, v186
	v_exp_f32_e32 v184, v184
	v_cmp_nlt_f32_e32 vcc, s38, v182
	v_ldexp_f32 v184, v184, v185
	s_nop 0
	v_cndmask_b32_e32 v184, 0, v184, vcc
	v_cmp_ngt_f32_e32 vcc, s39, v182
	s_nop 1
	v_cndmask_b32_e32 v184, v178, v184, vcc
	v_sub_f32_e32 v184, 1.0, v184
	v_mul_f32_e32 v183, v180, v180
	v_fmamk_f32 v185, v183, 0xba1345e1, v176
	v_fmaak_f32 v185, v183, v185, 0xbcdac9b8
	v_fmaak_f32 v185, v183, v185, 0x3de703be
	v_fmaak_f32 v185, v183, v185, 0xbec09330
	v_fmaak_f32 v183, v183, v185, 0x3e0375d0
	v_fma_f32 v183, |v180|, v183, |v180|
	v_cmp_nlt_f32_e64 vcc, |v180|, 1.0
	s_nop 1
	v_cndmask_b32_e32 v184, v183, v184, vcc
	v_bfi_b32 v184, s10, v184, v180
	v_add_f32_e32 v184, 1.0, v184
	v_mul_f32_e32 v80, 0.5, v80
	v_mul_f32_e32 v32, v32, v36
	v_mul_f32_e32 v80, v80, v184
	v_mul_f32_e32 v80, v32, v80
	v_mul_f32_e32 v81, v35, v81
	v_mul_f32_e32 v180, 0x3f3504f3, v81
	v_fma_f32 v182, |v180|, s12, v177
	v_fma_f32 v182, |v180|, v182, s15
	v_fma_f32 v182, |v180|, v182, s16
	v_fma_f32 v182, |v180|, v182, s17
	v_fma_f32 v182, |v180|, v182, s18
	v_fma_f32 v182, |v180|, v182, s19
	v_fma_f32 v182, |v180|, v182, |v180|
	v_mul_f32_e32 v184, 0xbfb8aa3b, v182
	v_fma_f32 v185, v182, s98, -v184
	v_rndne_f32_e32 v186, v184
	v_fmac_f32_e32 v185, 0xb2a5705f, v182
	v_sub_f32_e32 v184, v184, v186
	v_add_f32_e32 v184, v184, v185
	v_cvt_i32_f32_e32 v185, v186
	v_exp_f32_e32 v184, v184
	v_cmp_nlt_f32_e32 vcc, s38, v182
	v_ldexp_f32 v184, v184, v185
	s_nop 0
	v_cndmask_b32_e32 v184, 0, v184, vcc
	v_cmp_ngt_f32_e32 vcc, s39, v182
	s_nop 1
	v_cndmask_b32_e32 v184, v178, v184, vcc
	v_sub_f32_e32 v184, 1.0, v184
	v_mul_f32_e32 v183, v180, v180
	v_fmamk_f32 v185, v183, 0xba1345e1, v176
	v_fmaak_f32 v185, v183, v185, 0xbcdac9b8
	v_fmaak_f32 v185, v183, v185, 0x3de703be
	v_fmaak_f32 v185, v183, v185, 0xbec09330
	v_fmaak_f32 v183, v183, v185, 0x3e0375d0
	v_fma_f32 v183, |v180|, v183, |v180|
	v_cmp_nlt_f32_e64 vcc, |v180|, 1.0
	s_nop 1
	v_cndmask_b32_e32 v184, v183, v184, vcc
	v_bfi_b32 v184, s10, v184, v180
	v_add_f32_e32 v184, 1.0, v184
	v_mul_f32_e32 v81, 0.5, v81
	v_mul_f32_e32 v33, v33, v37
	v_mul_f32_e32 v81, v81, v184
	v_mul_f32_e32 v81, v33, v81
	global_store_dword v160, v80, s[8:9]
	global_store_dword v160, v81, s[8:9] offset:256
	s_add_u32 s8, s8, s14
	s_addc_u32 s9, s9, 0
	v_mul_f32_e32 v82, v40, v82
	v_mul_f32_e32 v180, 0x3f3504f3, v82
	v_fma_f32 v182, |v180|, s12, v177
	v_fma_f32 v182, |v180|, v182, s15
	v_fma_f32 v182, |v180|, v182, s16
	v_fma_f32 v182, |v180|, v182, s17
	v_fma_f32 v182, |v180|, v182, s18
	v_fma_f32 v182, |v180|, v182, s19
	v_fma_f32 v182, |v180|, v182, |v180|
	v_mul_f32_e32 v184, 0xbfb8aa3b, v182
	v_fma_f32 v185, v182, s98, -v184
	v_rndne_f32_e32 v186, v184
	v_fmac_f32_e32 v185, 0xb2a5705f, v182
	v_sub_f32_e32 v184, v184, v186
	v_add_f32_e32 v184, v184, v185
	v_cvt_i32_f32_e32 v185, v186
	v_exp_f32_e32 v184, v184
	v_cmp_nlt_f32_e32 vcc, s38, v182
	v_ldexp_f32 v184, v184, v185
	s_nop 0
	v_cndmask_b32_e32 v184, 0, v184, vcc
	v_cmp_ngt_f32_e32 vcc, s39, v182
	s_nop 1
	v_cndmask_b32_e32 v184, v178, v184, vcc
	v_sub_f32_e32 v184, 1.0, v184
	v_mul_f32_e32 v183, v180, v180
	v_fmamk_f32 v185, v183, 0xba1345e1, v176
	v_fmaak_f32 v185, v183, v185, 0xbcdac9b8
	v_fmaak_f32 v185, v183, v185, 0x3de703be
	v_fmaak_f32 v185, v183, v185, 0xbec09330
	v_fmaak_f32 v183, v183, v185, 0x3e0375d0
	v_fma_f32 v183, |v180|, v183, |v180|
	v_cmp_nlt_f32_e64 vcc, |v180|, 1.0
	s_nop 1
	v_cndmask_b32_e32 v184, v183, v184, vcc
	v_bfi_b32 v184, s10, v184, v180
	v_add_f32_e32 v184, 1.0, v184
	v_mul_f32_e32 v82, 0.5, v82
	v_mul_f32_e32 v38, v38, v42
	v_mul_f32_e32 v82, v82, v184
	v_mul_f32_e32 v82, v38, v82
	v_mul_f32_e32 v83, v41, v83
	v_mul_f32_e32 v180, 0x3f3504f3, v83
	v_fma_f32 v182, |v180|, s12, v177
	v_fma_f32 v182, |v180|, v182, s15
	v_fma_f32 v182, |v180|, v182, s16
	v_fma_f32 v182, |v180|, v182, s17
	v_fma_f32 v182, |v180|, v182, s18
	v_fma_f32 v182, |v180|, v182, s19
	v_fma_f32 v182, |v180|, v182, |v180|
	v_mul_f32_e32 v184, 0xbfb8aa3b, v182
	v_fma_f32 v185, v182, s98, -v184
	v_rndne_f32_e32 v186, v184
	v_fmac_f32_e32 v185, 0xb2a5705f, v182
	v_sub_f32_e32 v184, v184, v186
	v_add_f32_e32 v184, v184, v185
	v_cvt_i32_f32_e32 v185, v186
	v_exp_f32_e32 v184, v184
	v_cmp_nlt_f32_e32 vcc, s38, v182
	v_ldexp_f32 v184, v184, v185
	s_nop 0
	v_cndmask_b32_e32 v184, 0, v184, vcc
	v_cmp_ngt_f32_e32 vcc, s39, v182
	s_nop 1
	v_cndmask_b32_e32 v184, v178, v184, vcc
	v_sub_f32_e32 v184, 1.0, v184
	v_mul_f32_e32 v183, v180, v180
	v_fmamk_f32 v185, v183, 0xba1345e1, v176
	v_fmaak_f32 v185, v183, v185, 0xbcdac9b8
	v_fmaak_f32 v185, v183, v185, 0x3de703be
	v_fmaak_f32 v185, v183, v185, 0xbec09330
	v_fmaak_f32 v183, v183, v185, 0x3e0375d0
	v_fma_f32 v183, |v180|, v183, |v180|
	v_cmp_nlt_f32_e64 vcc, |v180|, 1.0
	s_nop 1
	v_cndmask_b32_e32 v184, v183, v184, vcc
	v_bfi_b32 v184, s10, v184, v180
	v_add_f32_e32 v184, 1.0, v184
	v_mul_f32_e32 v83, 0.5, v83
	v_mul_f32_e32 v39, v39, v43
	v_mul_f32_e32 v83, v83, v184
	v_mul_f32_e32 v83, v39, v83
	global_store_dword v160, v82, s[8:9]
	global_store_dword v160, v83, s[8:9] offset:256
	s_add_u32 s8, s8, s14
	s_addc_u32 s9, s9, 0
	v_mul_f32_e32 v84, v46, v84
	v_mul_f32_e32 v180, 0x3f3504f3, v84
	v_fma_f32 v182, |v180|, s12, v177
	v_fma_f32 v182, |v180|, v182, s15
	v_fma_f32 v182, |v180|, v182, s16
	v_fma_f32 v182, |v180|, v182, s17
	v_fma_f32 v182, |v180|, v182, s18
	v_fma_f32 v182, |v180|, v182, s19
	v_fma_f32 v182, |v180|, v182, |v180|
	v_mul_f32_e32 v184, 0xbfb8aa3b, v182
	v_fma_f32 v185, v182, s98, -v184
	v_rndne_f32_e32 v186, v184
	v_fmac_f32_e32 v185, 0xb2a5705f, v182
	v_sub_f32_e32 v184, v184, v186
	v_add_f32_e32 v184, v184, v185
	v_cvt_i32_f32_e32 v185, v186
	v_exp_f32_e32 v184, v184
	v_cmp_nlt_f32_e32 vcc, s38, v182
	v_ldexp_f32 v184, v184, v185
	s_nop 0
	v_cndmask_b32_e32 v184, 0, v184, vcc
	v_cmp_ngt_f32_e32 vcc, s39, v182
	s_nop 1
	v_cndmask_b32_e32 v184, v178, v184, vcc
	v_sub_f32_e32 v184, 1.0, v184
	v_mul_f32_e32 v183, v180, v180
	v_fmamk_f32 v185, v183, 0xba1345e1, v176
	v_fmaak_f32 v185, v183, v185, 0xbcdac9b8
	v_fmaak_f32 v185, v183, v185, 0x3de703be
	v_fmaak_f32 v185, v183, v185, 0xbec09330
	v_fmaak_f32 v183, v183, v185, 0x3e0375d0
	v_fma_f32 v183, |v180|, v183, |v180|
	v_cmp_nlt_f32_e64 vcc, |v180|, 1.0
	s_nop 1
	v_cndmask_b32_e32 v184, v183, v184, vcc
	v_bfi_b32 v184, s10, v184, v180
	v_add_f32_e32 v184, 1.0, v184
	v_mul_f32_e32 v84, 0.5, v84
	v_mul_f32_e32 v44, v44, v48
	v_mul_f32_e32 v84, v84, v184
	v_mul_f32_e32 v84, v44, v84
	v_mul_f32_e32 v85, v47, v85
	v_mul_f32_e32 v180, 0x3f3504f3, v85
	v_fma_f32 v182, |v180|, s12, v177
	v_fma_f32 v182, |v180|, v182, s15
	v_fma_f32 v182, |v180|, v182, s16
	v_fma_f32 v182, |v180|, v182, s17
	v_fma_f32 v182, |v180|, v182, s18
	v_fma_f32 v182, |v180|, v182, s19
	v_fma_f32 v182, |v180|, v182, |v180|
	v_mul_f32_e32 v184, 0xbfb8aa3b, v182
	v_fma_f32 v185, v182, s98, -v184
	v_rndne_f32_e32 v186, v184
	v_fmac_f32_e32 v185, 0xb2a5705f, v182
	v_sub_f32_e32 v184, v184, v186
	v_add_f32_e32 v184, v184, v185
	v_cvt_i32_f32_e32 v185, v186
	v_exp_f32_e32 v184, v184
	v_cmp_nlt_f32_e32 vcc, s38, v182
	v_ldexp_f32 v184, v184, v185
	s_nop 0
	v_cndmask_b32_e32 v184, 0, v184, vcc
	v_cmp_ngt_f32_e32 vcc, s39, v182
	s_nop 1
	v_cndmask_b32_e32 v184, v178, v184, vcc
	v_sub_f32_e32 v184, 1.0, v184
	v_mul_f32_e32 v183, v180, v180
	v_fmamk_f32 v185, v183, 0xba1345e1, v176
	v_fmaak_f32 v185, v183, v185, 0xbcdac9b8
	v_fmaak_f32 v185, v183, v185, 0x3de703be
	v_fmaak_f32 v185, v183, v185, 0xbec09330
	v_fmaak_f32 v183, v183, v185, 0x3e0375d0
	v_fma_f32 v183, |v180|, v183, |v180|
	v_cmp_nlt_f32_e64 vcc, |v180|, 1.0
	s_nop 1
	v_cndmask_b32_e32 v184, v183, v184, vcc
	v_bfi_b32 v184, s10, v184, v180
	v_add_f32_e32 v184, 1.0, v184
	v_mul_f32_e32 v85, 0.5, v85
	v_mul_f32_e32 v45, v45, v49
	v_mul_f32_e32 v85, v85, v184
	v_mul_f32_e32 v85, v45, v85
	global_store_dword v160, v84, s[8:9]
	global_store_dword v160, v85, s[8:9] offset:256
	s_add_u32 s8, s8, s14
	s_addc_u32 s9, s9, 0
	v_mul_f32_e32 v86, v52, v86
	v_mul_f32_e32 v180, 0x3f3504f3, v86
	v_fma_f32 v182, |v180|, s12, v177
	v_fma_f32 v182, |v180|, v182, s15
	v_fma_f32 v182, |v180|, v182, s16
	v_fma_f32 v182, |v180|, v182, s17
	v_fma_f32 v182, |v180|, v182, s18
	v_fma_f32 v182, |v180|, v182, s19
	v_fma_f32 v182, |v180|, v182, |v180|
	v_mul_f32_e32 v184, 0xbfb8aa3b, v182
	v_fma_f32 v185, v182, s98, -v184
	v_rndne_f32_e32 v186, v184
	v_fmac_f32_e32 v185, 0xb2a5705f, v182
	v_sub_f32_e32 v184, v184, v186
	v_add_f32_e32 v184, v184, v185
	v_cvt_i32_f32_e32 v185, v186
	v_exp_f32_e32 v184, v184
	v_cmp_nlt_f32_e32 vcc, s38, v182
	v_ldexp_f32 v184, v184, v185
	s_nop 0
	v_cndmask_b32_e32 v184, 0, v184, vcc
	v_cmp_ngt_f32_e32 vcc, s39, v182
	s_nop 1
	v_cndmask_b32_e32 v184, v178, v184, vcc
	v_sub_f32_e32 v184, 1.0, v184
	v_mul_f32_e32 v183, v180, v180
	v_fmamk_f32 v185, v183, 0xba1345e1, v176
	v_fmaak_f32 v185, v183, v185, 0xbcdac9b8
	v_fmaak_f32 v185, v183, v185, 0x3de703be
	v_fmaak_f32 v185, v183, v185, 0xbec09330
	v_fmaak_f32 v183, v183, v185, 0x3e0375d0
	v_fma_f32 v183, |v180|, v183, |v180|
	v_cmp_nlt_f32_e64 vcc, |v180|, 1.0
	s_nop 1
	v_cndmask_b32_e32 v184, v183, v184, vcc
	v_bfi_b32 v184, s10, v184, v180
	v_add_f32_e32 v184, 1.0, v184
	v_mul_f32_e32 v86, 0.5, v86
	v_mul_f32_e32 v50, v50, v54
	v_mul_f32_e32 v86, v86, v184
	v_mul_f32_e32 v86, v50, v86
	v_mul_f32_e32 v87, v53, v87
	v_mul_f32_e32 v180, 0x3f3504f3, v87
	v_fma_f32 v182, |v180|, s12, v177
	v_fma_f32 v182, |v180|, v182, s15
	v_fma_f32 v182, |v180|, v182, s16
	v_fma_f32 v182, |v180|, v182, s17
	v_fma_f32 v182, |v180|, v182, s18
	v_fma_f32 v182, |v180|, v182, s19
	v_fma_f32 v182, |v180|, v182, |v180|
	v_mul_f32_e32 v184, 0xbfb8aa3b, v182
	v_fma_f32 v185, v182, s98, -v184
	v_rndne_f32_e32 v186, v184
	v_fmac_f32_e32 v185, 0xb2a5705f, v182
	v_sub_f32_e32 v184, v184, v186
	v_add_f32_e32 v184, v184, v185
	v_cvt_i32_f32_e32 v185, v186
	v_exp_f32_e32 v184, v184
	v_cmp_nlt_f32_e32 vcc, s38, v182
	v_ldexp_f32 v184, v184, v185
	s_nop 0
	v_cndmask_b32_e32 v184, 0, v184, vcc
	v_cmp_ngt_f32_e32 vcc, s39, v182
	s_nop 1
	v_cndmask_b32_e32 v184, v178, v184, vcc
	v_sub_f32_e32 v184, 1.0, v184
	v_mul_f32_e32 v183, v180, v180
	v_fmamk_f32 v185, v183, 0xba1345e1, v176
	v_fmaak_f32 v185, v183, v185, 0xbcdac9b8
	v_fmaak_f32 v185, v183, v185, 0x3de703be
	v_fmaak_f32 v185, v183, v185, 0xbec09330
	v_fmaak_f32 v183, v183, v185, 0x3e0375d0
	v_fma_f32 v183, |v180|, v183, |v180|
	v_cmp_nlt_f32_e64 vcc, |v180|, 1.0
	s_nop 1
	v_cndmask_b32_e32 v184, v183, v184, vcc
	v_bfi_b32 v184, s10, v184, v180
	v_add_f32_e32 v184, 1.0, v184
	v_mul_f32_e32 v87, 0.5, v87
	v_mul_f32_e32 v51, v51, v55
	v_mul_f32_e32 v87, v87, v184
	v_mul_f32_e32 v87, v51, v87
	global_store_dword v160, v86, s[8:9]
	global_store_dword v160, v87, s[8:9] offset:256
	s_add_u32 s8, s8, s14
	s_addc_u32 s9, s9, 0
	v_mul_f32_e32 v88, v58, v88
	v_mul_f32_e32 v180, 0x3f3504f3, v88
	v_fma_f32 v182, |v180|, s12, v177
	v_fma_f32 v182, |v180|, v182, s15
	v_fma_f32 v182, |v180|, v182, s16
	v_fma_f32 v182, |v180|, v182, s17
	v_fma_f32 v182, |v180|, v182, s18
	v_fma_f32 v182, |v180|, v182, s19
	v_fma_f32 v182, |v180|, v182, |v180|
	v_mul_f32_e32 v184, 0xbfb8aa3b, v182
	v_fma_f32 v185, v182, s98, -v184
	v_rndne_f32_e32 v186, v184
	v_fmac_f32_e32 v185, 0xb2a5705f, v182
	v_sub_f32_e32 v184, v184, v186
	v_add_f32_e32 v184, v184, v185
	v_cvt_i32_f32_e32 v185, v186
	v_exp_f32_e32 v184, v184
	v_cmp_nlt_f32_e32 vcc, s38, v182
	v_ldexp_f32 v184, v184, v185
	s_nop 0
	v_cndmask_b32_e32 v184, 0, v184, vcc
	v_cmp_ngt_f32_e32 vcc, s39, v182
	s_nop 1
	v_cndmask_b32_e32 v184, v178, v184, vcc
	v_sub_f32_e32 v184, 1.0, v184
	v_mul_f32_e32 v183, v180, v180
	v_fmamk_f32 v185, v183, 0xba1345e1, v176
	v_fmaak_f32 v185, v183, v185, 0xbcdac9b8
	v_fmaak_f32 v185, v183, v185, 0x3de703be
	v_fmaak_f32 v185, v183, v185, 0xbec09330
	v_fmaak_f32 v183, v183, v185, 0x3e0375d0
	v_fma_f32 v183, |v180|, v183, |v180|
	v_cmp_nlt_f32_e64 vcc, |v180|, 1.0
	s_nop 1
	v_cndmask_b32_e32 v184, v183, v184, vcc
	v_bfi_b32 v184, s10, v184, v180
	v_add_f32_e32 v184, 1.0, v184
	v_mul_f32_e32 v88, 0.5, v88
	v_mul_f32_e32 v56, v56, v60
	v_mul_f32_e32 v88, v88, v184
	v_mul_f32_e32 v88, v56, v88
	v_mul_f32_e32 v89, v59, v89
	v_mul_f32_e32 v180, 0x3f3504f3, v89
	v_fma_f32 v182, |v180|, s12, v177
	v_fma_f32 v182, |v180|, v182, s15
	v_fma_f32 v182, |v180|, v182, s16
	v_fma_f32 v182, |v180|, v182, s17
	v_fma_f32 v182, |v180|, v182, s18
	v_fma_f32 v182, |v180|, v182, s19
	v_fma_f32 v182, |v180|, v182, |v180|
	v_mul_f32_e32 v184, 0xbfb8aa3b, v182
	v_fma_f32 v185, v182, s98, -v184
	v_rndne_f32_e32 v186, v184
	v_fmac_f32_e32 v185, 0xb2a5705f, v182
	v_sub_f32_e32 v184, v184, v186
	v_add_f32_e32 v184, v184, v185
	v_cvt_i32_f32_e32 v185, v186
	v_exp_f32_e32 v184, v184
	v_cmp_nlt_f32_e32 vcc, s38, v182
	v_ldexp_f32 v184, v184, v185
	s_nop 0
	v_cndmask_b32_e32 v184, 0, v184, vcc
	v_cmp_ngt_f32_e32 vcc, s39, v182
	s_nop 1
	v_cndmask_b32_e32 v184, v178, v184, vcc
	v_sub_f32_e32 v184, 1.0, v184
	v_mul_f32_e32 v183, v180, v180
	v_fmamk_f32 v185, v183, 0xba1345e1, v176
	v_fmaak_f32 v185, v183, v185, 0xbcdac9b8
	v_fmaak_f32 v185, v183, v185, 0x3de703be
	v_fmaak_f32 v185, v183, v185, 0xbec09330
	v_fmaak_f32 v183, v183, v185, 0x3e0375d0
	v_fma_f32 v183, |v180|, v183, |v180|
	v_cmp_nlt_f32_e64 vcc, |v180|, 1.0
	s_nop 1
	v_cndmask_b32_e32 v184, v183, v184, vcc
	v_bfi_b32 v184, s10, v184, v180
	v_add_f32_e32 v184, 1.0, v184
	v_mul_f32_e32 v89, 0.5, v89
	v_mul_f32_e32 v57, v57, v61
	v_mul_f32_e32 v89, v89, v184
	v_mul_f32_e32 v89, v57, v89
	global_store_dword v160, v88, s[8:9]
	global_store_dword v160, v89, s[8:9] offset:256
	s_add_u32 s8, s8, s14
	s_addc_u32 s9, s9, 0
	v_mul_f32_e32 v90, v64, v90
	v_mul_f32_e32 v180, 0x3f3504f3, v90
	v_fma_f32 v182, |v180|, s12, v177
	v_fma_f32 v182, |v180|, v182, s15
	v_fma_f32 v182, |v180|, v182, s16
	v_fma_f32 v182, |v180|, v182, s17
	v_fma_f32 v182, |v180|, v182, s18
	v_fma_f32 v182, |v180|, v182, s19
	v_fma_f32 v182, |v180|, v182, |v180|
	v_mul_f32_e32 v184, 0xbfb8aa3b, v182
	v_fma_f32 v185, v182, s98, -v184
	v_rndne_f32_e32 v186, v184
	v_fmac_f32_e32 v185, 0xb2a5705f, v182
	v_sub_f32_e32 v184, v184, v186
	v_add_f32_e32 v184, v184, v185
	v_cvt_i32_f32_e32 v185, v186
	v_exp_f32_e32 v184, v184
	v_cmp_nlt_f32_e32 vcc, s38, v182
	v_ldexp_f32 v184, v184, v185
	s_nop 0
	v_cndmask_b32_e32 v184, 0, v184, vcc
	v_cmp_ngt_f32_e32 vcc, s39, v182
	s_nop 1
	v_cndmask_b32_e32 v184, v178, v184, vcc
	v_sub_f32_e32 v184, 1.0, v184
	v_mul_f32_e32 v183, v180, v180
	v_fmamk_f32 v185, v183, 0xba1345e1, v176
	v_fmaak_f32 v185, v183, v185, 0xbcdac9b8
	v_fmaak_f32 v185, v183, v185, 0x3de703be
	v_fmaak_f32 v185, v183, v185, 0xbec09330
	v_fmaak_f32 v183, v183, v185, 0x3e0375d0
	v_fma_f32 v183, |v180|, v183, |v180|
	v_cmp_nlt_f32_e64 vcc, |v180|, 1.0
	s_nop 1
	v_cndmask_b32_e32 v184, v183, v184, vcc
	v_bfi_b32 v184, s10, v184, v180
	v_add_f32_e32 v184, 1.0, v184
	v_mul_f32_e32 v90, 0.5, v90
	v_mul_f32_e32 v62, v62, v66
	v_mul_f32_e32 v90, v90, v184
	v_mul_f32_e32 v90, v62, v90
	v_mul_f32_e32 v91, v65, v91
	v_mul_f32_e32 v180, 0x3f3504f3, v91
	v_fma_f32 v182, |v180|, s12, v177
	v_fma_f32 v182, |v180|, v182, s15
	v_fma_f32 v182, |v180|, v182, s16
	v_fma_f32 v182, |v180|, v182, s17
	v_fma_f32 v182, |v180|, v182, s18
	v_fma_f32 v182, |v180|, v182, s19
	v_fma_f32 v182, |v180|, v182, |v180|
	v_mul_f32_e32 v184, 0xbfb8aa3b, v182
	v_fma_f32 v185, v182, s98, -v184
	v_rndne_f32_e32 v186, v184
	v_fmac_f32_e32 v185, 0xb2a5705f, v182
	v_sub_f32_e32 v184, v184, v186
	v_add_f32_e32 v184, v184, v185
	v_cvt_i32_f32_e32 v185, v186
	v_exp_f32_e32 v184, v184
	v_cmp_nlt_f32_e32 vcc, s38, v182
	v_ldexp_f32 v184, v184, v185
	s_nop 0
	v_cndmask_b32_e32 v184, 0, v184, vcc
	v_cmp_ngt_f32_e32 vcc, s39, v182
	s_nop 1
	v_cndmask_b32_e32 v184, v178, v184, vcc
	v_sub_f32_e32 v184, 1.0, v184
	v_mul_f32_e32 v183, v180, v180
	v_fmamk_f32 v185, v183, 0xba1345e1, v176
	v_fmaak_f32 v185, v183, v185, 0xbcdac9b8
	v_fmaak_f32 v185, v183, v185, 0x3de703be
	v_fmaak_f32 v185, v183, v185, 0xbec09330
	v_fmaak_f32 v183, v183, v185, 0x3e0375d0
	v_fma_f32 v183, |v180|, v183, |v180|
	v_cmp_nlt_f32_e64 vcc, |v180|, 1.0
	s_nop 1
	v_cndmask_b32_e32 v184, v183, v184, vcc
	v_bfi_b32 v184, s10, v184, v180
	v_add_f32_e32 v184, 1.0, v184
	v_mul_f32_e32 v91, 0.5, v91
	v_mul_f32_e32 v63, v63, v67
	v_mul_f32_e32 v91, v91, v184
	v_mul_f32_e32 v91, v63, v91
	global_store_dword v160, v90, s[8:9]
	global_store_dword v160, v91, s[8:9] offset:256
	s_add_u32 s8, s8, s14
	s_addc_u32 s9, s9, 0
	v_mul_f32_e32 v92, v70, v92
	v_mul_f32_e32 v180, 0x3f3504f3, v92
	v_fma_f32 v182, |v180|, s12, v177
	v_fma_f32 v182, |v180|, v182, s15
	v_fma_f32 v182, |v180|, v182, s16
	v_fma_f32 v182, |v180|, v182, s17
	v_fma_f32 v182, |v180|, v182, s18
	v_fma_f32 v182, |v180|, v182, s19
	v_fma_f32 v182, |v180|, v182, |v180|
	v_mul_f32_e32 v184, 0xbfb8aa3b, v182
	v_fma_f32 v185, v182, s98, -v184
	v_rndne_f32_e32 v186, v184
	v_fmac_f32_e32 v185, 0xb2a5705f, v182
	v_sub_f32_e32 v184, v184, v186
	v_add_f32_e32 v184, v184, v185
	v_cvt_i32_f32_e32 v185, v186
	v_exp_f32_e32 v184, v184
	v_cmp_nlt_f32_e32 vcc, s38, v182
	v_ldexp_f32 v184, v184, v185
	s_nop 0
	v_cndmask_b32_e32 v184, 0, v184, vcc
	v_cmp_ngt_f32_e32 vcc, s39, v182
	s_nop 1
	v_cndmask_b32_e32 v184, v178, v184, vcc
	v_sub_f32_e32 v184, 1.0, v184
	v_mul_f32_e32 v183, v180, v180
	v_fmamk_f32 v185, v183, 0xba1345e1, v176
	v_fmaak_f32 v185, v183, v185, 0xbcdac9b8
	v_fmaak_f32 v185, v183, v185, 0x3de703be
	v_fmaak_f32 v185, v183, v185, 0xbec09330
	v_fmaak_f32 v183, v183, v185, 0x3e0375d0
	v_fma_f32 v183, |v180|, v183, |v180|
	v_cmp_nlt_f32_e64 vcc, |v180|, 1.0
	s_nop 1
	v_cndmask_b32_e32 v184, v183, v184, vcc
	v_bfi_b32 v184, s10, v184, v180
	v_add_f32_e32 v184, 1.0, v184
	v_mul_f32_e32 v92, 0.5, v92
	v_mul_f32_e32 v68, v68, v72
	v_mul_f32_e32 v92, v92, v184
	v_mul_f32_e32 v92, v68, v92
	v_mul_f32_e32 v93, v71, v93
	v_mul_f32_e32 v180, 0x3f3504f3, v93
	v_fma_f32 v182, |v180|, s12, v177
	v_fma_f32 v182, |v180|, v182, s15
	v_fma_f32 v182, |v180|, v182, s16
	v_fma_f32 v182, |v180|, v182, s17
	v_fma_f32 v182, |v180|, v182, s18
	v_fma_f32 v182, |v180|, v182, s19
	v_fma_f32 v182, |v180|, v182, |v180|
	v_mul_f32_e32 v184, 0xbfb8aa3b, v182
	v_fma_f32 v185, v182, s98, -v184
	v_rndne_f32_e32 v186, v184
	v_fmac_f32_e32 v185, 0xb2a5705f, v182
	v_sub_f32_e32 v184, v184, v186
	v_add_f32_e32 v184, v184, v185
	v_cvt_i32_f32_e32 v185, v186
	v_exp_f32_e32 v184, v184
	v_cmp_nlt_f32_e32 vcc, s38, v182
	v_ldexp_f32 v184, v184, v185
	s_nop 0
	v_cndmask_b32_e32 v184, 0, v184, vcc
	v_cmp_ngt_f32_e32 vcc, s39, v182
	s_nop 1
	v_cndmask_b32_e32 v184, v178, v184, vcc
	v_sub_f32_e32 v184, 1.0, v184
	v_mul_f32_e32 v183, v180, v180
	v_fmamk_f32 v185, v183, 0xba1345e1, v176
	v_fmaak_f32 v185, v183, v185, 0xbcdac9b8
	v_fmaak_f32 v185, v183, v185, 0x3de703be
	v_fmaak_f32 v185, v183, v185, 0xbec09330
	v_fmaak_f32 v183, v183, v185, 0x3e0375d0
	v_fma_f32 v183, |v180|, v183, |v180|
	v_cmp_nlt_f32_e64 vcc, |v180|, 1.0
	s_nop 1
	v_cndmask_b32_e32 v184, v183, v184, vcc
	v_bfi_b32 v184, s10, v184, v180
	v_add_f32_e32 v184, 1.0, v184
	v_mul_f32_e32 v93, 0.5, v93
	v_mul_f32_e32 v69, v69, v73
	v_mul_f32_e32 v93, v93, v184
	v_mul_f32_e32 v93, v69, v93
	global_store_dword v160, v92, s[8:9]
	global_store_dword v160, v93, s[8:9] offset:256
	s_add_u32 s8, s8, s14
	s_addc_u32 s9, s9, 0
	v_mul_f32_e32 v94, v76, v94
	v_mul_f32_e32 v180, 0x3f3504f3, v94
	v_fma_f32 v182, |v180|, s12, v177
	v_fma_f32 v182, |v180|, v182, s15
	v_fma_f32 v182, |v180|, v182, s16
	v_fma_f32 v182, |v180|, v182, s17
	v_fma_f32 v182, |v180|, v182, s18
	v_fma_f32 v182, |v180|, v182, s19
	v_fma_f32 v182, |v180|, v182, |v180|
	v_mul_f32_e32 v184, 0xbfb8aa3b, v182
	v_fma_f32 v185, v182, s98, -v184
	v_rndne_f32_e32 v186, v184
	v_fmac_f32_e32 v185, 0xb2a5705f, v182
	v_sub_f32_e32 v184, v184, v186
	v_add_f32_e32 v184, v184, v185
	v_cvt_i32_f32_e32 v185, v186
	v_exp_f32_e32 v184, v184
	v_cmp_nlt_f32_e32 vcc, s38, v182
	v_ldexp_f32 v184, v184, v185
	s_nop 0
	v_cndmask_b32_e32 v184, 0, v184, vcc
	v_cmp_ngt_f32_e32 vcc, s39, v182
	s_nop 1
	v_cndmask_b32_e32 v184, v178, v184, vcc
	v_sub_f32_e32 v184, 1.0, v184
	v_mul_f32_e32 v183, v180, v180
	v_fmamk_f32 v185, v183, 0xba1345e1, v176
	v_fmaak_f32 v185, v183, v185, 0xbcdac9b8
	v_fmaak_f32 v185, v183, v185, 0x3de703be
	v_fmaak_f32 v185, v183, v185, 0xbec09330
	v_fmaak_f32 v183, v183, v185, 0x3e0375d0
	v_fma_f32 v183, |v180|, v183, |v180|
	v_cmp_nlt_f32_e64 vcc, |v180|, 1.0
	s_nop 1
	v_cndmask_b32_e32 v184, v183, v184, vcc
	v_bfi_b32 v184, s10, v184, v180
	v_add_f32_e32 v184, 1.0, v184
	v_mul_f32_e32 v94, 0.5, v94
	v_mul_f32_e32 v74, v74, v78
	v_mul_f32_e32 v94, v94, v184
	v_mul_f32_e32 v94, v74, v94
	v_mul_f32_e32 v95, v77, v95
	v_mul_f32_e32 v180, 0x3f3504f3, v95
	v_fma_f32 v182, |v180|, s12, v177
	v_fma_f32 v182, |v180|, v182, s15
	v_fma_f32 v182, |v180|, v182, s16
	v_fma_f32 v182, |v180|, v182, s17
	v_fma_f32 v182, |v180|, v182, s18
	v_fma_f32 v182, |v180|, v182, s19
	v_fma_f32 v182, |v180|, v182, |v180|
	v_mul_f32_e32 v184, 0xbfb8aa3b, v182
	v_fma_f32 v185, v182, s98, -v184
	v_rndne_f32_e32 v186, v184
	v_fmac_f32_e32 v185, 0xb2a5705f, v182
	v_sub_f32_e32 v184, v184, v186
	v_add_f32_e32 v184, v184, v185
	v_cvt_i32_f32_e32 v185, v186
	v_exp_f32_e32 v184, v184
	v_cmp_nlt_f32_e32 vcc, s38, v182
	v_ldexp_f32 v184, v184, v185
	s_nop 0
	v_cndmask_b32_e32 v184, 0, v184, vcc
	v_cmp_ngt_f32_e32 vcc, s39, v182
	s_nop 1
	v_cndmask_b32_e32 v184, v178, v184, vcc
	v_sub_f32_e32 v184, 1.0, v184
	v_mul_f32_e32 v183, v180, v180
	v_fmamk_f32 v185, v183, 0xba1345e1, v176
	v_fmaak_f32 v185, v183, v185, 0xbcdac9b8
	v_fmaak_f32 v185, v183, v185, 0x3de703be
	v_fmaak_f32 v185, v183, v185, 0xbec09330
	v_fmaak_f32 v183, v183, v185, 0x3e0375d0
	v_fma_f32 v183, |v180|, v183, |v180|
	v_cmp_nlt_f32_e64 vcc, |v180|, 1.0
	s_nop 1
	v_cndmask_b32_e32 v184, v183, v184, vcc
	v_bfi_b32 v184, s10, v184, v180
	v_add_f32_e32 v184, 1.0, v184
	v_mul_f32_e32 v95, 0.5, v95
	v_mul_f32_e32 v75, v75, v79
	v_mul_f32_e32 v95, v95, v184
	v_mul_f32_e32 v95, v75, v95
	global_store_dword v160, v94, s[8:9]
	global_store_dword v160, v95, s[8:9] offset:256
	s_add_u32 s8, s8, s14
	s_addc_u32 s9, s9, 0
	ds_read2st64_b32 v[16:17], v174 offset0:16 offset1:17
	ds_read2st64_b32 v[80:81], v175 offset0:16 offset1:17
	ds_read2st64_b32 v[18:19], v174 offset0:18 offset1:19
	ds_read2st64_b32 v[82:83], v175 offset0:18 offset1:19
	ds_read2st64_b32 v[20:21], v174 offset0:20 offset1:21
	ds_read2st64_b32 v[84:85], v175 offset0:20 offset1:21
	ds_read2st64_b32 v[22:23], v174 offset0:22 offset1:23
	ds_read2st64_b32 v[86:87], v175 offset0:22 offset1:23
	ds_read2st64_b32 v[24:25], v174 offset0:24 offset1:25
	ds_read2st64_b32 v[88:89], v175 offset0:24 offset1:25
	ds_read2st64_b32 v[26:27], v174 offset0:26 offset1:27
	ds_read2st64_b32 v[90:91], v175 offset0:26 offset1:27
	ds_read2st64_b32 v[28:29], v174 offset0:28 offset1:29
	ds_read2st64_b32 v[92:93], v175 offset0:28 offset1:29
	ds_read2st64_b32 v[30:31], v174 offset0:30 offset1:31
	ds_read2st64_b32 v[94:95], v175 offset0:30 offset1:31
	s_waitcnt lgkmcnt(0)
	v_lshlrev_b32_e32 v16, 2, v16
	v_lshlrev_b32_e32 v17, 2, v17
	v_lshlrev_b32_e32 v18, 2, v18
	v_lshlrev_b32_e32 v19, 2, v19
	v_lshlrev_b32_e32 v20, 2, v20
	v_lshlrev_b32_e32 v21, 2, v21
	v_lshlrev_b32_e32 v22, 2, v22
	v_lshlrev_b32_e32 v23, 2, v23
	v_lshlrev_b32_e32 v24, 2, v24
	v_lshlrev_b32_e32 v25, 2, v25
	v_lshlrev_b32_e32 v26, 2, v26
	v_lshlrev_b32_e32 v27, 2, v27
	v_lshlrev_b32_e32 v28, 2, v28
	v_lshlrev_b32_e32 v29, 2, v29
	v_lshlrev_b32_e32 v30, 2, v30
	v_lshlrev_b32_e32 v31, 2, v31
	global_load_dword v32, v160, s[6:7]
	global_load_dword v33, v160, s[6:7] offset:256
	global_load_dword v34, v16, s[0:1]
	global_load_dword v35, v17, s[0:1]
	global_load_dword v36, v16, s[4:5]
	global_load_dword v37, v17, s[4:5]
	s_add_u32 s6, s6, s14
	s_addc_u32 s7, s7, 0
	global_load_dword v38, v160, s[6:7]
	global_load_dword v39, v160, s[6:7] offset:256
	global_load_dword v40, v18, s[0:1]
	global_load_dword v41, v19, s[0:1]
	global_load_dword v42, v18, s[4:5]
	global_load_dword v43, v19, s[4:5]
	s_add_u32 s6, s6, s14
	s_addc_u32 s7, s7, 0
	global_load_dword v44, v160, s[6:7]
	global_load_dword v45, v160, s[6:7] offset:256
	global_load_dword v46, v20, s[0:1]
	global_load_dword v47, v21, s[0:1]
	global_load_dword v48, v20, s[4:5]
	global_load_dword v49, v21, s[4:5]
	s_add_u32 s6, s6, s14
	s_addc_u32 s7, s7, 0
	global_load_dword v50, v160, s[6:7]
	global_load_dword v51, v160, s[6:7] offset:256
	global_load_dword v52, v22, s[0:1]
	global_load_dword v53, v23, s[0:1]
	global_load_dword v54, v22, s[4:5]
	global_load_dword v55, v23, s[4:5]
	s_add_u32 s6, s6, s14
	s_addc_u32 s7, s7, 0
	global_load_dword v56, v160, s[6:7]
	global_load_dword v57, v160, s[6:7] offset:256
	global_load_dword v58, v24, s[0:1]
	global_load_dword v59, v25, s[0:1]
	global_load_dword v60, v24, s[4:5]
	global_load_dword v61, v25, s[4:5]
	s_add_u32 s6, s6, s14
	s_addc_u32 s7, s7, 0
	global_load_dword v62, v160, s[6:7]
	global_load_dword v63, v160, s[6:7] offset:256
	global_load_dword v64, v26, s[0:1]
	global_load_dword v65, v27, s[0:1]
	global_load_dword v66, v26, s[4:5]
	global_load_dword v67, v27, s[4:5]
	s_add_u32 s6, s6, s14
	s_addc_u32 s7, s7, 0
	global_load_dword v68, v160, s[6:7]
	global_load_dword v69, v160, s[6:7] offset:256
	global_load_dword v70, v28, s[0:1]
	global_load_dword v71, v29, s[0:1]
	global_load_dword v72, v28, s[4:5]
	global_load_dword v73, v29, s[4:5]
	s_add_u32 s6, s6, s14
	s_addc_u32 s7, s7, 0
	global_load_dword v74, v160, s[6:7]
	global_load_dword v75, v160, s[6:7] offset:256
	global_load_dword v76, v30, s[0:1]
	global_load_dword v77, v31, s[0:1]
	global_load_dword v78, v30, s[4:5]
	global_load_dword v79, v31, s[4:5]
	s_add_u32 s6, s6, s14
	s_addc_u32 s7, s7, 0
	s_waitcnt vmcnt(0)
	v_mul_f32_e32 v80, v34, v80
	v_mul_f32_e32 v180, 0x3f3504f3, v80
	v_fma_f32 v182, |v180|, s12, v177
	v_fma_f32 v182, |v180|, v182, s15
	v_fma_f32 v182, |v180|, v182, s16
	v_fma_f32 v182, |v180|, v182, s17
	v_fma_f32 v182, |v180|, v182, s18
	v_fma_f32 v182, |v180|, v182, s19
	v_fma_f32 v182, |v180|, v182, |v180|
	v_mul_f32_e32 v184, 0xbfb8aa3b, v182
	v_fma_f32 v185, v182, s98, -v184
	v_rndne_f32_e32 v186, v184
	v_fmac_f32_e32 v185, 0xb2a5705f, v182
	v_sub_f32_e32 v184, v184, v186
	v_add_f32_e32 v184, v184, v185
	v_cvt_i32_f32_e32 v185, v186
	v_exp_f32_e32 v184, v184
	v_cmp_nlt_f32_e32 vcc, s38, v182
	v_ldexp_f32 v184, v184, v185
	s_nop 0
	v_cndmask_b32_e32 v184, 0, v184, vcc
	v_cmp_ngt_f32_e32 vcc, s39, v182
	s_nop 1
	v_cndmask_b32_e32 v184, v178, v184, vcc
	v_sub_f32_e32 v184, 1.0, v184
	v_mul_f32_e32 v183, v180, v180
	v_fmamk_f32 v185, v183, 0xba1345e1, v176
	v_fmaak_f32 v185, v183, v185, 0xbcdac9b8
	v_fmaak_f32 v185, v183, v185, 0x3de703be
	v_fmaak_f32 v185, v183, v185, 0xbec09330
	v_fmaak_f32 v183, v183, v185, 0x3e0375d0
	v_fma_f32 v183, |v180|, v183, |v180|
	v_cmp_nlt_f32_e64 vcc, |v180|, 1.0
	s_nop 1
	v_cndmask_b32_e32 v184, v183, v184, vcc
	v_bfi_b32 v184, s10, v184, v180
	v_add_f32_e32 v184, 1.0, v184
	v_mul_f32_e32 v80, 0.5, v80
	v_mul_f32_e32 v32, v32, v36
	v_mul_f32_e32 v80, v80, v184
	v_mul_f32_e32 v80, v32, v80
	v_mul_f32_e32 v81, v35, v81
	v_mul_f32_e32 v180, 0x3f3504f3, v81
	v_fma_f32 v182, |v180|, s12, v177
	v_fma_f32 v182, |v180|, v182, s15
	v_fma_f32 v182, |v180|, v182, s16
	v_fma_f32 v182, |v180|, v182, s17
	v_fma_f32 v182, |v180|, v182, s18
	v_fma_f32 v182, |v180|, v182, s19
	v_fma_f32 v182, |v180|, v182, |v180|
	v_mul_f32_e32 v184, 0xbfb8aa3b, v182
	v_fma_f32 v185, v182, s98, -v184
	v_rndne_f32_e32 v186, v184
	v_fmac_f32_e32 v185, 0xb2a5705f, v182
	v_sub_f32_e32 v184, v184, v186
	v_add_f32_e32 v184, v184, v185
	v_cvt_i32_f32_e32 v185, v186
	v_exp_f32_e32 v184, v184
	v_cmp_nlt_f32_e32 vcc, s38, v182
	v_ldexp_f32 v184, v184, v185
	s_nop 0
	v_cndmask_b32_e32 v184, 0, v184, vcc
	v_cmp_ngt_f32_e32 vcc, s39, v182
	s_nop 1
	v_cndmask_b32_e32 v184, v178, v184, vcc
	v_sub_f32_e32 v184, 1.0, v184
	v_mul_f32_e32 v183, v180, v180
	v_fmamk_f32 v185, v183, 0xba1345e1, v176
	v_fmaak_f32 v185, v183, v185, 0xbcdac9b8
	v_fmaak_f32 v185, v183, v185, 0x3de703be
	v_fmaak_f32 v185, v183, v185, 0xbec09330
	v_fmaak_f32 v183, v183, v185, 0x3e0375d0
	v_fma_f32 v183, |v180|, v183, |v180|
	v_cmp_nlt_f32_e64 vcc, |v180|, 1.0
	s_nop 1
	v_cndmask_b32_e32 v184, v183, v184, vcc
	v_bfi_b32 v184, s10, v184, v180
	v_add_f32_e32 v184, 1.0, v184
	v_mul_f32_e32 v81, 0.5, v81
	v_mul_f32_e32 v33, v33, v37
	v_mul_f32_e32 v81, v81, v184
	v_mul_f32_e32 v81, v33, v81
	global_store_dword v160, v80, s[8:9]
	global_store_dword v160, v81, s[8:9] offset:256
	s_add_u32 s8, s8, s14
	s_addc_u32 s9, s9, 0
	v_mul_f32_e32 v82, v40, v82
	v_mul_f32_e32 v180, 0x3f3504f3, v82
	v_fma_f32 v182, |v180|, s12, v177
	v_fma_f32 v182, |v180|, v182, s15
	v_fma_f32 v182, |v180|, v182, s16
	v_fma_f32 v182, |v180|, v182, s17
	v_fma_f32 v182, |v180|, v182, s18
	v_fma_f32 v182, |v180|, v182, s19
	v_fma_f32 v182, |v180|, v182, |v180|
	v_mul_f32_e32 v184, 0xbfb8aa3b, v182
	v_fma_f32 v185, v182, s98, -v184
	v_rndne_f32_e32 v186, v184
	v_fmac_f32_e32 v185, 0xb2a5705f, v182
	v_sub_f32_e32 v184, v184, v186
	v_add_f32_e32 v184, v184, v185
	v_cvt_i32_f32_e32 v185, v186
	v_exp_f32_e32 v184, v184
	v_cmp_nlt_f32_e32 vcc, s38, v182
	v_ldexp_f32 v184, v184, v185
	s_nop 0
	v_cndmask_b32_e32 v184, 0, v184, vcc
	v_cmp_ngt_f32_e32 vcc, s39, v182
	s_nop 1
	v_cndmask_b32_e32 v184, v178, v184, vcc
	v_sub_f32_e32 v184, 1.0, v184
	v_mul_f32_e32 v183, v180, v180
	v_fmamk_f32 v185, v183, 0xba1345e1, v176
	v_fmaak_f32 v185, v183, v185, 0xbcdac9b8
	v_fmaak_f32 v185, v183, v185, 0x3de703be
	v_fmaak_f32 v185, v183, v185, 0xbec09330
	v_fmaak_f32 v183, v183, v185, 0x3e0375d0
	v_fma_f32 v183, |v180|, v183, |v180|
	v_cmp_nlt_f32_e64 vcc, |v180|, 1.0
	s_nop 1
	v_cndmask_b32_e32 v184, v183, v184, vcc
	v_bfi_b32 v184, s10, v184, v180
	v_add_f32_e32 v184, 1.0, v184
	v_mul_f32_e32 v82, 0.5, v82
	v_mul_f32_e32 v38, v38, v42
	v_mul_f32_e32 v82, v82, v184
	v_mul_f32_e32 v82, v38, v82
	v_mul_f32_e32 v83, v41, v83
	v_mul_f32_e32 v180, 0x3f3504f3, v83
	v_fma_f32 v182, |v180|, s12, v177
	v_fma_f32 v182, |v180|, v182, s15
	v_fma_f32 v182, |v180|, v182, s16
	v_fma_f32 v182, |v180|, v182, s17
	v_fma_f32 v182, |v180|, v182, s18
	v_fma_f32 v182, |v180|, v182, s19
	v_fma_f32 v182, |v180|, v182, |v180|
	v_mul_f32_e32 v184, 0xbfb8aa3b, v182
	v_fma_f32 v185, v182, s98, -v184
	v_rndne_f32_e32 v186, v184
	v_fmac_f32_e32 v185, 0xb2a5705f, v182
	v_sub_f32_e32 v184, v184, v186
	v_add_f32_e32 v184, v184, v185
	v_cvt_i32_f32_e32 v185, v186
	v_exp_f32_e32 v184, v184
	v_cmp_nlt_f32_e32 vcc, s38, v182
	v_ldexp_f32 v184, v184, v185
	s_nop 0
	v_cndmask_b32_e32 v184, 0, v184, vcc
	v_cmp_ngt_f32_e32 vcc, s39, v182
	s_nop 1
	v_cndmask_b32_e32 v184, v178, v184, vcc
	v_sub_f32_e32 v184, 1.0, v184
	v_mul_f32_e32 v183, v180, v180
	v_fmamk_f32 v185, v183, 0xba1345e1, v176
	v_fmaak_f32 v185, v183, v185, 0xbcdac9b8
	v_fmaak_f32 v185, v183, v185, 0x3de703be
	v_fmaak_f32 v185, v183, v185, 0xbec09330
	v_fmaak_f32 v183, v183, v185, 0x3e0375d0
	v_fma_f32 v183, |v180|, v183, |v180|
	v_cmp_nlt_f32_e64 vcc, |v180|, 1.0
	s_nop 1
	v_cndmask_b32_e32 v184, v183, v184, vcc
	v_bfi_b32 v184, s10, v184, v180
	v_add_f32_e32 v184, 1.0, v184
	v_mul_f32_e32 v83, 0.5, v83
	v_mul_f32_e32 v39, v39, v43
	v_mul_f32_e32 v83, v83, v184
	v_mul_f32_e32 v83, v39, v83
	global_store_dword v160, v82, s[8:9]
	global_store_dword v160, v83, s[8:9] offset:256
	s_add_u32 s8, s8, s14
	s_addc_u32 s9, s9, 0
	v_mul_f32_e32 v84, v46, v84
	v_mul_f32_e32 v180, 0x3f3504f3, v84
	v_fma_f32 v182, |v180|, s12, v177
	v_fma_f32 v182, |v180|, v182, s15
	v_fma_f32 v182, |v180|, v182, s16
	v_fma_f32 v182, |v180|, v182, s17
	v_fma_f32 v182, |v180|, v182, s18
	v_fma_f32 v182, |v180|, v182, s19
	v_fma_f32 v182, |v180|, v182, |v180|
	v_mul_f32_e32 v184, 0xbfb8aa3b, v182
	v_fma_f32 v185, v182, s98, -v184
	v_rndne_f32_e32 v186, v184
	v_fmac_f32_e32 v185, 0xb2a5705f, v182
	v_sub_f32_e32 v184, v184, v186
	v_add_f32_e32 v184, v184, v185
	v_cvt_i32_f32_e32 v185, v186
	v_exp_f32_e32 v184, v184
	v_cmp_nlt_f32_e32 vcc, s38, v182
	v_ldexp_f32 v184, v184, v185
	s_nop 0
	v_cndmask_b32_e32 v184, 0, v184, vcc
	v_cmp_ngt_f32_e32 vcc, s39, v182
	s_nop 1
	v_cndmask_b32_e32 v184, v178, v184, vcc
	v_sub_f32_e32 v184, 1.0, v184
	v_mul_f32_e32 v183, v180, v180
	v_fmamk_f32 v185, v183, 0xba1345e1, v176
	v_fmaak_f32 v185, v183, v185, 0xbcdac9b8
	v_fmaak_f32 v185, v183, v185, 0x3de703be
	v_fmaak_f32 v185, v183, v185, 0xbec09330
	v_fmaak_f32 v183, v183, v185, 0x3e0375d0
	v_fma_f32 v183, |v180|, v183, |v180|
	v_cmp_nlt_f32_e64 vcc, |v180|, 1.0
	s_nop 1
	v_cndmask_b32_e32 v184, v183, v184, vcc
	v_bfi_b32 v184, s10, v184, v180
	v_add_f32_e32 v184, 1.0, v184
	v_mul_f32_e32 v84, 0.5, v84
	v_mul_f32_e32 v44, v44, v48
	v_mul_f32_e32 v84, v84, v184
	v_mul_f32_e32 v84, v44, v84
	v_mul_f32_e32 v85, v47, v85
	v_mul_f32_e32 v180, 0x3f3504f3, v85
	v_fma_f32 v182, |v180|, s12, v177
	v_fma_f32 v182, |v180|, v182, s15
	v_fma_f32 v182, |v180|, v182, s16
	v_fma_f32 v182, |v180|, v182, s17
	v_fma_f32 v182, |v180|, v182, s18
	v_fma_f32 v182, |v180|, v182, s19
	v_fma_f32 v182, |v180|, v182, |v180|
	v_mul_f32_e32 v184, 0xbfb8aa3b, v182
	v_fma_f32 v185, v182, s98, -v184
	v_rndne_f32_e32 v186, v184
	v_fmac_f32_e32 v185, 0xb2a5705f, v182
	v_sub_f32_e32 v184, v184, v186
	v_add_f32_e32 v184, v184, v185
	v_cvt_i32_f32_e32 v185, v186
	v_exp_f32_e32 v184, v184
	v_cmp_nlt_f32_e32 vcc, s38, v182
	v_ldexp_f32 v184, v184, v185
	s_nop 0
	v_cndmask_b32_e32 v184, 0, v184, vcc
	v_cmp_ngt_f32_e32 vcc, s39, v182
	s_nop 1
	v_cndmask_b32_e32 v184, v178, v184, vcc
	v_sub_f32_e32 v184, 1.0, v184
	v_mul_f32_e32 v183, v180, v180
	v_fmamk_f32 v185, v183, 0xba1345e1, v176
	v_fmaak_f32 v185, v183, v185, 0xbcdac9b8
	v_fmaak_f32 v185, v183, v185, 0x3de703be
	v_fmaak_f32 v185, v183, v185, 0xbec09330
	v_fmaak_f32 v183, v183, v185, 0x3e0375d0
	v_fma_f32 v183, |v180|, v183, |v180|
	v_cmp_nlt_f32_e64 vcc, |v180|, 1.0
	s_nop 1
	v_cndmask_b32_e32 v184, v183, v184, vcc
	v_bfi_b32 v184, s10, v184, v180
	v_add_f32_e32 v184, 1.0, v184
	v_mul_f32_e32 v85, 0.5, v85
	v_mul_f32_e32 v45, v45, v49
	v_mul_f32_e32 v85, v85, v184
	v_mul_f32_e32 v85, v45, v85
	global_store_dword v160, v84, s[8:9]
	global_store_dword v160, v85, s[8:9] offset:256
	s_add_u32 s8, s8, s14
	s_addc_u32 s9, s9, 0
	v_mul_f32_e32 v86, v52, v86
	v_mul_f32_e32 v180, 0x3f3504f3, v86
	v_fma_f32 v182, |v180|, s12, v177
	v_fma_f32 v182, |v180|, v182, s15
	v_fma_f32 v182, |v180|, v182, s16
	v_fma_f32 v182, |v180|, v182, s17
	v_fma_f32 v182, |v180|, v182, s18
	v_fma_f32 v182, |v180|, v182, s19
	v_fma_f32 v182, |v180|, v182, |v180|
	v_mul_f32_e32 v184, 0xbfb8aa3b, v182
	v_fma_f32 v185, v182, s98, -v184
	v_rndne_f32_e32 v186, v184
	v_fmac_f32_e32 v185, 0xb2a5705f, v182
	v_sub_f32_e32 v184, v184, v186
	v_add_f32_e32 v184, v184, v185
	v_cvt_i32_f32_e32 v185, v186
	v_exp_f32_e32 v184, v184
	v_cmp_nlt_f32_e32 vcc, s38, v182
	v_ldexp_f32 v184, v184, v185
	s_nop 0
	v_cndmask_b32_e32 v184, 0, v184, vcc
	v_cmp_ngt_f32_e32 vcc, s39, v182
	s_nop 1
	v_cndmask_b32_e32 v184, v178, v184, vcc
	v_sub_f32_e32 v184, 1.0, v184
	v_mul_f32_e32 v183, v180, v180
	v_fmamk_f32 v185, v183, 0xba1345e1, v176
	v_fmaak_f32 v185, v183, v185, 0xbcdac9b8
	v_fmaak_f32 v185, v183, v185, 0x3de703be
	v_fmaak_f32 v185, v183, v185, 0xbec09330
	v_fmaak_f32 v183, v183, v185, 0x3e0375d0
	v_fma_f32 v183, |v180|, v183, |v180|
	v_cmp_nlt_f32_e64 vcc, |v180|, 1.0
	s_nop 1
	v_cndmask_b32_e32 v184, v183, v184, vcc
	v_bfi_b32 v184, s10, v184, v180
	v_add_f32_e32 v184, 1.0, v184
	v_mul_f32_e32 v86, 0.5, v86
	v_mul_f32_e32 v50, v50, v54
	v_mul_f32_e32 v86, v86, v184
	v_mul_f32_e32 v86, v50, v86
	v_mul_f32_e32 v87, v53, v87
	v_mul_f32_e32 v180, 0x3f3504f3, v87
	v_fma_f32 v182, |v180|, s12, v177
	v_fma_f32 v182, |v180|, v182, s15
	v_fma_f32 v182, |v180|, v182, s16
	v_fma_f32 v182, |v180|, v182, s17
	v_fma_f32 v182, |v180|, v182, s18
	v_fma_f32 v182, |v180|, v182, s19
	v_fma_f32 v182, |v180|, v182, |v180|
	v_mul_f32_e32 v184, 0xbfb8aa3b, v182
	v_fma_f32 v185, v182, s98, -v184
	v_rndne_f32_e32 v186, v184
	v_fmac_f32_e32 v185, 0xb2a5705f, v182
	v_sub_f32_e32 v184, v184, v186
	v_add_f32_e32 v184, v184, v185
	v_cvt_i32_f32_e32 v185, v186
	v_exp_f32_e32 v184, v184
	v_cmp_nlt_f32_e32 vcc, s38, v182
	v_ldexp_f32 v184, v184, v185
	s_nop 0
	v_cndmask_b32_e32 v184, 0, v184, vcc
	v_cmp_ngt_f32_e32 vcc, s39, v182
	s_nop 1
	v_cndmask_b32_e32 v184, v178, v184, vcc
	v_sub_f32_e32 v184, 1.0, v184
	v_mul_f32_e32 v183, v180, v180
	v_fmamk_f32 v185, v183, 0xba1345e1, v176
	v_fmaak_f32 v185, v183, v185, 0xbcdac9b8
	v_fmaak_f32 v185, v183, v185, 0x3de703be
	v_fmaak_f32 v185, v183, v185, 0xbec09330
	v_fmaak_f32 v183, v183, v185, 0x3e0375d0
	v_fma_f32 v183, |v180|, v183, |v180|
	v_cmp_nlt_f32_e64 vcc, |v180|, 1.0
	s_nop 1
	v_cndmask_b32_e32 v184, v183, v184, vcc
	v_bfi_b32 v184, s10, v184, v180
	v_add_f32_e32 v184, 1.0, v184
	v_mul_f32_e32 v87, 0.5, v87
	v_mul_f32_e32 v51, v51, v55
	v_mul_f32_e32 v87, v87, v184
	v_mul_f32_e32 v87, v51, v87
	global_store_dword v160, v86, s[8:9]
	global_store_dword v160, v87, s[8:9] offset:256
	s_add_u32 s8, s8, s14
	s_addc_u32 s9, s9, 0
	v_mul_f32_e32 v88, v58, v88
	v_mul_f32_e32 v180, 0x3f3504f3, v88
	v_fma_f32 v182, |v180|, s12, v177
	v_fma_f32 v182, |v180|, v182, s15
	v_fma_f32 v182, |v180|, v182, s16
	v_fma_f32 v182, |v180|, v182, s17
	v_fma_f32 v182, |v180|, v182, s18
	v_fma_f32 v182, |v180|, v182, s19
	v_fma_f32 v182, |v180|, v182, |v180|
	v_mul_f32_e32 v184, 0xbfb8aa3b, v182
	v_fma_f32 v185, v182, s98, -v184
	v_rndne_f32_e32 v186, v184
	v_fmac_f32_e32 v185, 0xb2a5705f, v182
	v_sub_f32_e32 v184, v184, v186
	v_add_f32_e32 v184, v184, v185
	v_cvt_i32_f32_e32 v185, v186
	v_exp_f32_e32 v184, v184
	v_cmp_nlt_f32_e32 vcc, s38, v182
	v_ldexp_f32 v184, v184, v185
	s_nop 0
	v_cndmask_b32_e32 v184, 0, v184, vcc
	v_cmp_ngt_f32_e32 vcc, s39, v182
	s_nop 1
	v_cndmask_b32_e32 v184, v178, v184, vcc
	v_sub_f32_e32 v184, 1.0, v184
	v_mul_f32_e32 v183, v180, v180
	v_fmamk_f32 v185, v183, 0xba1345e1, v176
	v_fmaak_f32 v185, v183, v185, 0xbcdac9b8
	v_fmaak_f32 v185, v183, v185, 0x3de703be
	v_fmaak_f32 v185, v183, v185, 0xbec09330
	v_fmaak_f32 v183, v183, v185, 0x3e0375d0
	v_fma_f32 v183, |v180|, v183, |v180|
	v_cmp_nlt_f32_e64 vcc, |v180|, 1.0
	s_nop 1
	v_cndmask_b32_e32 v184, v183, v184, vcc
	v_bfi_b32 v184, s10, v184, v180
	v_add_f32_e32 v184, 1.0, v184
	v_mul_f32_e32 v88, 0.5, v88
	v_mul_f32_e32 v56, v56, v60
	v_mul_f32_e32 v88, v88, v184
	v_mul_f32_e32 v88, v56, v88
	v_mul_f32_e32 v89, v59, v89
	v_mul_f32_e32 v180, 0x3f3504f3, v89
	v_fma_f32 v182, |v180|, s12, v177
	v_fma_f32 v182, |v180|, v182, s15
	v_fma_f32 v182, |v180|, v182, s16
	v_fma_f32 v182, |v180|, v182, s17
	v_fma_f32 v182, |v180|, v182, s18
	v_fma_f32 v182, |v180|, v182, s19
	v_fma_f32 v182, |v180|, v182, |v180|
	v_mul_f32_e32 v184, 0xbfb8aa3b, v182
	v_fma_f32 v185, v182, s98, -v184
	v_rndne_f32_e32 v186, v184
	v_fmac_f32_e32 v185, 0xb2a5705f, v182
	v_sub_f32_e32 v184, v184, v186
	v_add_f32_e32 v184, v184, v185
	v_cvt_i32_f32_e32 v185, v186
	v_exp_f32_e32 v184, v184
	v_cmp_nlt_f32_e32 vcc, s38, v182
	v_ldexp_f32 v184, v184, v185
	s_nop 0
	v_cndmask_b32_e32 v184, 0, v184, vcc
	v_cmp_ngt_f32_e32 vcc, s39, v182
	s_nop 1
	v_cndmask_b32_e32 v184, v178, v184, vcc
	v_sub_f32_e32 v184, 1.0, v184
	v_mul_f32_e32 v183, v180, v180
	v_fmamk_f32 v185, v183, 0xba1345e1, v176
	v_fmaak_f32 v185, v183, v185, 0xbcdac9b8
	v_fmaak_f32 v185, v183, v185, 0x3de703be
	v_fmaak_f32 v185, v183, v185, 0xbec09330
	v_fmaak_f32 v183, v183, v185, 0x3e0375d0
	v_fma_f32 v183, |v180|, v183, |v180|
	v_cmp_nlt_f32_e64 vcc, |v180|, 1.0
	s_nop 1
	v_cndmask_b32_e32 v184, v183, v184, vcc
	v_bfi_b32 v184, s10, v184, v180
	v_add_f32_e32 v184, 1.0, v184
	v_mul_f32_e32 v89, 0.5, v89
	v_mul_f32_e32 v57, v57, v61
	v_mul_f32_e32 v89, v89, v184
	v_mul_f32_e32 v89, v57, v89
	global_store_dword v160, v88, s[8:9]
	global_store_dword v160, v89, s[8:9] offset:256
	s_add_u32 s8, s8, s14
	s_addc_u32 s9, s9, 0
	v_mul_f32_e32 v90, v64, v90
	v_mul_f32_e32 v180, 0x3f3504f3, v90
	v_fma_f32 v182, |v180|, s12, v177
	v_fma_f32 v182, |v180|, v182, s15
	v_fma_f32 v182, |v180|, v182, s16
	v_fma_f32 v182, |v180|, v182, s17
	v_fma_f32 v182, |v180|, v182, s18
	v_fma_f32 v182, |v180|, v182, s19
	v_fma_f32 v182, |v180|, v182, |v180|
	v_mul_f32_e32 v184, 0xbfb8aa3b, v182
	v_fma_f32 v185, v182, s98, -v184
	v_rndne_f32_e32 v186, v184
	v_fmac_f32_e32 v185, 0xb2a5705f, v182
	v_sub_f32_e32 v184, v184, v186
	v_add_f32_e32 v184, v184, v185
	v_cvt_i32_f32_e32 v185, v186
	v_exp_f32_e32 v184, v184
	v_cmp_nlt_f32_e32 vcc, s38, v182
	v_ldexp_f32 v184, v184, v185
	s_nop 0
	v_cndmask_b32_e32 v184, 0, v184, vcc
	v_cmp_ngt_f32_e32 vcc, s39, v182
	s_nop 1
	v_cndmask_b32_e32 v184, v178, v184, vcc
	v_sub_f32_e32 v184, 1.0, v184
	v_mul_f32_e32 v183, v180, v180
	v_fmamk_f32 v185, v183, 0xba1345e1, v176
	v_fmaak_f32 v185, v183, v185, 0xbcdac9b8
	v_fmaak_f32 v185, v183, v185, 0x3de703be
	v_fmaak_f32 v185, v183, v185, 0xbec09330
	v_fmaak_f32 v183, v183, v185, 0x3e0375d0
	v_fma_f32 v183, |v180|, v183, |v180|
	v_cmp_nlt_f32_e64 vcc, |v180|, 1.0
	s_nop 1
	v_cndmask_b32_e32 v184, v183, v184, vcc
	v_bfi_b32 v184, s10, v184, v180
	v_add_f32_e32 v184, 1.0, v184
	v_mul_f32_e32 v90, 0.5, v90
	v_mul_f32_e32 v62, v62, v66
	v_mul_f32_e32 v90, v90, v184
	v_mul_f32_e32 v90, v62, v90
	v_mul_f32_e32 v91, v65, v91
	v_mul_f32_e32 v180, 0x3f3504f3, v91
	v_fma_f32 v182, |v180|, s12, v177
	v_fma_f32 v182, |v180|, v182, s15
	v_fma_f32 v182, |v180|, v182, s16
	v_fma_f32 v182, |v180|, v182, s17
	v_fma_f32 v182, |v180|, v182, s18
	v_fma_f32 v182, |v180|, v182, s19
	v_fma_f32 v182, |v180|, v182, |v180|
	v_mul_f32_e32 v184, 0xbfb8aa3b, v182
	v_fma_f32 v185, v182, s98, -v184
	v_rndne_f32_e32 v186, v184
	v_fmac_f32_e32 v185, 0xb2a5705f, v182
	v_sub_f32_e32 v184, v184, v186
	v_add_f32_e32 v184, v184, v185
	v_cvt_i32_f32_e32 v185, v186
	v_exp_f32_e32 v184, v184
	v_cmp_nlt_f32_e32 vcc, s38, v182
	v_ldexp_f32 v184, v184, v185
	s_nop 0
	v_cndmask_b32_e32 v184, 0, v184, vcc
	v_cmp_ngt_f32_e32 vcc, s39, v182
	s_nop 1
	v_cndmask_b32_e32 v184, v178, v184, vcc
	v_sub_f32_e32 v184, 1.0, v184
	v_mul_f32_e32 v183, v180, v180
	v_fmamk_f32 v185, v183, 0xba1345e1, v176
	v_fmaak_f32 v185, v183, v185, 0xbcdac9b8
	v_fmaak_f32 v185, v183, v185, 0x3de703be
	v_fmaak_f32 v185, v183, v185, 0xbec09330
	v_fmaak_f32 v183, v183, v185, 0x3e0375d0
	v_fma_f32 v183, |v180|, v183, |v180|
	v_cmp_nlt_f32_e64 vcc, |v180|, 1.0
	s_nop 1
	v_cndmask_b32_e32 v184, v183, v184, vcc
	v_bfi_b32 v184, s10, v184, v180
	v_add_f32_e32 v184, 1.0, v184
	v_mul_f32_e32 v91, 0.5, v91
	v_mul_f32_e32 v63, v63, v67
	v_mul_f32_e32 v91, v91, v184
	v_mul_f32_e32 v91, v63, v91
	global_store_dword v160, v90, s[8:9]
	global_store_dword v160, v91, s[8:9] offset:256
	s_add_u32 s8, s8, s14
	s_addc_u32 s9, s9, 0
	v_mul_f32_e32 v92, v70, v92
	v_mul_f32_e32 v180, 0x3f3504f3, v92
	v_fma_f32 v182, |v180|, s12, v177
	v_fma_f32 v182, |v180|, v182, s15
	v_fma_f32 v182, |v180|, v182, s16
	v_fma_f32 v182, |v180|, v182, s17
	v_fma_f32 v182, |v180|, v182, s18
	v_fma_f32 v182, |v180|, v182, s19
	v_fma_f32 v182, |v180|, v182, |v180|
	v_mul_f32_e32 v184, 0xbfb8aa3b, v182
	v_fma_f32 v185, v182, s98, -v184
	v_rndne_f32_e32 v186, v184
	v_fmac_f32_e32 v185, 0xb2a5705f, v182
	v_sub_f32_e32 v184, v184, v186
	v_add_f32_e32 v184, v184, v185
	v_cvt_i32_f32_e32 v185, v186
	v_exp_f32_e32 v184, v184
	v_cmp_nlt_f32_e32 vcc, s38, v182
	v_ldexp_f32 v184, v184, v185
	s_nop 0
	v_cndmask_b32_e32 v184, 0, v184, vcc
	v_cmp_ngt_f32_e32 vcc, s39, v182
	s_nop 1
	v_cndmask_b32_e32 v184, v178, v184, vcc
	v_sub_f32_e32 v184, 1.0, v184
	v_mul_f32_e32 v183, v180, v180
	v_fmamk_f32 v185, v183, 0xba1345e1, v176
	v_fmaak_f32 v185, v183, v185, 0xbcdac9b8
	v_fmaak_f32 v185, v183, v185, 0x3de703be
	v_fmaak_f32 v185, v183, v185, 0xbec09330
	v_fmaak_f32 v183, v183, v185, 0x3e0375d0
	v_fma_f32 v183, |v180|, v183, |v180|
	v_cmp_nlt_f32_e64 vcc, |v180|, 1.0
	s_nop 1
	v_cndmask_b32_e32 v184, v183, v184, vcc
	v_bfi_b32 v184, s10, v184, v180
	v_add_f32_e32 v184, 1.0, v184
	v_mul_f32_e32 v92, 0.5, v92
	v_mul_f32_e32 v68, v68, v72
	v_mul_f32_e32 v92, v92, v184
	v_mul_f32_e32 v92, v68, v92
	v_mul_f32_e32 v93, v71, v93
	v_mul_f32_e32 v180, 0x3f3504f3, v93
	v_fma_f32 v182, |v180|, s12, v177
	v_fma_f32 v182, |v180|, v182, s15
	v_fma_f32 v182, |v180|, v182, s16
	v_fma_f32 v182, |v180|, v182, s17
	v_fma_f32 v182, |v180|, v182, s18
	v_fma_f32 v182, |v180|, v182, s19
	v_fma_f32 v182, |v180|, v182, |v180|
	v_mul_f32_e32 v184, 0xbfb8aa3b, v182
	v_fma_f32 v185, v182, s98, -v184
	v_rndne_f32_e32 v186, v184
	v_fmac_f32_e32 v185, 0xb2a5705f, v182
	v_sub_f32_e32 v184, v184, v186
	v_add_f32_e32 v184, v184, v185
	v_cvt_i32_f32_e32 v185, v186
	v_exp_f32_e32 v184, v184
	v_cmp_nlt_f32_e32 vcc, s38, v182
	v_ldexp_f32 v184, v184, v185
	s_nop 0
	v_cndmask_b32_e32 v184, 0, v184, vcc
	v_cmp_ngt_f32_e32 vcc, s39, v182
	s_nop 1
	v_cndmask_b32_e32 v184, v178, v184, vcc
	v_sub_f32_e32 v184, 1.0, v184
	v_mul_f32_e32 v183, v180, v180
	v_fmamk_f32 v185, v183, 0xba1345e1, v176
	v_fmaak_f32 v185, v183, v185, 0xbcdac9b8
	v_fmaak_f32 v185, v183, v185, 0x3de703be
	v_fmaak_f32 v185, v183, v185, 0xbec09330
	v_fmaak_f32 v183, v183, v185, 0x3e0375d0
	v_fma_f32 v183, |v180|, v183, |v180|
	v_cmp_nlt_f32_e64 vcc, |v180|, 1.0
	s_nop 1
	v_cndmask_b32_e32 v184, v183, v184, vcc
	v_bfi_b32 v184, s10, v184, v180
	v_add_f32_e32 v184, 1.0, v184
	v_mul_f32_e32 v93, 0.5, v93
	v_mul_f32_e32 v69, v69, v73
	v_mul_f32_e32 v93, v93, v184
	v_mul_f32_e32 v93, v69, v93
	global_store_dword v160, v92, s[8:9]
	global_store_dword v160, v93, s[8:9] offset:256
	s_add_u32 s8, s8, s14
	s_addc_u32 s9, s9, 0
	v_mul_f32_e32 v94, v76, v94
	v_mul_f32_e32 v180, 0x3f3504f3, v94
	v_fma_f32 v182, |v180|, s12, v177
	v_fma_f32 v182, |v180|, v182, s15
	v_fma_f32 v182, |v180|, v182, s16
	v_fma_f32 v182, |v180|, v182, s17
	v_fma_f32 v182, |v180|, v182, s18
	v_fma_f32 v182, |v180|, v182, s19
	v_fma_f32 v182, |v180|, v182, |v180|
	v_mul_f32_e32 v184, 0xbfb8aa3b, v182
	v_fma_f32 v185, v182, s98, -v184
	v_rndne_f32_e32 v186, v184
	v_fmac_f32_e32 v185, 0xb2a5705f, v182
	v_sub_f32_e32 v184, v184, v186
	v_add_f32_e32 v184, v184, v185
	v_cvt_i32_f32_e32 v185, v186
	v_exp_f32_e32 v184, v184
	v_cmp_nlt_f32_e32 vcc, s38, v182
	v_ldexp_f32 v184, v184, v185
	s_nop 0
	v_cndmask_b32_e32 v184, 0, v184, vcc
	v_cmp_ngt_f32_e32 vcc, s39, v182
	s_nop 1
	v_cndmask_b32_e32 v184, v178, v184, vcc
	v_sub_f32_e32 v184, 1.0, v184
	v_mul_f32_e32 v183, v180, v180
	v_fmamk_f32 v185, v183, 0xba1345e1, v176
	v_fmaak_f32 v185, v183, v185, 0xbcdac9b8
	v_fmaak_f32 v185, v183, v185, 0x3de703be
	v_fmaak_f32 v185, v183, v185, 0xbec09330
	v_fmaak_f32 v183, v183, v185, 0x3e0375d0
	v_fma_f32 v183, |v180|, v183, |v180|
	v_cmp_nlt_f32_e64 vcc, |v180|, 1.0
	s_nop 1
	v_cndmask_b32_e32 v184, v183, v184, vcc
	v_bfi_b32 v184, s10, v184, v180
	v_add_f32_e32 v184, 1.0, v184
	v_mul_f32_e32 v94, 0.5, v94
	v_mul_f32_e32 v74, v74, v78
	v_mul_f32_e32 v94, v94, v184
	v_mul_f32_e32 v94, v74, v94
	v_mul_f32_e32 v95, v77, v95
	v_mul_f32_e32 v180, 0x3f3504f3, v95
	v_fma_f32 v182, |v180|, s12, v177
	v_fma_f32 v182, |v180|, v182, s15
	v_fma_f32 v182, |v180|, v182, s16
	v_fma_f32 v182, |v180|, v182, s17
	v_fma_f32 v182, |v180|, v182, s18
	v_fma_f32 v182, |v180|, v182, s19
	v_fma_f32 v182, |v180|, v182, |v180|
	v_mul_f32_e32 v184, 0xbfb8aa3b, v182
	v_fma_f32 v185, v182, s98, -v184
	v_rndne_f32_e32 v186, v184
	v_fmac_f32_e32 v185, 0xb2a5705f, v182
	v_sub_f32_e32 v184, v184, v186
	v_add_f32_e32 v184, v184, v185
	v_cvt_i32_f32_e32 v185, v186
	v_exp_f32_e32 v184, v184
	v_cmp_nlt_f32_e32 vcc, s38, v182
	v_ldexp_f32 v184, v184, v185
	s_nop 0
	v_cndmask_b32_e32 v184, 0, v184, vcc
	v_cmp_ngt_f32_e32 vcc, s39, v182
	s_nop 1
	v_cndmask_b32_e32 v184, v178, v184, vcc
	v_sub_f32_e32 v184, 1.0, v184
	v_mul_f32_e32 v183, v180, v180
	v_fmamk_f32 v185, v183, 0xba1345e1, v176
	v_fmaak_f32 v185, v183, v185, 0xbcdac9b8
	v_fmaak_f32 v185, v183, v185, 0x3de703be
	v_fmaak_f32 v185, v183, v185, 0xbec09330
	v_fmaak_f32 v183, v183, v185, 0x3e0375d0
	v_fma_f32 v183, |v180|, v183, |v180|
	v_cmp_nlt_f32_e64 vcc, |v180|, 1.0
	s_nop 1
	v_cndmask_b32_e32 v184, v183, v184, vcc
	v_bfi_b32 v184, s10, v184, v180
	v_add_f32_e32 v184, 1.0, v184
	v_mul_f32_e32 v95, 0.5, v95
	v_mul_f32_e32 v75, v75, v79
	v_mul_f32_e32 v95, v95, v184
	v_mul_f32_e32 v95, v75, v95
	global_store_dword v160, v94, s[8:9]
	global_store_dword v160, v95, s[8:9] offset:256
	s_add_u32 s8, s8, s14
	s_addc_u32 s9, s9, 0
	s_lshl_b32 s13, s92, 6
	s_add_u32 s35, s35, s13
	s_cmpk_lt_u32 s35, 0x8000
	s_cbranch_scc1 .Lgu1_chunk
	s_branch .LBB0_1045

	.amdhsa_kernel _Z12trunk_kernel6Params
		.amdhsa_group_segment_fixed_size 73744
		.amdhsa_private_segment_fixed_size 0
		.amdhsa_kernarg_size 440
		.amdhsa_user_sgpr_count 2
		.amdhsa_user_sgpr_dispatch_ptr 0
		.amdhsa_user_sgpr_queue_ptr 0
		.amdhsa_user_sgpr_kernarg_segment_ptr 1
		.amdhsa_user_sgpr_dispatch_id 0
		.amdhsa_user_sgpr_kernarg_preload_length 0
		.amdhsa_user_sgpr_kernarg_preload_offset 0
		.amdhsa_user_sgpr_private_segment_size 0
		.amdhsa_uses_dynamic_stack 0
		.amdhsa_enable_private_segment 0
		.amdhsa_system_sgpr_workgroup_id_x 1
		.amdhsa_system_sgpr_workgroup_id_y 0
		.amdhsa_system_sgpr_workgroup_id_z 0
		.amdhsa_system_sgpr_workgroup_info 0
		.amdhsa_system_vgpr_workitem_id 2
		.amdhsa_next_free_vgpr 237
		.amdhsa_next_free_sgpr 102
		.amdhsa_accum_offset 240
		.amdhsa_reserve_vcc 1
		.amdhsa_float_round_mode_32 0
		.amdhsa_float_round_mode_16_64 0
		.amdhsa_float_denorm_mode_32 3
		.amdhsa_float_denorm_mode_16_64 3
		.amdhsa_dx10_clamp 1
		.amdhsa_ieee_mode 1
		.amdhsa_fp16_overflow 0
		.amdhsa_tg_split 0
		.amdhsa_exception_fp_ieee_invalid_op 0
		.amdhsa_exception_fp_denorm_src 0
		.amdhsa_exception_fp_ieee_div_zero 0
		.amdhsa_exception_fp_ieee_overflow 0
		.amdhsa_exception_fp_ieee_underflow 0
		.amdhsa_exception_fp_ieee_inexact 0
		.amdhsa_exception_int_div_zero 0
	.end_amdhsa_kernel

amdhsa.kernels:
  - .agpr_count:     0
    .args:
      - .offset:         0
        .size:           184
        .value_kind:     by_value
      - .offset:         184
        .size:           4
        .value_kind:     hidden_block_count_x
      - .offset:         188
        .size:           4
        .value_kind:     hidden_block_count_y
      - .offset:         192
        .size:           4
        .value_kind:     hidden_block_count_z
      - .offset:         196
        .size:           2
        .value_kind:     hidden_group_size_x
      - .offset:         198
        .size:           2
        .value_kind:     hidden_group_size_y
      - .offset:         200
        .size:           2
        .value_kind:     hidden_group_size_z
      - .offset:         202
        .size:           2
        .value_kind:     hidden_remainder_x
      - .offset:         204
        .size:           2
        .value_kind:     hidden_remainder_y
      - .offset:         206
        .size:           2
        .value_kind:     hidden_remainder_z
      - .offset:         224
        .size:           8
        .value_kind:     hidden_global_offset_x
      - .offset:         232
        .size:           8
        .value_kind:     hidden_global_offset_y
      - .offset:         240
        .size:           8
        .value_kind:     hidden_global_offset_z
      - .offset:         248
        .size:           2
        .value_kind:     hidden_grid_dims
      - .offset:         272
        .size:           8
        .value_kind:     hidden_multigrid_sync_arg
    .group_segment_fixed_size: 73744
    .kernarg_segment_align: 8
    .kernarg_segment_size: 440
    .language:       OpenCL C
    .language_version:
      - 2
      - 0
    .max_flat_workgroup_size: 256
    .name:           _Z12trunk_kernel6Params
    .private_segment_fixed_size: 0
    .sgpr_count:     108
    .sgpr_spill_count: 2
    .symbol:         _Z12trunk_kernel6Params.kd
    .uniform_work_group_size: 1
    .uses_dynamic_stack: false
    .vgpr_count:     237
    .vgpr_spill_count: 0
    .wavefront_size: 64
